# GLA chunk scan (G2) rewritten with rolling load pipeline; vgt row loop loads hoisted; prologue silu table loads batched
# speedup vs baseline: 1.0350x; 1.0310x over previous
; DI float silu(float x) { return x * __builtin_amdgcn_rcpf(1.f + __expf(-x)); }
; DI void phase_prologue(const Ctx& c) {
;     ...
;   for (int i = tid; i < 3072; i += NT) { const float v = (i < 2048) ? p.c[i] : p.c_ctx[i - 2048]; c.sm[i] = silu(v); }
.LBB0_7:
	v_lshl_add_u64 v[14:15], v[4:5], 2, s[50:51]
	v_add_co_u32_e32 v16, vcc, 0x1000, v2
	s_nop 1
	v_addc_co_u32_e32 v17, vcc, 0, v3, vcc
	global_load_dword v20, v[2:3], off offset:0
	global_load_dword v21, v[2:3], off offset:1024
	global_load_dword v22, v[2:3], off offset:2048
	global_load_dword v23, v[2:3], off offset:3072
	global_load_dword v24, v[16:17], off offset:0
	global_load_dword v25, v[16:17], off offset:1024
	global_load_dword v26, v[16:17], off offset:2048
	global_load_dword v27, v[16:17], off offset:3072
	global_load_dword v28, v[14:15], off offset:0
	global_load_dword v29, v[14:15], off offset:1024
	global_load_dword v30, v[14:15], off offset:2048
	global_load_dword v31, v[14:15], off offset:3072
	s_waitcnt vmcnt(11)
	v_mul_f32_e32 v5, 0xbfb8aa3b, v20
	v_exp_f32_e32 v5, v5
	s_nop 0
	v_add_f32_e32 v5, 1.0, v5
	v_rcp_f32_e32 v5, v5
	s_nop 0
	v_mul_f32_e32 v5, v20, v5
	ds_write_b32 v1, v5 offset:0
	s_waitcnt vmcnt(10)
	v_mul_f32_e32 v5, 0xbfb8aa3b, v21
	v_exp_f32_e32 v5, v5
	s_nop 0
	v_add_f32_e32 v5, 1.0, v5
	v_rcp_f32_e32 v5, v5
	s_nop 0
	v_mul_f32_e32 v5, v21, v5
	ds_write_b32 v1, v5 offset:1024
	s_waitcnt vmcnt(9)
	v_mul_f32_e32 v5, 0xbfb8aa3b, v22
	v_exp_f32_e32 v5, v5
	s_nop 0
	v_add_f32_e32 v5, 1.0, v5
	v_rcp_f32_e32 v5, v5
	s_nop 0
	v_mul_f32_e32 v5, v22, v5
	ds_write_b32 v1, v5 offset:2048
	s_waitcnt vmcnt(8)
	v_mul_f32_e32 v5, 0xbfb8aa3b, v23
	v_exp_f32_e32 v5, v5
	s_nop 0
	v_add_f32_e32 v5, 1.0, v5
	v_rcp_f32_e32 v5, v5
	s_nop 0
	v_mul_f32_e32 v5, v23, v5
	ds_write_b32 v1, v5 offset:3072
	s_waitcnt vmcnt(7)
	v_mul_f32_e32 v5, 0xbfb8aa3b, v24
	v_exp_f32_e32 v5, v5
	s_nop 0
	v_add_f32_e32 v5, 1.0, v5
	v_rcp_f32_e32 v5, v5
	s_nop 0
	v_mul_f32_e32 v5, v24, v5
	ds_write_b32 v1, v5 offset:4096
	s_waitcnt vmcnt(6)
	v_mul_f32_e32 v5, 0xbfb8aa3b, v25
	v_exp_f32_e32 v5, v5
	s_nop 0
	v_add_f32_e32 v5, 1.0, v5
	v_rcp_f32_e32 v5, v5
	s_nop 0
	v_mul_f32_e32 v5, v25, v5
	ds_write_b32 v1, v5 offset:5120
	s_waitcnt vmcnt(5)
	v_mul_f32_e32 v5, 0xbfb8aa3b, v26
	v_exp_f32_e32 v5, v5
	s_nop 0
	v_add_f32_e32 v5, 1.0, v5
	v_rcp_f32_e32 v5, v5
	s_nop 0
	v_mul_f32_e32 v5, v26, v5
	ds_write_b32 v1, v5 offset:6144
	s_waitcnt vmcnt(4)
	v_mul_f32_e32 v5, 0xbfb8aa3b, v27
	v_exp_f32_e32 v5, v5
	s_nop 0
	v_add_f32_e32 v5, 1.0, v5
	v_rcp_f32_e32 v5, v5
	s_nop 0
	v_mul_f32_e32 v5, v27, v5
	ds_write_b32 v1, v5 offset:7168
	s_waitcnt vmcnt(3)
	v_mul_f32_e32 v5, 0xbfb8aa3b, v28
	v_exp_f32_e32 v5, v5
	s_nop 0
	v_add_f32_e32 v5, 1.0, v5
	v_rcp_f32_e32 v5, v5
	s_nop 0
	v_mul_f32_e32 v5, v28, v5
	ds_write_b32 v1, v5 offset:8192
	s_waitcnt vmcnt(2)
	v_mul_f32_e32 v5, 0xbfb8aa3b, v29
	v_exp_f32_e32 v5, v5
	s_nop 0
	v_add_f32_e32 v5, 1.0, v5
	v_rcp_f32_e32 v5, v5
	s_nop 0
	v_mul_f32_e32 v5, v29, v5
	ds_write_b32 v1, v5 offset:9216
	s_waitcnt vmcnt(1)
	v_mul_f32_e32 v5, 0xbfb8aa3b, v30
	v_exp_f32_e32 v5, v5
	s_nop 0
	v_add_f32_e32 v5, 1.0, v5
	v_rcp_f32_e32 v5, v5
	s_nop 0
	v_mul_f32_e32 v5, v30, v5
	ds_write_b32 v1, v5 offset:10240
	s_waitcnt vmcnt(0)
	v_mul_f32_e32 v5, 0xbfb8aa3b, v31
	v_exp_f32_e32 v5, v5
	s_nop 0
	v_add_f32_e32 v5, 1.0, v5
	v_rcp_f32_e32 v5, v5
	s_nop 0
	v_mul_f32_e32 v5, v31, v5
	ds_write_b32 v1, v5 offset:11264

; DI bf16 f2bf(float f) { unsigned u = __float_as_uint(f); u += 0x7fffu + ((u >> 16) & 1u); return (bf16)(u >> 16); }
; DI float gelu(float x) { return 0.5f * x * (1.f + erf_as(x * 0.70710678118654752f)); }
;   DI bf16* P() const { return (bf16*)(p.ws + WS_P); }
; DI void vgt_tile(const Ctx& c, int ti, bf16* lds) {
;     ...
;   for (int rr = 0; rr < 32; ++rr) {
;     const int t = wave * 32 + rr;
;     const unsigned u = *(const unsigned*)(c.P() + (size_t)(row0 + t) * LDP + C_V + g * 128 + 2 * lane);
;     const float a = gelu(__uint_as_float(u << 16)), b = gelu(__uint_as_float(u & 0xffff0000u));
;     const float mean = wave_sum(a + b) * (1.f / 128.f);
;     const float da = a - mean, db = b - mean;
;     const float rstd = rsqrtf(wave_sum(da * da + db * db) * (1.f / 128.f) + LN_EPS);
;     lds[(2 * lane) * LDT + t] = f2bf(da * rstd);
;     lds[(2 * lane + 1) * LDT + t] = f2bf(db * rstd);
;   }
.LBB0_321:
	s_mov_b64 s[6:7], 0x1400
	global_load_dword v20, v[4:5], off
	v_lshl_add_u64 v[4:5], v[4:5], 0, s[6:7]
	global_load_dword v21, v[4:5], off
	v_lshl_add_u64 v[4:5], v[4:5], 0, s[6:7]
	global_load_dword v22, v[4:5], off
	v_lshl_add_u64 v[4:5], v[4:5], 0, s[6:7]
	global_load_dword v23, v[4:5], off
	v_lshl_add_u64 v[4:5], v[4:5], 0, s[6:7]
	global_load_dword v24, v[4:5], off
	v_lshl_add_u64 v[4:5], v[4:5], 0, s[6:7]
	global_load_dword v25, v[4:5], off
	v_lshl_add_u64 v[4:5], v[4:5], 0, s[6:7]
	global_load_dword v26, v[4:5], off
	v_lshl_add_u64 v[4:5], v[4:5], 0, s[6:7]
	global_load_dword v27, v[4:5], off
	v_lshl_add_u64 v[4:5], v[4:5], 0, s[6:7]
	global_load_dword v28, v[4:5], off
	v_lshl_add_u64 v[4:5], v[4:5], 0, s[6:7]
	global_load_dword v29, v[4:5], off
	v_lshl_add_u64 v[4:5], v[4:5], 0, s[6:7]
	global_load_dword v30, v[4:5], off
	v_lshl_add_u64 v[4:5], v[4:5], 0, s[6:7]
	global_load_dword v31, v[4:5], off
	v_lshl_add_u64 v[4:5], v[4:5], 0, s[6:7]
	global_load_dword v32, v[4:5], off
	v_lshl_add_u64 v[4:5], v[4:5], 0, s[6:7]
	global_load_dword v33, v[4:5], off
	v_lshl_add_u64 v[4:5], v[4:5], 0, s[6:7]
	global_load_dword v34, v[4:5], off
	v_lshl_add_u64 v[4:5], v[4:5], 0, s[6:7]
	global_load_dword v35, v[4:5], off
	v_lshl_add_u64 v[4:5], v[4:5], 0, s[6:7]
	global_load_dword v36, v[4:5], off
	v_lshl_add_u64 v[4:5], v[4:5], 0, s[6:7]
	global_load_dword v37, v[4:5], off
	v_lshl_add_u64 v[4:5], v[4:5], 0, s[6:7]
	global_load_dword v38, v[4:5], off
	v_lshl_add_u64 v[4:5], v[4:5], 0, s[6:7]
	global_load_dword v39, v[4:5], off
	v_lshl_add_u64 v[4:5], v[4:5], 0, s[6:7]
	global_load_dword v40, v[4:5], off
	v_lshl_add_u64 v[4:5], v[4:5], 0, s[6:7]
	global_load_dword v41, v[4:5], off
	v_lshl_add_u64 v[4:5], v[4:5], 0, s[6:7]
	global_load_dword v42, v[4:5], off
	v_lshl_add_u64 v[4:5], v[4:5], 0, s[6:7]
	global_load_dword v43, v[4:5], off
	v_lshl_add_u64 v[4:5], v[4:5], 0, s[6:7]
	global_load_dword v44, v[4:5], off
	v_lshl_add_u64 v[4:5], v[4:5], 0, s[6:7]
	global_load_dword v45, v[4:5], off
	v_lshl_add_u64 v[4:5], v[4:5], 0, s[6:7]
	global_load_dword v46, v[4:5], off
	v_lshl_add_u64 v[4:5], v[4:5], 0, s[6:7]
	global_load_dword v47, v[4:5], off
	v_lshl_add_u64 v[4:5], v[4:5], 0, s[6:7]
	global_load_dword v48, v[4:5], off
	v_lshl_add_u64 v[4:5], v[4:5], 0, s[6:7]
	global_load_dword v49, v[4:5], off
	v_lshl_add_u64 v[4:5], v[4:5], 0, s[6:7]
	global_load_dword v50, v[4:5], off
	v_lshl_add_u64 v[4:5], v[4:5], 0, s[6:7]
	global_load_dword v51, v[4:5], off
	v_lshl_add_u64 v[4:5], v[4:5], 0, s[6:7]
	s_waitcnt vmcnt(31)
	v_lshlrev_b32_e32 v8, 16, v20
	v_mul_f32_e32 v9, 0.5, v8
	v_mul_f32_e32 v8, 0x3f3504f3, v8
	v_fma_f32 v10, |v8|, s2, 1.0
	v_rcp_f32_e32 v10, v10
	v_and_b32_e32 v7, 0xffff0000, v20
	v_fmamk_f32 v11, v10, 0x3f87dc22, v176
	v_fmaak_f32 v11, v10, v11, 0x3fb5f0e3
	v_fmaak_f32 v11, v10, v11, 0xbe91a98e
	v_fmaak_f32 v11, v10, v11, 0x3e827906
	v_mul_f32_e32 v10, v10, v11
	v_mul_f32_e64 v11, |v8|, s3
	v_mul_f32_e64 v11, |v8|, v11
	v_exp_f32_e32 v11, v11
	s_nop 0
	v_fma_f32 v10, -v11, v10, 1.0
	v_bfi_b32 v8, s13, v10, v8
	v_mul_f32_e32 v10, 0.5, v7
	v_mul_f32_e32 v7, 0x3f3504f3, v7
	v_fma_f32 v11, |v7|, s2, 1.0
	v_rcp_f32_e32 v11, v11
	v_add_f32_e32 v8, 1.0, v8
	v_fmamk_f32 v12, v11, 0x3f87dc22, v176
	v_fmaak_f32 v12, v11, v12, 0x3fb5f0e3
	v_fmaak_f32 v12, v11, v12, 0xbe91a98e
	v_fmaak_f32 v12, v11, v12, 0x3e827906
	v_mul_f32_e32 v11, v11, v12
	v_mul_f32_e64 v12, |v7|, s3
	v_mul_f32_e64 v12, |v7|, v12
	v_exp_f32_e32 v12, v12
	s_nop 0
	v_fma_f32 v11, -v12, v11, 1.0
	v_bfi_b32 v7, s13, v11, v7
	v_add_f32_e32 v7, 1.0, v7
	v_mul_f32_e32 v11, v10, v7
	v_fmac_f32_e32 v11, v9, v8
	s_nop 1
	v_add_f32_dpp v11, v11, v11 row_ror:8 row_mask:0xf bank_mask:0xf bound_ctrl:1
	s_nop 1
	v_add_f32_dpp v11, v11, v11 row_ror:4 row_mask:0xf bank_mask:0xf bound_ctrl:1
	s_nop 1
	v_add_f32_dpp v11, v11, v11 row_ror:2 row_mask:0xf bank_mask:0xf bound_ctrl:1
	s_nop 1
	v_add_f32_dpp v11, v11, v11 row_ror:1 row_mask:0xf bank_mask:0xf bound_ctrl:1
	ds_bpermute_b32 v12, v3, v11
	s_waitcnt lgkmcnt(0)
	v_add_f32_e32 v11, v11, v12
	v_mov_b32_e32 v12, v11
	s_nop 1
	v_permlane32_swap_b32_e32 v11, v12
	v_add_f32_e32 v11, v11, v12
	v_mul_f32_e32 v11, 0x3c000000, v11
	v_fma_f32 v7, v10, v7, -v11
	v_fma_f32 v8, v9, v8, -v11
	v_mul_f32_e32 v9, v7, v7
	v_fmac_f32_e32 v9, v8, v8
	s_nop 1
	v_add_f32_dpp v9, v9, v9 row_ror:8 row_mask:0xf bank_mask:0xf bound_ctrl:1
	s_nop 1
	v_add_f32_dpp v9, v9, v9 row_ror:4 row_mask:0xf bank_mask:0xf bound_ctrl:1
	s_nop 1
	v_add_f32_dpp v9, v9, v9 row_ror:2 row_mask:0xf bank_mask:0xf bound_ctrl:1
	s_nop 1
	v_add_f32_dpp v9, v9, v9 row_ror:1 row_mask:0xf bank_mask:0xf bound_ctrl:1
	ds_bpermute_b32 v10, v3, v9
	s_waitcnt lgkmcnt(0)
	v_add_f32_e32 v9, v9, v10
	v_mov_b32_e32 v10, v9
	s_nop 1
	v_permlane32_swap_b32_e32 v9, v10
	v_add_f32_e32 v9, v9, v10
	v_fmamk_f32 v9, v9, 0x3c000000, v177
	v_cmp_gt_f32_e32 vcc, s16, v9
	v_mul_f32_e32 v10, 0x4b800000, v9
	s_nop 0
	v_cndmask_b32_e32 v9, v9, v10, vcc
	v_rsq_f32_e32 v9, v9
	s_nop 0
	v_mul_f32_e32 v10, 0x45800000, v9
	v_cndmask_b32_e32 v9, v9, v10, vcc
	v_mul_f32_e32 v8, v8, v9
	v_bfe_u32 v10, v8, 16, 1
	v_add3_u32 v8, v8, v10, s83
	v_add_u32_e32 v10, s5, v6
	v_mul_f32_e32 v7, v7, v9
	ds_write_b16_d16_hi v10, v8
	v_bfe_u32 v8, v7, 16, 1
	s_add_i32 s5, s5, 2
	v_add3_u32 v7, v7, v8, s83
	ds_write_b16_d16_hi v10, v7 offset:272
	s_waitcnt vmcnt(30)
; DI bf16 f2bf(float f) { unsigned u = __float_as_uint(f); u += 0x7fffu + ((u >> 16) & 1u); return (bf16)(u >> 16); }
; DI float gelu(float x) { return 0.5f * x * (1.f + erf_as(x * 0.70710678118654752f)); }
;   DI bf16* P() const { return (bf16*)(p.ws + WS_P); }
; DI void vgt_tile(const Ctx& c, int ti, bf16* lds) {
;     ...
;   for (int rr = 0; rr < 32; ++rr) {
;     const int t = wave * 32 + rr;
;     const unsigned u = *(const unsigned*)(c.P() + (size_t)(row0 + t) * LDP + C_V + g * 128 + 2 * lane);
;     const float a = gelu(__uint_as_float(u << 16)), b = gelu(__uint_as_float(u & 0xffff0000u));
;     const float mean = wave_sum(a + b) * (1.f / 128.f);
;     const float da = a - mean, db = b - mean;
;     const float rstd = rsqrtf(wave_sum(da * da + db * db) * (1.f / 128.f) + LN_EPS);
;     lds[(2 * lane) * LDT + t] = f2bf(da * rstd);
;     lds[(2 * lane + 1) * LDT + t] = f2bf(db * rstd);
;   }
	v_lshlrev_b32_e32 v8, 16, v21
	v_mul_f32_e32 v9, 0.5, v8
	v_mul_f32_e32 v8, 0x3f3504f3, v8
	v_fma_f32 v10, |v8|, s2, 1.0
	v_rcp_f32_e32 v10, v10
	v_and_b32_e32 v7, 0xffff0000, v21
	v_fmamk_f32 v11, v10, 0x3f87dc22, v176
	v_fmaak_f32 v11, v10, v11, 0x3fb5f0e3
	v_fmaak_f32 v11, v10, v11, 0xbe91a98e
	v_fmaak_f32 v11, v10, v11, 0x3e827906
	v_mul_f32_e32 v10, v10, v11
	v_mul_f32_e64 v11, |v8|, s3
	v_mul_f32_e64 v11, |v8|, v11
	v_exp_f32_e32 v11, v11
	s_nop 0
	v_fma_f32 v10, -v11, v10, 1.0
	v_bfi_b32 v8, s13, v10, v8
	v_mul_f32_e32 v10, 0.5, v7
	v_mul_f32_e32 v7, 0x3f3504f3, v7
	v_fma_f32 v11, |v7|, s2, 1.0
	v_rcp_f32_e32 v11, v11
	v_add_f32_e32 v8, 1.0, v8
	v_fmamk_f32 v12, v11, 0x3f87dc22, v176
	v_fmaak_f32 v12, v11, v12, 0x3fb5f0e3
	v_fmaak_f32 v12, v11, v12, 0xbe91a98e
	v_fmaak_f32 v12, v11, v12, 0x3e827906
	v_mul_f32_e32 v11, v11, v12
	v_mul_f32_e64 v12, |v7|, s3
	v_mul_f32_e64 v12, |v7|, v12
	v_exp_f32_e32 v12, v12
	s_nop 0
	v_fma_f32 v11, -v12, v11, 1.0
	v_bfi_b32 v7, s13, v11, v7
	v_add_f32_e32 v7, 1.0, v7
	v_mul_f32_e32 v11, v10, v7
	v_fmac_f32_e32 v11, v9, v8
	s_nop 1
	v_add_f32_dpp v11, v11, v11 row_ror:8 row_mask:0xf bank_mask:0xf bound_ctrl:1
	s_nop 1
	v_add_f32_dpp v11, v11, v11 row_ror:4 row_mask:0xf bank_mask:0xf bound_ctrl:1
	s_nop 1
	v_add_f32_dpp v11, v11, v11 row_ror:2 row_mask:0xf bank_mask:0xf bound_ctrl:1
	s_nop 1
	v_add_f32_dpp v11, v11, v11 row_ror:1 row_mask:0xf bank_mask:0xf bound_ctrl:1
	ds_bpermute_b32 v12, v3, v11
	s_waitcnt lgkmcnt(0)
	v_add_f32_e32 v11, v11, v12
	v_mov_b32_e32 v12, v11
	s_nop 1
	v_permlane32_swap_b32_e32 v11, v12
	v_add_f32_e32 v11, v11, v12
	v_mul_f32_e32 v11, 0x3c000000, v11
	v_fma_f32 v7, v10, v7, -v11
	v_fma_f32 v8, v9, v8, -v11
	v_mul_f32_e32 v9, v7, v7
	v_fmac_f32_e32 v9, v8, v8
	s_nop 1
	v_add_f32_dpp v9, v9, v9 row_ror:8 row_mask:0xf bank_mask:0xf bound_ctrl:1
	s_nop 1
	v_add_f32_dpp v9, v9, v9 row_ror:4 row_mask:0xf bank_mask:0xf bound_ctrl:1
	s_nop 1
	v_add_f32_dpp v9, v9, v9 row_ror:2 row_mask:0xf bank_mask:0xf bound_ctrl:1
	s_nop 1
	v_add_f32_dpp v9, v9, v9 row_ror:1 row_mask:0xf bank_mask:0xf bound_ctrl:1
	ds_bpermute_b32 v10, v3, v9
	s_waitcnt lgkmcnt(0)
	v_add_f32_e32 v9, v9, v10
	v_mov_b32_e32 v10, v9
	s_nop 1
	v_permlane32_swap_b32_e32 v9, v10
	v_add_f32_e32 v9, v9, v10
	v_fmamk_f32 v9, v9, 0x3c000000, v177
	v_cmp_gt_f32_e32 vcc, s16, v9
	v_mul_f32_e32 v10, 0x4b800000, v9
	s_nop 0
	v_cndmask_b32_e32 v9, v9, v10, vcc
	v_rsq_f32_e32 v9, v9
	s_nop 0
	v_mul_f32_e32 v10, 0x45800000, v9
	v_cndmask_b32_e32 v9, v9, v10, vcc
	v_mul_f32_e32 v8, v8, v9
	v_bfe_u32 v10, v8, 16, 1
	v_add3_u32 v8, v8, v10, s83
	v_add_u32_e32 v10, s5, v6
	v_mul_f32_e32 v7, v7, v9
	ds_write_b16_d16_hi v10, v8
	v_bfe_u32 v8, v7, 16, 1
	s_add_i32 s5, s5, 2
	v_add3_u32 v7, v7, v8, s83
	ds_write_b16_d16_hi v10, v7 offset:272
	s_waitcnt vmcnt(29)
	v_lshlrev_b32_e32 v8, 16, v22
	v_mul_f32_e32 v9, 0.5, v8
	v_mul_f32_e32 v8, 0x3f3504f3, v8
	v_fma_f32 v10, |v8|, s2, 1.0
	v_rcp_f32_e32 v10, v10
	v_and_b32_e32 v7, 0xffff0000, v22
	v_fmamk_f32 v11, v10, 0x3f87dc22, v176
	v_fmaak_f32 v11, v10, v11, 0x3fb5f0e3
	v_fmaak_f32 v11, v10, v11, 0xbe91a98e
	v_fmaak_f32 v11, v10, v11, 0x3e827906
	v_mul_f32_e32 v10, v10, v11
	v_mul_f32_e64 v11, |v8|, s3
	v_mul_f32_e64 v11, |v8|, v11
	v_exp_f32_e32 v11, v11
	s_nop 0
	v_fma_f32 v10, -v11, v10, 1.0
	v_bfi_b32 v8, s13, v10, v8
	v_mul_f32_e32 v10, 0.5, v7
	v_mul_f32_e32 v7, 0x3f3504f3, v7
	v_fma_f32 v11, |v7|, s2, 1.0
	v_rcp_f32_e32 v11, v11
	v_add_f32_e32 v8, 1.0, v8
	v_fmamk_f32 v12, v11, 0x3f87dc22, v176
	v_fmaak_f32 v12, v11, v12, 0x3fb5f0e3
	v_fmaak_f32 v12, v11, v12, 0xbe91a98e
	v_fmaak_f32 v12, v11, v12, 0x3e827906
	v_mul_f32_e32 v11, v11, v12
	v_mul_f32_e64 v12, |v7|, s3
	v_mul_f32_e64 v12, |v7|, v12
	v_exp_f32_e32 v12, v12
	s_nop 0
	v_fma_f32 v11, -v12, v11, 1.0
	v_bfi_b32 v7, s13, v11, v7
	v_add_f32_e32 v7, 1.0, v7
	v_mul_f32_e32 v11, v10, v7
	v_fmac_f32_e32 v11, v9, v8
	s_nop 1
	v_add_f32_dpp v11, v11, v11 row_ror:8 row_mask:0xf bank_mask:0xf bound_ctrl:1
	s_nop 1
	v_add_f32_dpp v11, v11, v11 row_ror:4 row_mask:0xf bank_mask:0xf bound_ctrl:1
	s_nop 1
	v_add_f32_dpp v11, v11, v11 row_ror:2 row_mask:0xf bank_mask:0xf bound_ctrl:1
	s_nop 1
	v_add_f32_dpp v11, v11, v11 row_ror:1 row_mask:0xf bank_mask:0xf bound_ctrl:1
	ds_bpermute_b32 v12, v3, v11
	s_waitcnt lgkmcnt(0)
	v_add_f32_e32 v11, v11, v12
	v_mov_b32_e32 v12, v11
	s_nop 1
	v_permlane32_swap_b32_e32 v11, v12
	v_add_f32_e32 v11, v11, v12
	v_mul_f32_e32 v11, 0x3c000000, v11
	v_fma_f32 v7, v10, v7, -v11
	v_fma_f32 v8, v9, v8, -v11
	v_mul_f32_e32 v9, v7, v7
	v_fmac_f32_e32 v9, v8, v8
	s_nop 1
	v_add_f32_dpp v9, v9, v9 row_ror:8 row_mask:0xf bank_mask:0xf bound_ctrl:1
	s_nop 1
	v_add_f32_dpp v9, v9, v9 row_ror:4 row_mask:0xf bank_mask:0xf bound_ctrl:1
	s_nop 1
	v_add_f32_dpp v9, v9, v9 row_ror:2 row_mask:0xf bank_mask:0xf bound_ctrl:1
	s_nop 1
	v_add_f32_dpp v9, v9, v9 row_ror:1 row_mask:0xf bank_mask:0xf bound_ctrl:1
	ds_bpermute_b32 v10, v3, v9
	s_waitcnt lgkmcnt(0)
	v_add_f32_e32 v9, v9, v10
	v_mov_b32_e32 v10, v9
	s_nop 1
	v_permlane32_swap_b32_e32 v9, v10
	v_add_f32_e32 v9, v9, v10
	v_fmamk_f32 v9, v9, 0x3c000000, v177
	v_cmp_gt_f32_e32 vcc, s16, v9
	v_mul_f32_e32 v10, 0x4b800000, v9
	s_nop 0
	v_cndmask_b32_e32 v9, v9, v10, vcc
	v_rsq_f32_e32 v9, v9
	s_nop 0
	v_mul_f32_e32 v10, 0x45800000, v9
	v_cndmask_b32_e32 v9, v9, v10, vcc
	v_mul_f32_e32 v8, v8, v9
	v_bfe_u32 v10, v8, 16, 1
	v_add3_u32 v8, v8, v10, s83
	v_add_u32_e32 v10, s5, v6
	v_mul_f32_e32 v7, v7, v9
	ds_write_b16_d16_hi v10, v8
	v_bfe_u32 v8, v7, 16, 1
	s_add_i32 s5, s5, 2
	v_add3_u32 v7, v7, v8, s83
	ds_write_b16_d16_hi v10, v7 offset:272
	s_waitcnt vmcnt(28)
; DI bf16 f2bf(float f) { unsigned u = __float_as_uint(f); u += 0x7fffu + ((u >> 16) & 1u); return (bf16)(u >> 16); }
; DI float gelu(float x) { return 0.5f * x * (1.f + erf_as(x * 0.70710678118654752f)); }
;   DI bf16* P() const { return (bf16*)(p.ws + WS_P); }
; DI void vgt_tile(const Ctx& c, int ti, bf16* lds) {
;     ...
;   for (int rr = 0; rr < 32; ++rr) {
;     const int t = wave * 32 + rr;
;     const unsigned u = *(const unsigned*)(c.P() + (size_t)(row0 + t) * LDP + C_V + g * 128 + 2 * lane);
;     const float a = gelu(__uint_as_float(u << 16)), b = gelu(__uint_as_float(u & 0xffff0000u));
;     const float mean = wave_sum(a + b) * (1.f / 128.f);
;     const float da = a - mean, db = b - mean;
;     const float rstd = rsqrtf(wave_sum(da * da + db * db) * (1.f / 128.f) + LN_EPS);
;     lds[(2 * lane) * LDT + t] = f2bf(da * rstd);
;     lds[(2 * lane + 1) * LDT + t] = f2bf(db * rstd);
;   }
	v_lshlrev_b32_e32 v8, 16, v23
	v_mul_f32_e32 v9, 0.5, v8
	v_mul_f32_e32 v8, 0x3f3504f3, v8
	v_fma_f32 v10, |v8|, s2, 1.0
	v_rcp_f32_e32 v10, v10
	v_and_b32_e32 v7, 0xffff0000, v23
	v_fmamk_f32 v11, v10, 0x3f87dc22, v176
	v_fmaak_f32 v11, v10, v11, 0x3fb5f0e3
	v_fmaak_f32 v11, v10, v11, 0xbe91a98e
	v_fmaak_f32 v11, v10, v11, 0x3e827906
	v_mul_f32_e32 v10, v10, v11
	v_mul_f32_e64 v11, |v8|, s3
	v_mul_f32_e64 v11, |v8|, v11
	v_exp_f32_e32 v11, v11
	s_nop 0
	v_fma_f32 v10, -v11, v10, 1.0
	v_bfi_b32 v8, s13, v10, v8
	v_mul_f32_e32 v10, 0.5, v7
	v_mul_f32_e32 v7, 0x3f3504f3, v7
	v_fma_f32 v11, |v7|, s2, 1.0
	v_rcp_f32_e32 v11, v11
	v_add_f32_e32 v8, 1.0, v8
	v_fmamk_f32 v12, v11, 0x3f87dc22, v176
	v_fmaak_f32 v12, v11, v12, 0x3fb5f0e3
	v_fmaak_f32 v12, v11, v12, 0xbe91a98e
	v_fmaak_f32 v12, v11, v12, 0x3e827906
	v_mul_f32_e32 v11, v11, v12
	v_mul_f32_e64 v12, |v7|, s3
	v_mul_f32_e64 v12, |v7|, v12
	v_exp_f32_e32 v12, v12
	s_nop 0
	v_fma_f32 v11, -v12, v11, 1.0
	v_bfi_b32 v7, s13, v11, v7
	v_add_f32_e32 v7, 1.0, v7
	v_mul_f32_e32 v11, v10, v7
	v_fmac_f32_e32 v11, v9, v8
	s_nop 1
	v_add_f32_dpp v11, v11, v11 row_ror:8 row_mask:0xf bank_mask:0xf bound_ctrl:1
	s_nop 1
	v_add_f32_dpp v11, v11, v11 row_ror:4 row_mask:0xf bank_mask:0xf bound_ctrl:1
	s_nop 1
	v_add_f32_dpp v11, v11, v11 row_ror:2 row_mask:0xf bank_mask:0xf bound_ctrl:1
	s_nop 1
	v_add_f32_dpp v11, v11, v11 row_ror:1 row_mask:0xf bank_mask:0xf bound_ctrl:1
	ds_bpermute_b32 v12, v3, v11
	s_waitcnt lgkmcnt(0)
	v_add_f32_e32 v11, v11, v12
	v_mov_b32_e32 v12, v11
	s_nop 1
	v_permlane32_swap_b32_e32 v11, v12
	v_add_f32_e32 v11, v11, v12
	v_mul_f32_e32 v11, 0x3c000000, v11
	v_fma_f32 v7, v10, v7, -v11
	v_fma_f32 v8, v9, v8, -v11
	v_mul_f32_e32 v9, v7, v7
	v_fmac_f32_e32 v9, v8, v8
	s_nop 1
	v_add_f32_dpp v9, v9, v9 row_ror:8 row_mask:0xf bank_mask:0xf bound_ctrl:1
	s_nop 1
	v_add_f32_dpp v9, v9, v9 row_ror:4 row_mask:0xf bank_mask:0xf bound_ctrl:1
	s_nop 1
	v_add_f32_dpp v9, v9, v9 row_ror:2 row_mask:0xf bank_mask:0xf bound_ctrl:1
	s_nop 1
	v_add_f32_dpp v9, v9, v9 row_ror:1 row_mask:0xf bank_mask:0xf bound_ctrl:1
	ds_bpermute_b32 v10, v3, v9
	s_waitcnt lgkmcnt(0)
	v_add_f32_e32 v9, v9, v10
	v_mov_b32_e32 v10, v9
	s_nop 1
	v_permlane32_swap_b32_e32 v9, v10
	v_add_f32_e32 v9, v9, v10
	v_fmamk_f32 v9, v9, 0x3c000000, v177
	v_cmp_gt_f32_e32 vcc, s16, v9
	v_mul_f32_e32 v10, 0x4b800000, v9
	s_nop 0
	v_cndmask_b32_e32 v9, v9, v10, vcc
	v_rsq_f32_e32 v9, v9
	s_nop 0
	v_mul_f32_e32 v10, 0x45800000, v9
	v_cndmask_b32_e32 v9, v9, v10, vcc
	v_mul_f32_e32 v8, v8, v9
	v_bfe_u32 v10, v8, 16, 1
	v_add3_u32 v8, v8, v10, s83
	v_add_u32_e32 v10, s5, v6
	v_mul_f32_e32 v7, v7, v9
	ds_write_b16_d16_hi v10, v8
	v_bfe_u32 v8, v7, 16, 1
	s_add_i32 s5, s5, 2
	v_add3_u32 v7, v7, v8, s83
	ds_write_b16_d16_hi v10, v7 offset:272
	s_waitcnt vmcnt(27)
	v_lshlrev_b32_e32 v8, 16, v24
	v_mul_f32_e32 v9, 0.5, v8
	v_mul_f32_e32 v8, 0x3f3504f3, v8
	v_fma_f32 v10, |v8|, s2, 1.0
	v_rcp_f32_e32 v10, v10
	v_and_b32_e32 v7, 0xffff0000, v24
	v_fmamk_f32 v11, v10, 0x3f87dc22, v176
	v_fmaak_f32 v11, v10, v11, 0x3fb5f0e3
	v_fmaak_f32 v11, v10, v11, 0xbe91a98e
	v_fmaak_f32 v11, v10, v11, 0x3e827906
	v_mul_f32_e32 v10, v10, v11
	v_mul_f32_e64 v11, |v8|, s3
	v_mul_f32_e64 v11, |v8|, v11
	v_exp_f32_e32 v11, v11
	s_nop 0
	v_fma_f32 v10, -v11, v10, 1.0
	v_bfi_b32 v8, s13, v10, v8
	v_mul_f32_e32 v10, 0.5, v7
	v_mul_f32_e32 v7, 0x3f3504f3, v7
	v_fma_f32 v11, |v7|, s2, 1.0
	v_rcp_f32_e32 v11, v11
	v_add_f32_e32 v8, 1.0, v8
	v_fmamk_f32 v12, v11, 0x3f87dc22, v176
	v_fmaak_f32 v12, v11, v12, 0x3fb5f0e3
	v_fmaak_f32 v12, v11, v12, 0xbe91a98e
	v_fmaak_f32 v12, v11, v12, 0x3e827906
	v_mul_f32_e32 v11, v11, v12
	v_mul_f32_e64 v12, |v7|, s3
	v_mul_f32_e64 v12, |v7|, v12
	v_exp_f32_e32 v12, v12
	s_nop 0
	v_fma_f32 v11, -v12, v11, 1.0
	v_bfi_b32 v7, s13, v11, v7
	v_add_f32_e32 v7, 1.0, v7
	v_mul_f32_e32 v11, v10, v7
	v_fmac_f32_e32 v11, v9, v8
	s_nop 1
	v_add_f32_dpp v11, v11, v11 row_ror:8 row_mask:0xf bank_mask:0xf bound_ctrl:1
	s_nop 1
	v_add_f32_dpp v11, v11, v11 row_ror:4 row_mask:0xf bank_mask:0xf bound_ctrl:1
	s_nop 1
	v_add_f32_dpp v11, v11, v11 row_ror:2 row_mask:0xf bank_mask:0xf bound_ctrl:1
	s_nop 1
	v_add_f32_dpp v11, v11, v11 row_ror:1 row_mask:0xf bank_mask:0xf bound_ctrl:1
	ds_bpermute_b32 v12, v3, v11
	s_waitcnt lgkmcnt(0)
	v_add_f32_e32 v11, v11, v12
	v_mov_b32_e32 v12, v11
	s_nop 1
	v_permlane32_swap_b32_e32 v11, v12
	v_add_f32_e32 v11, v11, v12
	v_mul_f32_e32 v11, 0x3c000000, v11
	v_fma_f32 v7, v10, v7, -v11
	v_fma_f32 v8, v9, v8, -v11
	v_mul_f32_e32 v9, v7, v7
	v_fmac_f32_e32 v9, v8, v8
	s_nop 1
	v_add_f32_dpp v9, v9, v9 row_ror:8 row_mask:0xf bank_mask:0xf bound_ctrl:1
	s_nop 1
	v_add_f32_dpp v9, v9, v9 row_ror:4 row_mask:0xf bank_mask:0xf bound_ctrl:1
	s_nop 1
	v_add_f32_dpp v9, v9, v9 row_ror:2 row_mask:0xf bank_mask:0xf bound_ctrl:1
	s_nop 1
	v_add_f32_dpp v9, v9, v9 row_ror:1 row_mask:0xf bank_mask:0xf bound_ctrl:1
	ds_bpermute_b32 v10, v3, v9
	s_waitcnt lgkmcnt(0)
	v_add_f32_e32 v9, v9, v10
	v_mov_b32_e32 v10, v9
	s_nop 1
	v_permlane32_swap_b32_e32 v9, v10
	v_add_f32_e32 v9, v9, v10
	v_fmamk_f32 v9, v9, 0x3c000000, v177
	v_cmp_gt_f32_e32 vcc, s16, v9
	v_mul_f32_e32 v10, 0x4b800000, v9
	s_nop 0
	v_cndmask_b32_e32 v9, v9, v10, vcc
	v_rsq_f32_e32 v9, v9
	s_nop 0
	v_mul_f32_e32 v10, 0x45800000, v9
	v_cndmask_b32_e32 v9, v9, v10, vcc
	v_mul_f32_e32 v8, v8, v9
	v_bfe_u32 v10, v8, 16, 1
	v_add3_u32 v8, v8, v10, s83
	v_add_u32_e32 v10, s5, v6
	v_mul_f32_e32 v7, v7, v9
	ds_write_b16_d16_hi v10, v8
	v_bfe_u32 v8, v7, 16, 1
	s_add_i32 s5, s5, 2
	v_add3_u32 v7, v7, v8, s83
	ds_write_b16_d16_hi v10, v7 offset:272
	s_waitcnt vmcnt(26)
; DI bf16 f2bf(float f) { unsigned u = __float_as_uint(f); u += 0x7fffu + ((u >> 16) & 1u); return (bf16)(u >> 16); }
; DI float gelu(float x) { return 0.5f * x * (1.f + erf_as(x * 0.70710678118654752f)); }
;   DI bf16* P() const { return (bf16*)(p.ws + WS_P); }
; DI void vgt_tile(const Ctx& c, int ti, bf16* lds) {
;     ...
;   for (int rr = 0; rr < 32; ++rr) {
;     const int t = wave * 32 + rr;
;     const unsigned u = *(const unsigned*)(c.P() + (size_t)(row0 + t) * LDP + C_V + g * 128 + 2 * lane);
;     const float a = gelu(__uint_as_float(u << 16)), b = gelu(__uint_as_float(u & 0xffff0000u));
;     const float mean = wave_sum(a + b) * (1.f / 128.f);
;     const float da = a - mean, db = b - mean;
;     const float rstd = rsqrtf(wave_sum(da * da + db * db) * (1.f / 128.f) + LN_EPS);
;     lds[(2 * lane) * LDT + t] = f2bf(da * rstd);
;     lds[(2 * lane + 1) * LDT + t] = f2bf(db * rstd);
;   }
	v_lshlrev_b32_e32 v8, 16, v25
	v_mul_f32_e32 v9, 0.5, v8
	v_mul_f32_e32 v8, 0x3f3504f3, v8
	v_fma_f32 v10, |v8|, s2, 1.0
	v_rcp_f32_e32 v10, v10
	v_and_b32_e32 v7, 0xffff0000, v25
	v_fmamk_f32 v11, v10, 0x3f87dc22, v176
	v_fmaak_f32 v11, v10, v11, 0x3fb5f0e3
	v_fmaak_f32 v11, v10, v11, 0xbe91a98e
	v_fmaak_f32 v11, v10, v11, 0x3e827906
	v_mul_f32_e32 v10, v10, v11
	v_mul_f32_e64 v11, |v8|, s3
	v_mul_f32_e64 v11, |v8|, v11
	v_exp_f32_e32 v11, v11
	s_nop 0
	v_fma_f32 v10, -v11, v10, 1.0
	v_bfi_b32 v8, s13, v10, v8
	v_mul_f32_e32 v10, 0.5, v7
	v_mul_f32_e32 v7, 0x3f3504f3, v7
	v_fma_f32 v11, |v7|, s2, 1.0
	v_rcp_f32_e32 v11, v11
	v_add_f32_e32 v8, 1.0, v8
	v_fmamk_f32 v12, v11, 0x3f87dc22, v176
	v_fmaak_f32 v12, v11, v12, 0x3fb5f0e3
	v_fmaak_f32 v12, v11, v12, 0xbe91a98e
	v_fmaak_f32 v12, v11, v12, 0x3e827906
	v_mul_f32_e32 v11, v11, v12
	v_mul_f32_e64 v12, |v7|, s3
	v_mul_f32_e64 v12, |v7|, v12
	v_exp_f32_e32 v12, v12
	s_nop 0
	v_fma_f32 v11, -v12, v11, 1.0
	v_bfi_b32 v7, s13, v11, v7
	v_add_f32_e32 v7, 1.0, v7
	v_mul_f32_e32 v11, v10, v7
	v_fmac_f32_e32 v11, v9, v8
	s_nop 1
	v_add_f32_dpp v11, v11, v11 row_ror:8 row_mask:0xf bank_mask:0xf bound_ctrl:1
	s_nop 1
	v_add_f32_dpp v11, v11, v11 row_ror:4 row_mask:0xf bank_mask:0xf bound_ctrl:1
	s_nop 1
	v_add_f32_dpp v11, v11, v11 row_ror:2 row_mask:0xf bank_mask:0xf bound_ctrl:1
	s_nop 1
	v_add_f32_dpp v11, v11, v11 row_ror:1 row_mask:0xf bank_mask:0xf bound_ctrl:1
	ds_bpermute_b32 v12, v3, v11
	s_waitcnt lgkmcnt(0)
	v_add_f32_e32 v11, v11, v12
	v_mov_b32_e32 v12, v11
	s_nop 1
	v_permlane32_swap_b32_e32 v11, v12
	v_add_f32_e32 v11, v11, v12
	v_mul_f32_e32 v11, 0x3c000000, v11
	v_fma_f32 v7, v10, v7, -v11
	v_fma_f32 v8, v9, v8, -v11
	v_mul_f32_e32 v9, v7, v7
	v_fmac_f32_e32 v9, v8, v8
	s_nop 1
	v_add_f32_dpp v9, v9, v9 row_ror:8 row_mask:0xf bank_mask:0xf bound_ctrl:1
	s_nop 1
	v_add_f32_dpp v9, v9, v9 row_ror:4 row_mask:0xf bank_mask:0xf bound_ctrl:1
	s_nop 1
	v_add_f32_dpp v9, v9, v9 row_ror:2 row_mask:0xf bank_mask:0xf bound_ctrl:1
	s_nop 1
	v_add_f32_dpp v9, v9, v9 row_ror:1 row_mask:0xf bank_mask:0xf bound_ctrl:1
	ds_bpermute_b32 v10, v3, v9
	s_waitcnt lgkmcnt(0)
	v_add_f32_e32 v9, v9, v10
	v_mov_b32_e32 v10, v9
	s_nop 1
	v_permlane32_swap_b32_e32 v9, v10
	v_add_f32_e32 v9, v9, v10
	v_fmamk_f32 v9, v9, 0x3c000000, v177
	v_cmp_gt_f32_e32 vcc, s16, v9
	v_mul_f32_e32 v10, 0x4b800000, v9
	s_nop 0
	v_cndmask_b32_e32 v9, v9, v10, vcc
	v_rsq_f32_e32 v9, v9
	s_nop 0
	v_mul_f32_e32 v10, 0x45800000, v9
	v_cndmask_b32_e32 v9, v9, v10, vcc
	v_mul_f32_e32 v8, v8, v9
	v_bfe_u32 v10, v8, 16, 1
	v_add3_u32 v8, v8, v10, s83
	v_add_u32_e32 v10, s5, v6
	v_mul_f32_e32 v7, v7, v9
	ds_write_b16_d16_hi v10, v8
	v_bfe_u32 v8, v7, 16, 1
	s_add_i32 s5, s5, 2
	v_add3_u32 v7, v7, v8, s83
	ds_write_b16_d16_hi v10, v7 offset:272
	s_waitcnt vmcnt(25)
	v_lshlrev_b32_e32 v8, 16, v26
	v_mul_f32_e32 v9, 0.5, v8
	v_mul_f32_e32 v8, 0x3f3504f3, v8
	v_fma_f32 v10, |v8|, s2, 1.0
	v_rcp_f32_e32 v10, v10
	v_and_b32_e32 v7, 0xffff0000, v26
	v_fmamk_f32 v11, v10, 0x3f87dc22, v176
	v_fmaak_f32 v11, v10, v11, 0x3fb5f0e3
	v_fmaak_f32 v11, v10, v11, 0xbe91a98e
	v_fmaak_f32 v11, v10, v11, 0x3e827906
	v_mul_f32_e32 v10, v10, v11
	v_mul_f32_e64 v11, |v8|, s3
	v_mul_f32_e64 v11, |v8|, v11
	v_exp_f32_e32 v11, v11
	s_nop 0
	v_fma_f32 v10, -v11, v10, 1.0
	v_bfi_b32 v8, s13, v10, v8
	v_mul_f32_e32 v10, 0.5, v7
	v_mul_f32_e32 v7, 0x3f3504f3, v7
	v_fma_f32 v11, |v7|, s2, 1.0
	v_rcp_f32_e32 v11, v11
	v_add_f32_e32 v8, 1.0, v8
	v_fmamk_f32 v12, v11, 0x3f87dc22, v176
	v_fmaak_f32 v12, v11, v12, 0x3fb5f0e3
	v_fmaak_f32 v12, v11, v12, 0xbe91a98e
	v_fmaak_f32 v12, v11, v12, 0x3e827906
	v_mul_f32_e32 v11, v11, v12
	v_mul_f32_e64 v12, |v7|, s3
	v_mul_f32_e64 v12, |v7|, v12
	v_exp_f32_e32 v12, v12
	s_nop 0
	v_fma_f32 v11, -v12, v11, 1.0
	v_bfi_b32 v7, s13, v11, v7
	v_add_f32_e32 v7, 1.0, v7
	v_mul_f32_e32 v11, v10, v7
	v_fmac_f32_e32 v11, v9, v8
	s_nop 1
	v_add_f32_dpp v11, v11, v11 row_ror:8 row_mask:0xf bank_mask:0xf bound_ctrl:1
	s_nop 1
	v_add_f32_dpp v11, v11, v11 row_ror:4 row_mask:0xf bank_mask:0xf bound_ctrl:1
	s_nop 1
	v_add_f32_dpp v11, v11, v11 row_ror:2 row_mask:0xf bank_mask:0xf bound_ctrl:1
	s_nop 1
	v_add_f32_dpp v11, v11, v11 row_ror:1 row_mask:0xf bank_mask:0xf bound_ctrl:1
	ds_bpermute_b32 v12, v3, v11
	s_waitcnt lgkmcnt(0)
	v_add_f32_e32 v11, v11, v12
	v_mov_b32_e32 v12, v11
	s_nop 1
	v_permlane32_swap_b32_e32 v11, v12
	v_add_f32_e32 v11, v11, v12
	v_mul_f32_e32 v11, 0x3c000000, v11
	v_fma_f32 v7, v10, v7, -v11
	v_fma_f32 v8, v9, v8, -v11
	v_mul_f32_e32 v9, v7, v7
	v_fmac_f32_e32 v9, v8, v8
	s_nop 1
	v_add_f32_dpp v9, v9, v9 row_ror:8 row_mask:0xf bank_mask:0xf bound_ctrl:1
	s_nop 1
	v_add_f32_dpp v9, v9, v9 row_ror:4 row_mask:0xf bank_mask:0xf bound_ctrl:1
	s_nop 1
	v_add_f32_dpp v9, v9, v9 row_ror:2 row_mask:0xf bank_mask:0xf bound_ctrl:1
	s_nop 1
	v_add_f32_dpp v9, v9, v9 row_ror:1 row_mask:0xf bank_mask:0xf bound_ctrl:1
	ds_bpermute_b32 v10, v3, v9
	s_waitcnt lgkmcnt(0)
	v_add_f32_e32 v9, v9, v10
	v_mov_b32_e32 v10, v9
	s_nop 1
	v_permlane32_swap_b32_e32 v9, v10
	v_add_f32_e32 v9, v9, v10
	v_fmamk_f32 v9, v9, 0x3c000000, v177
	v_cmp_gt_f32_e32 vcc, s16, v9
	v_mul_f32_e32 v10, 0x4b800000, v9
	s_nop 0
	v_cndmask_b32_e32 v9, v9, v10, vcc
	v_rsq_f32_e32 v9, v9
	s_nop 0
	v_mul_f32_e32 v10, 0x45800000, v9
	v_cndmask_b32_e32 v9, v9, v10, vcc
	v_mul_f32_e32 v8, v8, v9
	v_bfe_u32 v10, v8, 16, 1
	v_add3_u32 v8, v8, v10, s83
	v_add_u32_e32 v10, s5, v6
	v_mul_f32_e32 v7, v7, v9
	ds_write_b16_d16_hi v10, v8
	v_bfe_u32 v8, v7, 16, 1
	s_add_i32 s5, s5, 2
	v_add3_u32 v7, v7, v8, s83
	ds_write_b16_d16_hi v10, v7 offset:272
	s_waitcnt vmcnt(24)
; DI bf16 f2bf(float f) { unsigned u = __float_as_uint(f); u += 0x7fffu + ((u >> 16) & 1u); return (bf16)(u >> 16); }
; DI float gelu(float x) { return 0.5f * x * (1.f + erf_as(x * 0.70710678118654752f)); }
;   DI bf16* P() const { return (bf16*)(p.ws + WS_P); }
; DI void vgt_tile(const Ctx& c, int ti, bf16* lds) {
;     ...
;   for (int rr = 0; rr < 32; ++rr) {
;     const int t = wave * 32 + rr;
;     const unsigned u = *(const unsigned*)(c.P() + (size_t)(row0 + t) * LDP + C_V + g * 128 + 2 * lane);
;     const float a = gelu(__uint_as_float(u << 16)), b = gelu(__uint_as_float(u & 0xffff0000u));
;     const float mean = wave_sum(a + b) * (1.f / 128.f);
;     const float da = a - mean, db = b - mean;
;     const float rstd = rsqrtf(wave_sum(da * da + db * db) * (1.f / 128.f) + LN_EPS);
;     lds[(2 * lane) * LDT + t] = f2bf(da * rstd);
;     lds[(2 * lane + 1) * LDT + t] = f2bf(db * rstd);
;   }
	v_lshlrev_b32_e32 v8, 16, v27
	v_mul_f32_e32 v9, 0.5, v8
	v_mul_f32_e32 v8, 0x3f3504f3, v8
	v_fma_f32 v10, |v8|, s2, 1.0
	v_rcp_f32_e32 v10, v10
	v_and_b32_e32 v7, 0xffff0000, v27
	v_fmamk_f32 v11, v10, 0x3f87dc22, v176
	v_fmaak_f32 v11, v10, v11, 0x3fb5f0e3
	v_fmaak_f32 v11, v10, v11, 0xbe91a98e
	v_fmaak_f32 v11, v10, v11, 0x3e827906
	v_mul_f32_e32 v10, v10, v11
	v_mul_f32_e64 v11, |v8|, s3
	v_mul_f32_e64 v11, |v8|, v11
	v_exp_f32_e32 v11, v11
	s_nop 0
	v_fma_f32 v10, -v11, v10, 1.0
	v_bfi_b32 v8, s13, v10, v8
	v_mul_f32_e32 v10, 0.5, v7
	v_mul_f32_e32 v7, 0x3f3504f3, v7
	v_fma_f32 v11, |v7|, s2, 1.0
	v_rcp_f32_e32 v11, v11
	v_add_f32_e32 v8, 1.0, v8
	v_fmamk_f32 v12, v11, 0x3f87dc22, v176
	v_fmaak_f32 v12, v11, v12, 0x3fb5f0e3
	v_fmaak_f32 v12, v11, v12, 0xbe91a98e
	v_fmaak_f32 v12, v11, v12, 0x3e827906
	v_mul_f32_e32 v11, v11, v12
	v_mul_f32_e64 v12, |v7|, s3
	v_mul_f32_e64 v12, |v7|, v12
	v_exp_f32_e32 v12, v12
	s_nop 0
	v_fma_f32 v11, -v12, v11, 1.0
	v_bfi_b32 v7, s13, v11, v7
	v_add_f32_e32 v7, 1.0, v7
	v_mul_f32_e32 v11, v10, v7
	v_fmac_f32_e32 v11, v9, v8
	s_nop 1
	v_add_f32_dpp v11, v11, v11 row_ror:8 row_mask:0xf bank_mask:0xf bound_ctrl:1
	s_nop 1
	v_add_f32_dpp v11, v11, v11 row_ror:4 row_mask:0xf bank_mask:0xf bound_ctrl:1
	s_nop 1
	v_add_f32_dpp v11, v11, v11 row_ror:2 row_mask:0xf bank_mask:0xf bound_ctrl:1
	s_nop 1
	v_add_f32_dpp v11, v11, v11 row_ror:1 row_mask:0xf bank_mask:0xf bound_ctrl:1
	ds_bpermute_b32 v12, v3, v11
	s_waitcnt lgkmcnt(0)
	v_add_f32_e32 v11, v11, v12
	v_mov_b32_e32 v12, v11
	s_nop 1
	v_permlane32_swap_b32_e32 v11, v12
	v_add_f32_e32 v11, v11, v12
	v_mul_f32_e32 v11, 0x3c000000, v11
	v_fma_f32 v7, v10, v7, -v11
	v_fma_f32 v8, v9, v8, -v11
	v_mul_f32_e32 v9, v7, v7
	v_fmac_f32_e32 v9, v8, v8
	s_nop 1
	v_add_f32_dpp v9, v9, v9 row_ror:8 row_mask:0xf bank_mask:0xf bound_ctrl:1
	s_nop 1
	v_add_f32_dpp v9, v9, v9 row_ror:4 row_mask:0xf bank_mask:0xf bound_ctrl:1
	s_nop 1
	v_add_f32_dpp v9, v9, v9 row_ror:2 row_mask:0xf bank_mask:0xf bound_ctrl:1
	s_nop 1
	v_add_f32_dpp v9, v9, v9 row_ror:1 row_mask:0xf bank_mask:0xf bound_ctrl:1
	ds_bpermute_b32 v10, v3, v9
	s_waitcnt lgkmcnt(0)
	v_add_f32_e32 v9, v9, v10
	v_mov_b32_e32 v10, v9
	s_nop 1
	v_permlane32_swap_b32_e32 v9, v10
	v_add_f32_e32 v9, v9, v10
	v_fmamk_f32 v9, v9, 0x3c000000, v177
	v_cmp_gt_f32_e32 vcc, s16, v9
	v_mul_f32_e32 v10, 0x4b800000, v9
	s_nop 0
	v_cndmask_b32_e32 v9, v9, v10, vcc
	v_rsq_f32_e32 v9, v9
	s_nop 0
	v_mul_f32_e32 v10, 0x45800000, v9
	v_cndmask_b32_e32 v9, v9, v10, vcc
	v_mul_f32_e32 v8, v8, v9
	v_bfe_u32 v10, v8, 16, 1
	v_add3_u32 v8, v8, v10, s83
	v_add_u32_e32 v10, s5, v6
	v_mul_f32_e32 v7, v7, v9
	ds_write_b16_d16_hi v10, v8
	v_bfe_u32 v8, v7, 16, 1
	s_add_i32 s5, s5, 2
	v_add3_u32 v7, v7, v8, s83
	ds_write_b16_d16_hi v10, v7 offset:272
	s_waitcnt vmcnt(23)
	v_lshlrev_b32_e32 v8, 16, v28
	v_mul_f32_e32 v9, 0.5, v8
	v_mul_f32_e32 v8, 0x3f3504f3, v8
	v_fma_f32 v10, |v8|, s2, 1.0
	v_rcp_f32_e32 v10, v10
	v_and_b32_e32 v7, 0xffff0000, v28
	v_fmamk_f32 v11, v10, 0x3f87dc22, v176
	v_fmaak_f32 v11, v10, v11, 0x3fb5f0e3
	v_fmaak_f32 v11, v10, v11, 0xbe91a98e
	v_fmaak_f32 v11, v10, v11, 0x3e827906
	v_mul_f32_e32 v10, v10, v11
	v_mul_f32_e64 v11, |v8|, s3
	v_mul_f32_e64 v11, |v8|, v11
	v_exp_f32_e32 v11, v11
	s_nop 0
	v_fma_f32 v10, -v11, v10, 1.0
	v_bfi_b32 v8, s13, v10, v8
	v_mul_f32_e32 v10, 0.5, v7
	v_mul_f32_e32 v7, 0x3f3504f3, v7
	v_fma_f32 v11, |v7|, s2, 1.0
	v_rcp_f32_e32 v11, v11
	v_add_f32_e32 v8, 1.0, v8
	v_fmamk_f32 v12, v11, 0x3f87dc22, v176
	v_fmaak_f32 v12, v11, v12, 0x3fb5f0e3
	v_fmaak_f32 v12, v11, v12, 0xbe91a98e
	v_fmaak_f32 v12, v11, v12, 0x3e827906
	v_mul_f32_e32 v11, v11, v12
	v_mul_f32_e64 v12, |v7|, s3
	v_mul_f32_e64 v12, |v7|, v12
	v_exp_f32_e32 v12, v12
	s_nop 0
	v_fma_f32 v11, -v12, v11, 1.0
	v_bfi_b32 v7, s13, v11, v7
	v_add_f32_e32 v7, 1.0, v7
	v_mul_f32_e32 v11, v10, v7
	v_fmac_f32_e32 v11, v9, v8
	s_nop 1
	v_add_f32_dpp v11, v11, v11 row_ror:8 row_mask:0xf bank_mask:0xf bound_ctrl:1
	s_nop 1
	v_add_f32_dpp v11, v11, v11 row_ror:4 row_mask:0xf bank_mask:0xf bound_ctrl:1
	s_nop 1
	v_add_f32_dpp v11, v11, v11 row_ror:2 row_mask:0xf bank_mask:0xf bound_ctrl:1
	s_nop 1
	v_add_f32_dpp v11, v11, v11 row_ror:1 row_mask:0xf bank_mask:0xf bound_ctrl:1
	ds_bpermute_b32 v12, v3, v11
	s_waitcnt lgkmcnt(0)
	v_add_f32_e32 v11, v11, v12
	v_mov_b32_e32 v12, v11
	s_nop 1
	v_permlane32_swap_b32_e32 v11, v12
	v_add_f32_e32 v11, v11, v12
	v_mul_f32_e32 v11, 0x3c000000, v11
	v_fma_f32 v7, v10, v7, -v11
	v_fma_f32 v8, v9, v8, -v11
	v_mul_f32_e32 v9, v7, v7
	v_fmac_f32_e32 v9, v8, v8
	s_nop 1
	v_add_f32_dpp v9, v9, v9 row_ror:8 row_mask:0xf bank_mask:0xf bound_ctrl:1
	s_nop 1
	v_add_f32_dpp v9, v9, v9 row_ror:4 row_mask:0xf bank_mask:0xf bound_ctrl:1
	s_nop 1
	v_add_f32_dpp v9, v9, v9 row_ror:2 row_mask:0xf bank_mask:0xf bound_ctrl:1
	s_nop 1
	v_add_f32_dpp v9, v9, v9 row_ror:1 row_mask:0xf bank_mask:0xf bound_ctrl:1
	ds_bpermute_b32 v10, v3, v9
	s_waitcnt lgkmcnt(0)
	v_add_f32_e32 v9, v9, v10
	v_mov_b32_e32 v10, v9
	s_nop 1
	v_permlane32_swap_b32_e32 v9, v10
	v_add_f32_e32 v9, v9, v10
	v_fmamk_f32 v9, v9, 0x3c000000, v177
	v_cmp_gt_f32_e32 vcc, s16, v9
	v_mul_f32_e32 v10, 0x4b800000, v9
	s_nop 0
	v_cndmask_b32_e32 v9, v9, v10, vcc
	v_rsq_f32_e32 v9, v9
	s_nop 0
	v_mul_f32_e32 v10, 0x45800000, v9
	v_cndmask_b32_e32 v9, v9, v10, vcc
	v_mul_f32_e32 v8, v8, v9
	v_bfe_u32 v10, v8, 16, 1
	v_add3_u32 v8, v8, v10, s83
	v_add_u32_e32 v10, s5, v6
	v_mul_f32_e32 v7, v7, v9
	ds_write_b16_d16_hi v10, v8
	v_bfe_u32 v8, v7, 16, 1
	s_add_i32 s5, s5, 2
	v_add3_u32 v7, v7, v8, s83
	ds_write_b16_d16_hi v10, v7 offset:272
	s_waitcnt vmcnt(22)
; DI bf16 f2bf(float f) { unsigned u = __float_as_uint(f); u += 0x7fffu + ((u >> 16) & 1u); return (bf16)(u >> 16); }
; DI float gelu(float x) { return 0.5f * x * (1.f + erf_as(x * 0.70710678118654752f)); }
;   DI bf16* P() const { return (bf16*)(p.ws + WS_P); }
; DI void vgt_tile(const Ctx& c, int ti, bf16* lds) {
;     ...
;   for (int rr = 0; rr < 32; ++rr) {
;     const int t = wave * 32 + rr;
;     const unsigned u = *(const unsigned*)(c.P() + (size_t)(row0 + t) * LDP + C_V + g * 128 + 2 * lane);
;     const float a = gelu(__uint_as_float(u << 16)), b = gelu(__uint_as_float(u & 0xffff0000u));
;     const float mean = wave_sum(a + b) * (1.f / 128.f);
;     const float da = a - mean, db = b - mean;
;     const float rstd = rsqrtf(wave_sum(da * da + db * db) * (1.f / 128.f) + LN_EPS);
;     lds[(2 * lane) * LDT + t] = f2bf(da * rstd);
;     lds[(2 * lane + 1) * LDT + t] = f2bf(db * rstd);
;   }
	v_lshlrev_b32_e32 v8, 16, v29
	v_mul_f32_e32 v9, 0.5, v8
	v_mul_f32_e32 v8, 0x3f3504f3, v8
	v_fma_f32 v10, |v8|, s2, 1.0
	v_rcp_f32_e32 v10, v10
	v_and_b32_e32 v7, 0xffff0000, v29
	v_fmamk_f32 v11, v10, 0x3f87dc22, v176
	v_fmaak_f32 v11, v10, v11, 0x3fb5f0e3
	v_fmaak_f32 v11, v10, v11, 0xbe91a98e
	v_fmaak_f32 v11, v10, v11, 0x3e827906
	v_mul_f32_e32 v10, v10, v11
	v_mul_f32_e64 v11, |v8|, s3
	v_mul_f32_e64 v11, |v8|, v11
	v_exp_f32_e32 v11, v11
	s_nop 0
	v_fma_f32 v10, -v11, v10, 1.0
	v_bfi_b32 v8, s13, v10, v8
	v_mul_f32_e32 v10, 0.5, v7
	v_mul_f32_e32 v7, 0x3f3504f3, v7
	v_fma_f32 v11, |v7|, s2, 1.0
	v_rcp_f32_e32 v11, v11
	v_add_f32_e32 v8, 1.0, v8
	v_fmamk_f32 v12, v11, 0x3f87dc22, v176
	v_fmaak_f32 v12, v11, v12, 0x3fb5f0e3
	v_fmaak_f32 v12, v11, v12, 0xbe91a98e
	v_fmaak_f32 v12, v11, v12, 0x3e827906
	v_mul_f32_e32 v11, v11, v12
	v_mul_f32_e64 v12, |v7|, s3
	v_mul_f32_e64 v12, |v7|, v12
	v_exp_f32_e32 v12, v12
	s_nop 0
	v_fma_f32 v11, -v12, v11, 1.0
	v_bfi_b32 v7, s13, v11, v7
	v_add_f32_e32 v7, 1.0, v7
	v_mul_f32_e32 v11, v10, v7
	v_fmac_f32_e32 v11, v9, v8
	s_nop 1
	v_add_f32_dpp v11, v11, v11 row_ror:8 row_mask:0xf bank_mask:0xf bound_ctrl:1
	s_nop 1
	v_add_f32_dpp v11, v11, v11 row_ror:4 row_mask:0xf bank_mask:0xf bound_ctrl:1
	s_nop 1
	v_add_f32_dpp v11, v11, v11 row_ror:2 row_mask:0xf bank_mask:0xf bound_ctrl:1
	s_nop 1
	v_add_f32_dpp v11, v11, v11 row_ror:1 row_mask:0xf bank_mask:0xf bound_ctrl:1
	ds_bpermute_b32 v12, v3, v11
	s_waitcnt lgkmcnt(0)
	v_add_f32_e32 v11, v11, v12
	v_mov_b32_e32 v12, v11
	s_nop 1
	v_permlane32_swap_b32_e32 v11, v12
	v_add_f32_e32 v11, v11, v12
	v_mul_f32_e32 v11, 0x3c000000, v11
	v_fma_f32 v7, v10, v7, -v11
	v_fma_f32 v8, v9, v8, -v11
	v_mul_f32_e32 v9, v7, v7
	v_fmac_f32_e32 v9, v8, v8
	s_nop 1
	v_add_f32_dpp v9, v9, v9 row_ror:8 row_mask:0xf bank_mask:0xf bound_ctrl:1
	s_nop 1
	v_add_f32_dpp v9, v9, v9 row_ror:4 row_mask:0xf bank_mask:0xf bound_ctrl:1
	s_nop 1
	v_add_f32_dpp v9, v9, v9 row_ror:2 row_mask:0xf bank_mask:0xf bound_ctrl:1
	s_nop 1
	v_add_f32_dpp v9, v9, v9 row_ror:1 row_mask:0xf bank_mask:0xf bound_ctrl:1
	ds_bpermute_b32 v10, v3, v9
	s_waitcnt lgkmcnt(0)
	v_add_f32_e32 v9, v9, v10
	v_mov_b32_e32 v10, v9
	s_nop 1
	v_permlane32_swap_b32_e32 v9, v10
	v_add_f32_e32 v9, v9, v10
	v_fmamk_f32 v9, v9, 0x3c000000, v177
	v_cmp_gt_f32_e32 vcc, s16, v9
	v_mul_f32_e32 v10, 0x4b800000, v9
	s_nop 0
	v_cndmask_b32_e32 v9, v9, v10, vcc
	v_rsq_f32_e32 v9, v9
	s_nop 0
	v_mul_f32_e32 v10, 0x45800000, v9
	v_cndmask_b32_e32 v9, v9, v10, vcc
	v_mul_f32_e32 v8, v8, v9
	v_bfe_u32 v10, v8, 16, 1
	v_add3_u32 v8, v8, v10, s83
	v_add_u32_e32 v10, s5, v6
	v_mul_f32_e32 v7, v7, v9
	ds_write_b16_d16_hi v10, v8
	v_bfe_u32 v8, v7, 16, 1
	s_add_i32 s5, s5, 2
	v_add3_u32 v7, v7, v8, s83
	ds_write_b16_d16_hi v10, v7 offset:272
	s_waitcnt vmcnt(21)
	v_lshlrev_b32_e32 v8, 16, v30
	v_mul_f32_e32 v9, 0.5, v8
	v_mul_f32_e32 v8, 0x3f3504f3, v8
	v_fma_f32 v10, |v8|, s2, 1.0
	v_rcp_f32_e32 v10, v10
	v_and_b32_e32 v7, 0xffff0000, v30
	v_fmamk_f32 v11, v10, 0x3f87dc22, v176
	v_fmaak_f32 v11, v10, v11, 0x3fb5f0e3
	v_fmaak_f32 v11, v10, v11, 0xbe91a98e
	v_fmaak_f32 v11, v10, v11, 0x3e827906
	v_mul_f32_e32 v10, v10, v11
	v_mul_f32_e64 v11, |v8|, s3
	v_mul_f32_e64 v11, |v8|, v11
	v_exp_f32_e32 v11, v11
	s_nop 0
	v_fma_f32 v10, -v11, v10, 1.0
	v_bfi_b32 v8, s13, v10, v8
	v_mul_f32_e32 v10, 0.5, v7
	v_mul_f32_e32 v7, 0x3f3504f3, v7
	v_fma_f32 v11, |v7|, s2, 1.0
	v_rcp_f32_e32 v11, v11
	v_add_f32_e32 v8, 1.0, v8
	v_fmamk_f32 v12, v11, 0x3f87dc22, v176
	v_fmaak_f32 v12, v11, v12, 0x3fb5f0e3
	v_fmaak_f32 v12, v11, v12, 0xbe91a98e
	v_fmaak_f32 v12, v11, v12, 0x3e827906
	v_mul_f32_e32 v11, v11, v12
	v_mul_f32_e64 v12, |v7|, s3
	v_mul_f32_e64 v12, |v7|, v12
	v_exp_f32_e32 v12, v12
	s_nop 0
	v_fma_f32 v11, -v12, v11, 1.0
	v_bfi_b32 v7, s13, v11, v7
	v_add_f32_e32 v7, 1.0, v7
	v_mul_f32_e32 v11, v10, v7
	v_fmac_f32_e32 v11, v9, v8
	s_nop 1
	v_add_f32_dpp v11, v11, v11 row_ror:8 row_mask:0xf bank_mask:0xf bound_ctrl:1
	s_nop 1
	v_add_f32_dpp v11, v11, v11 row_ror:4 row_mask:0xf bank_mask:0xf bound_ctrl:1
	s_nop 1
	v_add_f32_dpp v11, v11, v11 row_ror:2 row_mask:0xf bank_mask:0xf bound_ctrl:1
	s_nop 1
	v_add_f32_dpp v11, v11, v11 row_ror:1 row_mask:0xf bank_mask:0xf bound_ctrl:1
	ds_bpermute_b32 v12, v3, v11
	s_waitcnt lgkmcnt(0)
	v_add_f32_e32 v11, v11, v12
	v_mov_b32_e32 v12, v11
	s_nop 1
	v_permlane32_swap_b32_e32 v11, v12
	v_add_f32_e32 v11, v11, v12
	v_mul_f32_e32 v11, 0x3c000000, v11
	v_fma_f32 v7, v10, v7, -v11
	v_fma_f32 v8, v9, v8, -v11
	v_mul_f32_e32 v9, v7, v7
	v_fmac_f32_e32 v9, v8, v8
	s_nop 1
	v_add_f32_dpp v9, v9, v9 row_ror:8 row_mask:0xf bank_mask:0xf bound_ctrl:1
	s_nop 1
	v_add_f32_dpp v9, v9, v9 row_ror:4 row_mask:0xf bank_mask:0xf bound_ctrl:1
	s_nop 1
	v_add_f32_dpp v9, v9, v9 row_ror:2 row_mask:0xf bank_mask:0xf bound_ctrl:1
	s_nop 1
	v_add_f32_dpp v9, v9, v9 row_ror:1 row_mask:0xf bank_mask:0xf bound_ctrl:1
	ds_bpermute_b32 v10, v3, v9
	s_waitcnt lgkmcnt(0)
	v_add_f32_e32 v9, v9, v10
	v_mov_b32_e32 v10, v9
	s_nop 1
	v_permlane32_swap_b32_e32 v9, v10
	v_add_f32_e32 v9, v9, v10
	v_fmamk_f32 v9, v9, 0x3c000000, v177
	v_cmp_gt_f32_e32 vcc, s16, v9
	v_mul_f32_e32 v10, 0x4b800000, v9
	s_nop 0
	v_cndmask_b32_e32 v9, v9, v10, vcc
	v_rsq_f32_e32 v9, v9
	s_nop 0
	v_mul_f32_e32 v10, 0x45800000, v9
	v_cndmask_b32_e32 v9, v9, v10, vcc
	v_mul_f32_e32 v8, v8, v9
	v_bfe_u32 v10, v8, 16, 1
	v_add3_u32 v8, v8, v10, s83
	v_add_u32_e32 v10, s5, v6
	v_mul_f32_e32 v7, v7, v9
	ds_write_b16_d16_hi v10, v8
	v_bfe_u32 v8, v7, 16, 1
	s_add_i32 s5, s5, 2
	v_add3_u32 v7, v7, v8, s83
	ds_write_b16_d16_hi v10, v7 offset:272
	s_waitcnt vmcnt(20)
; DI bf16 f2bf(float f) { unsigned u = __float_as_uint(f); u += 0x7fffu + ((u >> 16) & 1u); return (bf16)(u >> 16); }
; DI float gelu(float x) { return 0.5f * x * (1.f + erf_as(x * 0.70710678118654752f)); }
;   DI bf16* P() const { return (bf16*)(p.ws + WS_P); }
; DI void vgt_tile(const Ctx& c, int ti, bf16* lds) {
;     ...
;   for (int rr = 0; rr < 32; ++rr) {
;     const int t = wave * 32 + rr;
;     const unsigned u = *(const unsigned*)(c.P() + (size_t)(row0 + t) * LDP + C_V + g * 128 + 2 * lane);
;     const float a = gelu(__uint_as_float(u << 16)), b = gelu(__uint_as_float(u & 0xffff0000u));
;     const float mean = wave_sum(a + b) * (1.f / 128.f);
;     const float da = a - mean, db = b - mean;
;     const float rstd = rsqrtf(wave_sum(da * da + db * db) * (1.f / 128.f) + LN_EPS);
;     lds[(2 * lane) * LDT + t] = f2bf(da * rstd);
;     lds[(2 * lane + 1) * LDT + t] = f2bf(db * rstd);
;   }
	v_lshlrev_b32_e32 v8, 16, v31
	v_mul_f32_e32 v9, 0.5, v8
	v_mul_f32_e32 v8, 0x3f3504f3, v8
	v_fma_f32 v10, |v8|, s2, 1.0
	v_rcp_f32_e32 v10, v10
	v_and_b32_e32 v7, 0xffff0000, v31
	v_fmamk_f32 v11, v10, 0x3f87dc22, v176
	v_fmaak_f32 v11, v10, v11, 0x3fb5f0e3
	v_fmaak_f32 v11, v10, v11, 0xbe91a98e
	v_fmaak_f32 v11, v10, v11, 0x3e827906
	v_mul_f32_e32 v10, v10, v11
	v_mul_f32_e64 v11, |v8|, s3
	v_mul_f32_e64 v11, |v8|, v11
	v_exp_f32_e32 v11, v11
	s_nop 0
	v_fma_f32 v10, -v11, v10, 1.0
	v_bfi_b32 v8, s13, v10, v8
	v_mul_f32_e32 v10, 0.5, v7
	v_mul_f32_e32 v7, 0x3f3504f3, v7
	v_fma_f32 v11, |v7|, s2, 1.0
	v_rcp_f32_e32 v11, v11
	v_add_f32_e32 v8, 1.0, v8
	v_fmamk_f32 v12, v11, 0x3f87dc22, v176
	v_fmaak_f32 v12, v11, v12, 0x3fb5f0e3
	v_fmaak_f32 v12, v11, v12, 0xbe91a98e
	v_fmaak_f32 v12, v11, v12, 0x3e827906
	v_mul_f32_e32 v11, v11, v12
	v_mul_f32_e64 v12, |v7|, s3
	v_mul_f32_e64 v12, |v7|, v12
	v_exp_f32_e32 v12, v12
	s_nop 0
	v_fma_f32 v11, -v12, v11, 1.0
	v_bfi_b32 v7, s13, v11, v7
	v_add_f32_e32 v7, 1.0, v7
	v_mul_f32_e32 v11, v10, v7
	v_fmac_f32_e32 v11, v9, v8
	s_nop 1
	v_add_f32_dpp v11, v11, v11 row_ror:8 row_mask:0xf bank_mask:0xf bound_ctrl:1
	s_nop 1
	v_add_f32_dpp v11, v11, v11 row_ror:4 row_mask:0xf bank_mask:0xf bound_ctrl:1
	s_nop 1
	v_add_f32_dpp v11, v11, v11 row_ror:2 row_mask:0xf bank_mask:0xf bound_ctrl:1
	s_nop 1
	v_add_f32_dpp v11, v11, v11 row_ror:1 row_mask:0xf bank_mask:0xf bound_ctrl:1
	ds_bpermute_b32 v12, v3, v11
	s_waitcnt lgkmcnt(0)
	v_add_f32_e32 v11, v11, v12
	v_mov_b32_e32 v12, v11
	s_nop 1
	v_permlane32_swap_b32_e32 v11, v12
	v_add_f32_e32 v11, v11, v12
	v_mul_f32_e32 v11, 0x3c000000, v11
	v_fma_f32 v7, v10, v7, -v11
	v_fma_f32 v8, v9, v8, -v11
	v_mul_f32_e32 v9, v7, v7
	v_fmac_f32_e32 v9, v8, v8
	s_nop 1
	v_add_f32_dpp v9, v9, v9 row_ror:8 row_mask:0xf bank_mask:0xf bound_ctrl:1
	s_nop 1
	v_add_f32_dpp v9, v9, v9 row_ror:4 row_mask:0xf bank_mask:0xf bound_ctrl:1
	s_nop 1
	v_add_f32_dpp v9, v9, v9 row_ror:2 row_mask:0xf bank_mask:0xf bound_ctrl:1
	s_nop 1
	v_add_f32_dpp v9, v9, v9 row_ror:1 row_mask:0xf bank_mask:0xf bound_ctrl:1
	ds_bpermute_b32 v10, v3, v9
	s_waitcnt lgkmcnt(0)
	v_add_f32_e32 v9, v9, v10
	v_mov_b32_e32 v10, v9
	s_nop 1
	v_permlane32_swap_b32_e32 v9, v10
	v_add_f32_e32 v9, v9, v10
	v_fmamk_f32 v9, v9, 0x3c000000, v177
	v_cmp_gt_f32_e32 vcc, s16, v9
	v_mul_f32_e32 v10, 0x4b800000, v9
	s_nop 0
	v_cndmask_b32_e32 v9, v9, v10, vcc
	v_rsq_f32_e32 v9, v9
	s_nop 0
	v_mul_f32_e32 v10, 0x45800000, v9
	v_cndmask_b32_e32 v9, v9, v10, vcc
	v_mul_f32_e32 v8, v8, v9
	v_bfe_u32 v10, v8, 16, 1
	v_add3_u32 v8, v8, v10, s83
	v_add_u32_e32 v10, s5, v6
	v_mul_f32_e32 v7, v7, v9
	ds_write_b16_d16_hi v10, v8
	v_bfe_u32 v8, v7, 16, 1
	s_add_i32 s5, s5, 2
	v_add3_u32 v7, v7, v8, s83
	ds_write_b16_d16_hi v10, v7 offset:272
	s_waitcnt vmcnt(19)
	v_lshlrev_b32_e32 v8, 16, v32
	v_mul_f32_e32 v9, 0.5, v8
	v_mul_f32_e32 v8, 0x3f3504f3, v8
	v_fma_f32 v10, |v8|, s2, 1.0
	v_rcp_f32_e32 v10, v10
	v_and_b32_e32 v7, 0xffff0000, v32
	v_fmamk_f32 v11, v10, 0x3f87dc22, v176
	v_fmaak_f32 v11, v10, v11, 0x3fb5f0e3
	v_fmaak_f32 v11, v10, v11, 0xbe91a98e
	v_fmaak_f32 v11, v10, v11, 0x3e827906
	v_mul_f32_e32 v10, v10, v11
	v_mul_f32_e64 v11, |v8|, s3
	v_mul_f32_e64 v11, |v8|, v11
	v_exp_f32_e32 v11, v11
	s_nop 0
	v_fma_f32 v10, -v11, v10, 1.0
	v_bfi_b32 v8, s13, v10, v8
	v_mul_f32_e32 v10, 0.5, v7
	v_mul_f32_e32 v7, 0x3f3504f3, v7
	v_fma_f32 v11, |v7|, s2, 1.0
	v_rcp_f32_e32 v11, v11
	v_add_f32_e32 v8, 1.0, v8
	v_fmamk_f32 v12, v11, 0x3f87dc22, v176
	v_fmaak_f32 v12, v11, v12, 0x3fb5f0e3
	v_fmaak_f32 v12, v11, v12, 0xbe91a98e
	v_fmaak_f32 v12, v11, v12, 0x3e827906
	v_mul_f32_e32 v11, v11, v12
	v_mul_f32_e64 v12, |v7|, s3
	v_mul_f32_e64 v12, |v7|, v12
	v_exp_f32_e32 v12, v12
	s_nop 0
	v_fma_f32 v11, -v12, v11, 1.0
	v_bfi_b32 v7, s13, v11, v7
	v_add_f32_e32 v7, 1.0, v7
	v_mul_f32_e32 v11, v10, v7
	v_fmac_f32_e32 v11, v9, v8
	s_nop 1
	v_add_f32_dpp v11, v11, v11 row_ror:8 row_mask:0xf bank_mask:0xf bound_ctrl:1
	s_nop 1
	v_add_f32_dpp v11, v11, v11 row_ror:4 row_mask:0xf bank_mask:0xf bound_ctrl:1
	s_nop 1
	v_add_f32_dpp v11, v11, v11 row_ror:2 row_mask:0xf bank_mask:0xf bound_ctrl:1
	s_nop 1
	v_add_f32_dpp v11, v11, v11 row_ror:1 row_mask:0xf bank_mask:0xf bound_ctrl:1
	ds_bpermute_b32 v12, v3, v11
	s_waitcnt lgkmcnt(0)
	v_add_f32_e32 v11, v11, v12
	v_mov_b32_e32 v12, v11
	s_nop 1
	v_permlane32_swap_b32_e32 v11, v12
	v_add_f32_e32 v11, v11, v12
	v_mul_f32_e32 v11, 0x3c000000, v11
	v_fma_f32 v7, v10, v7, -v11
	v_fma_f32 v8, v9, v8, -v11
	v_mul_f32_e32 v9, v7, v7
	v_fmac_f32_e32 v9, v8, v8
	s_nop 1
	v_add_f32_dpp v9, v9, v9 row_ror:8 row_mask:0xf bank_mask:0xf bound_ctrl:1
	s_nop 1
	v_add_f32_dpp v9, v9, v9 row_ror:4 row_mask:0xf bank_mask:0xf bound_ctrl:1
	s_nop 1
	v_add_f32_dpp v9, v9, v9 row_ror:2 row_mask:0xf bank_mask:0xf bound_ctrl:1
	s_nop 1
	v_add_f32_dpp v9, v9, v9 row_ror:1 row_mask:0xf bank_mask:0xf bound_ctrl:1
	ds_bpermute_b32 v10, v3, v9
	s_waitcnt lgkmcnt(0)
	v_add_f32_e32 v9, v9, v10
	v_mov_b32_e32 v10, v9
	s_nop 1
	v_permlane32_swap_b32_e32 v9, v10
	v_add_f32_e32 v9, v9, v10
	v_fmamk_f32 v9, v9, 0x3c000000, v177
	v_cmp_gt_f32_e32 vcc, s16, v9
	v_mul_f32_e32 v10, 0x4b800000, v9
	s_nop 0
	v_cndmask_b32_e32 v9, v9, v10, vcc
	v_rsq_f32_e32 v9, v9
	s_nop 0
	v_mul_f32_e32 v10, 0x45800000, v9
	v_cndmask_b32_e32 v9, v9, v10, vcc
	v_mul_f32_e32 v8, v8, v9
	v_bfe_u32 v10, v8, 16, 1
	v_add3_u32 v8, v8, v10, s83
	v_add_u32_e32 v10, s5, v6
	v_mul_f32_e32 v7, v7, v9
	ds_write_b16_d16_hi v10, v8
	v_bfe_u32 v8, v7, 16, 1
	s_add_i32 s5, s5, 2
	v_add3_u32 v7, v7, v8, s83
	ds_write_b16_d16_hi v10, v7 offset:272
	s_waitcnt vmcnt(18)
; DI bf16 f2bf(float f) { unsigned u = __float_as_uint(f); u += 0x7fffu + ((u >> 16) & 1u); return (bf16)(u >> 16); }
; DI float gelu(float x) { return 0.5f * x * (1.f + erf_as(x * 0.70710678118654752f)); }
;   DI bf16* P() const { return (bf16*)(p.ws + WS_P); }
; DI void vgt_tile(const Ctx& c, int ti, bf16* lds) {
;     ...
;   for (int rr = 0; rr < 32; ++rr) {
;     const int t = wave * 32 + rr;
;     const unsigned u = *(const unsigned*)(c.P() + (size_t)(row0 + t) * LDP + C_V + g * 128 + 2 * lane);
;     const float a = gelu(__uint_as_float(u << 16)), b = gelu(__uint_as_float(u & 0xffff0000u));
;     const float mean = wave_sum(a + b) * (1.f / 128.f);
;     const float da = a - mean, db = b - mean;
;     const float rstd = rsqrtf(wave_sum(da * da + db * db) * (1.f / 128.f) + LN_EPS);
;     lds[(2 * lane) * LDT + t] = f2bf(da * rstd);
;     lds[(2 * lane + 1) * LDT + t] = f2bf(db * rstd);
;   }
	v_lshlrev_b32_e32 v8, 16, v33
	v_mul_f32_e32 v9, 0.5, v8
	v_mul_f32_e32 v8, 0x3f3504f3, v8
	v_fma_f32 v10, |v8|, s2, 1.0
	v_rcp_f32_e32 v10, v10
	v_and_b32_e32 v7, 0xffff0000, v33
	v_fmamk_f32 v11, v10, 0x3f87dc22, v176
	v_fmaak_f32 v11, v10, v11, 0x3fb5f0e3
	v_fmaak_f32 v11, v10, v11, 0xbe91a98e
	v_fmaak_f32 v11, v10, v11, 0x3e827906
	v_mul_f32_e32 v10, v10, v11
	v_mul_f32_e64 v11, |v8|, s3
	v_mul_f32_e64 v11, |v8|, v11
	v_exp_f32_e32 v11, v11
	s_nop 0
	v_fma_f32 v10, -v11, v10, 1.0
	v_bfi_b32 v8, s13, v10, v8
	v_mul_f32_e32 v10, 0.5, v7
	v_mul_f32_e32 v7, 0x3f3504f3, v7
	v_fma_f32 v11, |v7|, s2, 1.0
	v_rcp_f32_e32 v11, v11
	v_add_f32_e32 v8, 1.0, v8
	v_fmamk_f32 v12, v11, 0x3f87dc22, v176
	v_fmaak_f32 v12, v11, v12, 0x3fb5f0e3
	v_fmaak_f32 v12, v11, v12, 0xbe91a98e
	v_fmaak_f32 v12, v11, v12, 0x3e827906
	v_mul_f32_e32 v11, v11, v12
	v_mul_f32_e64 v12, |v7|, s3
	v_mul_f32_e64 v12, |v7|, v12
	v_exp_f32_e32 v12, v12
	s_nop 0
	v_fma_f32 v11, -v12, v11, 1.0
	v_bfi_b32 v7, s13, v11, v7
	v_add_f32_e32 v7, 1.0, v7
	v_mul_f32_e32 v11, v10, v7
	v_fmac_f32_e32 v11, v9, v8
	s_nop 1
	v_add_f32_dpp v11, v11, v11 row_ror:8 row_mask:0xf bank_mask:0xf bound_ctrl:1
	s_nop 1
	v_add_f32_dpp v11, v11, v11 row_ror:4 row_mask:0xf bank_mask:0xf bound_ctrl:1
	s_nop 1
	v_add_f32_dpp v11, v11, v11 row_ror:2 row_mask:0xf bank_mask:0xf bound_ctrl:1
	s_nop 1
	v_add_f32_dpp v11, v11, v11 row_ror:1 row_mask:0xf bank_mask:0xf bound_ctrl:1
	ds_bpermute_b32 v12, v3, v11
	s_waitcnt lgkmcnt(0)
	v_add_f32_e32 v11, v11, v12
	v_mov_b32_e32 v12, v11
	s_nop 1
	v_permlane32_swap_b32_e32 v11, v12
	v_add_f32_e32 v11, v11, v12
	v_mul_f32_e32 v11, 0x3c000000, v11
	v_fma_f32 v7, v10, v7, -v11
	v_fma_f32 v8, v9, v8, -v11
	v_mul_f32_e32 v9, v7, v7
	v_fmac_f32_e32 v9, v8, v8
	s_nop 1
	v_add_f32_dpp v9, v9, v9 row_ror:8 row_mask:0xf bank_mask:0xf bound_ctrl:1
	s_nop 1
	v_add_f32_dpp v9, v9, v9 row_ror:4 row_mask:0xf bank_mask:0xf bound_ctrl:1
	s_nop 1
	v_add_f32_dpp v9, v9, v9 row_ror:2 row_mask:0xf bank_mask:0xf bound_ctrl:1
	s_nop 1
	v_add_f32_dpp v9, v9, v9 row_ror:1 row_mask:0xf bank_mask:0xf bound_ctrl:1
	ds_bpermute_b32 v10, v3, v9
	s_waitcnt lgkmcnt(0)
	v_add_f32_e32 v9, v9, v10
	v_mov_b32_e32 v10, v9
	s_nop 1
	v_permlane32_swap_b32_e32 v9, v10
	v_add_f32_e32 v9, v9, v10
	v_fmamk_f32 v9, v9, 0x3c000000, v177
	v_cmp_gt_f32_e32 vcc, s16, v9
	v_mul_f32_e32 v10, 0x4b800000, v9
	s_nop 0
	v_cndmask_b32_e32 v9, v9, v10, vcc
	v_rsq_f32_e32 v9, v9
	s_nop 0
	v_mul_f32_e32 v10, 0x45800000, v9
	v_cndmask_b32_e32 v9, v9, v10, vcc
	v_mul_f32_e32 v8, v8, v9
	v_bfe_u32 v10, v8, 16, 1
	v_add3_u32 v8, v8, v10, s83
	v_add_u32_e32 v10, s5, v6
	v_mul_f32_e32 v7, v7, v9
	ds_write_b16_d16_hi v10, v8
	v_bfe_u32 v8, v7, 16, 1
	s_add_i32 s5, s5, 2
	v_add3_u32 v7, v7, v8, s83
	ds_write_b16_d16_hi v10, v7 offset:272
	s_waitcnt vmcnt(17)
	v_lshlrev_b32_e32 v8, 16, v34
	v_mul_f32_e32 v9, 0.5, v8
	v_mul_f32_e32 v8, 0x3f3504f3, v8
	v_fma_f32 v10, |v8|, s2, 1.0
	v_rcp_f32_e32 v10, v10
	v_and_b32_e32 v7, 0xffff0000, v34
	v_fmamk_f32 v11, v10, 0x3f87dc22, v176
	v_fmaak_f32 v11, v10, v11, 0x3fb5f0e3
	v_fmaak_f32 v11, v10, v11, 0xbe91a98e
	v_fmaak_f32 v11, v10, v11, 0x3e827906
	v_mul_f32_e32 v10, v10, v11
	v_mul_f32_e64 v11, |v8|, s3
	v_mul_f32_e64 v11, |v8|, v11
	v_exp_f32_e32 v11, v11
	s_nop 0
	v_fma_f32 v10, -v11, v10, 1.0
	v_bfi_b32 v8, s13, v10, v8
	v_mul_f32_e32 v10, 0.5, v7
	v_mul_f32_e32 v7, 0x3f3504f3, v7
	v_fma_f32 v11, |v7|, s2, 1.0
	v_rcp_f32_e32 v11, v11
	v_add_f32_e32 v8, 1.0, v8
	v_fmamk_f32 v12, v11, 0x3f87dc22, v176
	v_fmaak_f32 v12, v11, v12, 0x3fb5f0e3
	v_fmaak_f32 v12, v11, v12, 0xbe91a98e
	v_fmaak_f32 v12, v11, v12, 0x3e827906
	v_mul_f32_e32 v11, v11, v12
	v_mul_f32_e64 v12, |v7|, s3
	v_mul_f32_e64 v12, |v7|, v12
	v_exp_f32_e32 v12, v12
	s_nop 0
	v_fma_f32 v11, -v12, v11, 1.0
	v_bfi_b32 v7, s13, v11, v7
	v_add_f32_e32 v7, 1.0, v7
	v_mul_f32_e32 v11, v10, v7
	v_fmac_f32_e32 v11, v9, v8
	s_nop 1
	v_add_f32_dpp v11, v11, v11 row_ror:8 row_mask:0xf bank_mask:0xf bound_ctrl:1
	s_nop 1
	v_add_f32_dpp v11, v11, v11 row_ror:4 row_mask:0xf bank_mask:0xf bound_ctrl:1
	s_nop 1
	v_add_f32_dpp v11, v11, v11 row_ror:2 row_mask:0xf bank_mask:0xf bound_ctrl:1
	s_nop 1
	v_add_f32_dpp v11, v11, v11 row_ror:1 row_mask:0xf bank_mask:0xf bound_ctrl:1
	ds_bpermute_b32 v12, v3, v11
	s_waitcnt lgkmcnt(0)
	v_add_f32_e32 v11, v11, v12
	v_mov_b32_e32 v12, v11
	s_nop 1
	v_permlane32_swap_b32_e32 v11, v12
	v_add_f32_e32 v11, v11, v12
	v_mul_f32_e32 v11, 0x3c000000, v11
	v_fma_f32 v7, v10, v7, -v11
	v_fma_f32 v8, v9, v8, -v11
	v_mul_f32_e32 v9, v7, v7
	v_fmac_f32_e32 v9, v8, v8
	s_nop 1
	v_add_f32_dpp v9, v9, v9 row_ror:8 row_mask:0xf bank_mask:0xf bound_ctrl:1
	s_nop 1
	v_add_f32_dpp v9, v9, v9 row_ror:4 row_mask:0xf bank_mask:0xf bound_ctrl:1
	s_nop 1
	v_add_f32_dpp v9, v9, v9 row_ror:2 row_mask:0xf bank_mask:0xf bound_ctrl:1
	s_nop 1
	v_add_f32_dpp v9, v9, v9 row_ror:1 row_mask:0xf bank_mask:0xf bound_ctrl:1
	ds_bpermute_b32 v10, v3, v9
	s_waitcnt lgkmcnt(0)
	v_add_f32_e32 v9, v9, v10
	v_mov_b32_e32 v10, v9
	s_nop 1
	v_permlane32_swap_b32_e32 v9, v10
	v_add_f32_e32 v9, v9, v10
	v_fmamk_f32 v9, v9, 0x3c000000, v177
	v_cmp_gt_f32_e32 vcc, s16, v9
	v_mul_f32_e32 v10, 0x4b800000, v9
	s_nop 0
	v_cndmask_b32_e32 v9, v9, v10, vcc
	v_rsq_f32_e32 v9, v9
	s_nop 0
	v_mul_f32_e32 v10, 0x45800000, v9
	v_cndmask_b32_e32 v9, v9, v10, vcc
	v_mul_f32_e32 v8, v8, v9
	v_bfe_u32 v10, v8, 16, 1
	v_add3_u32 v8, v8, v10, s83
	v_add_u32_e32 v10, s5, v6
	v_mul_f32_e32 v7, v7, v9
	ds_write_b16_d16_hi v10, v8
	v_bfe_u32 v8, v7, 16, 1
	s_add_i32 s5, s5, 2
	v_add3_u32 v7, v7, v8, s83
	ds_write_b16_d16_hi v10, v7 offset:272
	s_waitcnt vmcnt(16)
; DI bf16 f2bf(float f) { unsigned u = __float_as_uint(f); u += 0x7fffu + ((u >> 16) & 1u); return (bf16)(u >> 16); }
; DI float gelu(float x) { return 0.5f * x * (1.f + erf_as(x * 0.70710678118654752f)); }
;   DI bf16* P() const { return (bf16*)(p.ws + WS_P); }
; DI void vgt_tile(const Ctx& c, int ti, bf16* lds) {
;     ...
;   for (int rr = 0; rr < 32; ++rr) {
;     const int t = wave * 32 + rr;
;     const unsigned u = *(const unsigned*)(c.P() + (size_t)(row0 + t) * LDP + C_V + g * 128 + 2 * lane);
;     const float a = gelu(__uint_as_float(u << 16)), b = gelu(__uint_as_float(u & 0xffff0000u));
;     const float mean = wave_sum(a + b) * (1.f / 128.f);
;     const float da = a - mean, db = b - mean;
;     const float rstd = rsqrtf(wave_sum(da * da + db * db) * (1.f / 128.f) + LN_EPS);
;     lds[(2 * lane) * LDT + t] = f2bf(da * rstd);
;     lds[(2 * lane + 1) * LDT + t] = f2bf(db * rstd);
;   }
	v_lshlrev_b32_e32 v8, 16, v35
	v_mul_f32_e32 v9, 0.5, v8
	v_mul_f32_e32 v8, 0x3f3504f3, v8
	v_fma_f32 v10, |v8|, s2, 1.0
	v_rcp_f32_e32 v10, v10
	v_and_b32_e32 v7, 0xffff0000, v35
	v_fmamk_f32 v11, v10, 0x3f87dc22, v176
	v_fmaak_f32 v11, v10, v11, 0x3fb5f0e3
	v_fmaak_f32 v11, v10, v11, 0xbe91a98e
	v_fmaak_f32 v11, v10, v11, 0x3e827906
	v_mul_f32_e32 v10, v10, v11
	v_mul_f32_e64 v11, |v8|, s3
	v_mul_f32_e64 v11, |v8|, v11
	v_exp_f32_e32 v11, v11
	s_nop 0
	v_fma_f32 v10, -v11, v10, 1.0
	v_bfi_b32 v8, s13, v10, v8
	v_mul_f32_e32 v10, 0.5, v7
	v_mul_f32_e32 v7, 0x3f3504f3, v7
	v_fma_f32 v11, |v7|, s2, 1.0
	v_rcp_f32_e32 v11, v11
	v_add_f32_e32 v8, 1.0, v8
	v_fmamk_f32 v12, v11, 0x3f87dc22, v176
	v_fmaak_f32 v12, v11, v12, 0x3fb5f0e3
	v_fmaak_f32 v12, v11, v12, 0xbe91a98e
	v_fmaak_f32 v12, v11, v12, 0x3e827906
	v_mul_f32_e32 v11, v11, v12
	v_mul_f32_e64 v12, |v7|, s3
	v_mul_f32_e64 v12, |v7|, v12
	v_exp_f32_e32 v12, v12
	s_nop 0
	v_fma_f32 v11, -v12, v11, 1.0
	v_bfi_b32 v7, s13, v11, v7
	v_add_f32_e32 v7, 1.0, v7
	v_mul_f32_e32 v11, v10, v7
	v_fmac_f32_e32 v11, v9, v8
	s_nop 1
	v_add_f32_dpp v11, v11, v11 row_ror:8 row_mask:0xf bank_mask:0xf bound_ctrl:1
	s_nop 1
	v_add_f32_dpp v11, v11, v11 row_ror:4 row_mask:0xf bank_mask:0xf bound_ctrl:1
	s_nop 1
	v_add_f32_dpp v11, v11, v11 row_ror:2 row_mask:0xf bank_mask:0xf bound_ctrl:1
	s_nop 1
	v_add_f32_dpp v11, v11, v11 row_ror:1 row_mask:0xf bank_mask:0xf bound_ctrl:1
	ds_bpermute_b32 v12, v3, v11
	s_waitcnt lgkmcnt(0)
	v_add_f32_e32 v11, v11, v12
	v_mov_b32_e32 v12, v11
	s_nop 1
	v_permlane32_swap_b32_e32 v11, v12
	v_add_f32_e32 v11, v11, v12
	v_mul_f32_e32 v11, 0x3c000000, v11
	v_fma_f32 v7, v10, v7, -v11
	v_fma_f32 v8, v9, v8, -v11
	v_mul_f32_e32 v9, v7, v7
	v_fmac_f32_e32 v9, v8, v8
	s_nop 1
	v_add_f32_dpp v9, v9, v9 row_ror:8 row_mask:0xf bank_mask:0xf bound_ctrl:1
	s_nop 1
	v_add_f32_dpp v9, v9, v9 row_ror:4 row_mask:0xf bank_mask:0xf bound_ctrl:1
	s_nop 1
	v_add_f32_dpp v9, v9, v9 row_ror:2 row_mask:0xf bank_mask:0xf bound_ctrl:1
	s_nop 1
	v_add_f32_dpp v9, v9, v9 row_ror:1 row_mask:0xf bank_mask:0xf bound_ctrl:1
	ds_bpermute_b32 v10, v3, v9
	s_waitcnt lgkmcnt(0)
	v_add_f32_e32 v9, v9, v10
	v_mov_b32_e32 v10, v9
	s_nop 1
	v_permlane32_swap_b32_e32 v9, v10
	v_add_f32_e32 v9, v9, v10
	v_fmamk_f32 v9, v9, 0x3c000000, v177
	v_cmp_gt_f32_e32 vcc, s16, v9
	v_mul_f32_e32 v10, 0x4b800000, v9
	s_nop 0
	v_cndmask_b32_e32 v9, v9, v10, vcc
	v_rsq_f32_e32 v9, v9
	s_nop 0
	v_mul_f32_e32 v10, 0x45800000, v9
	v_cndmask_b32_e32 v9, v9, v10, vcc
	v_mul_f32_e32 v8, v8, v9
	v_bfe_u32 v10, v8, 16, 1
	v_add3_u32 v8, v8, v10, s83
	v_add_u32_e32 v10, s5, v6
	v_mul_f32_e32 v7, v7, v9
	ds_write_b16_d16_hi v10, v8
	v_bfe_u32 v8, v7, 16, 1
	s_add_i32 s5, s5, 2
	v_add3_u32 v7, v7, v8, s83
	ds_write_b16_d16_hi v10, v7 offset:272
	s_waitcnt vmcnt(15)
	v_lshlrev_b32_e32 v8, 16, v36
	v_mul_f32_e32 v9, 0.5, v8
	v_mul_f32_e32 v8, 0x3f3504f3, v8
	v_fma_f32 v10, |v8|, s2, 1.0
	v_rcp_f32_e32 v10, v10
	v_and_b32_e32 v7, 0xffff0000, v36
	v_fmamk_f32 v11, v10, 0x3f87dc22, v176
	v_fmaak_f32 v11, v10, v11, 0x3fb5f0e3
	v_fmaak_f32 v11, v10, v11, 0xbe91a98e
	v_fmaak_f32 v11, v10, v11, 0x3e827906
	v_mul_f32_e32 v10, v10, v11
	v_mul_f32_e64 v11, |v8|, s3
	v_mul_f32_e64 v11, |v8|, v11
	v_exp_f32_e32 v11, v11
	s_nop 0
	v_fma_f32 v10, -v11, v10, 1.0
	v_bfi_b32 v8, s13, v10, v8
	v_mul_f32_e32 v10, 0.5, v7
	v_mul_f32_e32 v7, 0x3f3504f3, v7
	v_fma_f32 v11, |v7|, s2, 1.0
	v_rcp_f32_e32 v11, v11
	v_add_f32_e32 v8, 1.0, v8
	v_fmamk_f32 v12, v11, 0x3f87dc22, v176
	v_fmaak_f32 v12, v11, v12, 0x3fb5f0e3
	v_fmaak_f32 v12, v11, v12, 0xbe91a98e
	v_fmaak_f32 v12, v11, v12, 0x3e827906
	v_mul_f32_e32 v11, v11, v12
	v_mul_f32_e64 v12, |v7|, s3
	v_mul_f32_e64 v12, |v7|, v12
	v_exp_f32_e32 v12, v12
	s_nop 0
	v_fma_f32 v11, -v12, v11, 1.0
	v_bfi_b32 v7, s13, v11, v7
	v_add_f32_e32 v7, 1.0, v7
	v_mul_f32_e32 v11, v10, v7
	v_fmac_f32_e32 v11, v9, v8
	s_nop 1
	v_add_f32_dpp v11, v11, v11 row_ror:8 row_mask:0xf bank_mask:0xf bound_ctrl:1
	s_nop 1
	v_add_f32_dpp v11, v11, v11 row_ror:4 row_mask:0xf bank_mask:0xf bound_ctrl:1
	s_nop 1
	v_add_f32_dpp v11, v11, v11 row_ror:2 row_mask:0xf bank_mask:0xf bound_ctrl:1
	s_nop 1
	v_add_f32_dpp v11, v11, v11 row_ror:1 row_mask:0xf bank_mask:0xf bound_ctrl:1
	ds_bpermute_b32 v12, v3, v11
	s_waitcnt lgkmcnt(0)
	v_add_f32_e32 v11, v11, v12
	v_mov_b32_e32 v12, v11
	s_nop 1
	v_permlane32_swap_b32_e32 v11, v12
	v_add_f32_e32 v11, v11, v12
	v_mul_f32_e32 v11, 0x3c000000, v11
	v_fma_f32 v7, v10, v7, -v11
	v_fma_f32 v8, v9, v8, -v11
	v_mul_f32_e32 v9, v7, v7
	v_fmac_f32_e32 v9, v8, v8
	s_nop 1
	v_add_f32_dpp v9, v9, v9 row_ror:8 row_mask:0xf bank_mask:0xf bound_ctrl:1
	s_nop 1
	v_add_f32_dpp v9, v9, v9 row_ror:4 row_mask:0xf bank_mask:0xf bound_ctrl:1
	s_nop 1
	v_add_f32_dpp v9, v9, v9 row_ror:2 row_mask:0xf bank_mask:0xf bound_ctrl:1
	s_nop 1
	v_add_f32_dpp v9, v9, v9 row_ror:1 row_mask:0xf bank_mask:0xf bound_ctrl:1
	ds_bpermute_b32 v10, v3, v9
	s_waitcnt lgkmcnt(0)
	v_add_f32_e32 v9, v9, v10
	v_mov_b32_e32 v10, v9
	s_nop 1
	v_permlane32_swap_b32_e32 v9, v10
	v_add_f32_e32 v9, v9, v10
	v_fmamk_f32 v9, v9, 0x3c000000, v177
	v_cmp_gt_f32_e32 vcc, s16, v9
	v_mul_f32_e32 v10, 0x4b800000, v9
	s_nop 0
	v_cndmask_b32_e32 v9, v9, v10, vcc
	v_rsq_f32_e32 v9, v9
	s_nop 0
	v_mul_f32_e32 v10, 0x45800000, v9
	v_cndmask_b32_e32 v9, v9, v10, vcc
	v_mul_f32_e32 v8, v8, v9
	v_bfe_u32 v10, v8, 16, 1
	v_add3_u32 v8, v8, v10, s83
	v_add_u32_e32 v10, s5, v6
	v_mul_f32_e32 v7, v7, v9
	ds_write_b16_d16_hi v10, v8
	v_bfe_u32 v8, v7, 16, 1
	s_add_i32 s5, s5, 2
	v_add3_u32 v7, v7, v8, s83
	ds_write_b16_d16_hi v10, v7 offset:272
	s_waitcnt vmcnt(14)
; DI bf16 f2bf(float f) { unsigned u = __float_as_uint(f); u += 0x7fffu + ((u >> 16) & 1u); return (bf16)(u >> 16); }
; DI float gelu(float x) { return 0.5f * x * (1.f + erf_as(x * 0.70710678118654752f)); }
;   DI bf16* P() const { return (bf16*)(p.ws + WS_P); }
; DI void vgt_tile(const Ctx& c, int ti, bf16* lds) {
;     ...
;   for (int rr = 0; rr < 32; ++rr) {
;     const int t = wave * 32 + rr;
;     const unsigned u = *(const unsigned*)(c.P() + (size_t)(row0 + t) * LDP + C_V + g * 128 + 2 * lane);
;     const float a = gelu(__uint_as_float(u << 16)), b = gelu(__uint_as_float(u & 0xffff0000u));
;     const float mean = wave_sum(a + b) * (1.f / 128.f);
;     const float da = a - mean, db = b - mean;
;     const float rstd = rsqrtf(wave_sum(da * da + db * db) * (1.f / 128.f) + LN_EPS);
;     lds[(2 * lane) * LDT + t] = f2bf(da * rstd);
;     lds[(2 * lane + 1) * LDT + t] = f2bf(db * rstd);
;   }
	v_lshlrev_b32_e32 v8, 16, v37
	v_mul_f32_e32 v9, 0.5, v8
	v_mul_f32_e32 v8, 0x3f3504f3, v8
	v_fma_f32 v10, |v8|, s2, 1.0
	v_rcp_f32_e32 v10, v10
	v_and_b32_e32 v7, 0xffff0000, v37
	v_fmamk_f32 v11, v10, 0x3f87dc22, v176
	v_fmaak_f32 v11, v10, v11, 0x3fb5f0e3
	v_fmaak_f32 v11, v10, v11, 0xbe91a98e
	v_fmaak_f32 v11, v10, v11, 0x3e827906
	v_mul_f32_e32 v10, v10, v11
	v_mul_f32_e64 v11, |v8|, s3
	v_mul_f32_e64 v11, |v8|, v11
	v_exp_f32_e32 v11, v11
	s_nop 0
	v_fma_f32 v10, -v11, v10, 1.0
	v_bfi_b32 v8, s13, v10, v8
	v_mul_f32_e32 v10, 0.5, v7
	v_mul_f32_e32 v7, 0x3f3504f3, v7
	v_fma_f32 v11, |v7|, s2, 1.0
	v_rcp_f32_e32 v11, v11
	v_add_f32_e32 v8, 1.0, v8
	v_fmamk_f32 v12, v11, 0x3f87dc22, v176
	v_fmaak_f32 v12, v11, v12, 0x3fb5f0e3
	v_fmaak_f32 v12, v11, v12, 0xbe91a98e
	v_fmaak_f32 v12, v11, v12, 0x3e827906
	v_mul_f32_e32 v11, v11, v12
	v_mul_f32_e64 v12, |v7|, s3
	v_mul_f32_e64 v12, |v7|, v12
	v_exp_f32_e32 v12, v12
	s_nop 0
	v_fma_f32 v11, -v12, v11, 1.0
	v_bfi_b32 v7, s13, v11, v7
	v_add_f32_e32 v7, 1.0, v7
	v_mul_f32_e32 v11, v10, v7
	v_fmac_f32_e32 v11, v9, v8
	s_nop 1
	v_add_f32_dpp v11, v11, v11 row_ror:8 row_mask:0xf bank_mask:0xf bound_ctrl:1
	s_nop 1
	v_add_f32_dpp v11, v11, v11 row_ror:4 row_mask:0xf bank_mask:0xf bound_ctrl:1
	s_nop 1
	v_add_f32_dpp v11, v11, v11 row_ror:2 row_mask:0xf bank_mask:0xf bound_ctrl:1
	s_nop 1
	v_add_f32_dpp v11, v11, v11 row_ror:1 row_mask:0xf bank_mask:0xf bound_ctrl:1
	ds_bpermute_b32 v12, v3, v11
	s_waitcnt lgkmcnt(0)
	v_add_f32_e32 v11, v11, v12
	v_mov_b32_e32 v12, v11
	s_nop 1
	v_permlane32_swap_b32_e32 v11, v12
	v_add_f32_e32 v11, v11, v12
	v_mul_f32_e32 v11, 0x3c000000, v11
	v_fma_f32 v7, v10, v7, -v11
	v_fma_f32 v8, v9, v8, -v11
	v_mul_f32_e32 v9, v7, v7
	v_fmac_f32_e32 v9, v8, v8
	s_nop 1
	v_add_f32_dpp v9, v9, v9 row_ror:8 row_mask:0xf bank_mask:0xf bound_ctrl:1
	s_nop 1
	v_add_f32_dpp v9, v9, v9 row_ror:4 row_mask:0xf bank_mask:0xf bound_ctrl:1
	s_nop 1
	v_add_f32_dpp v9, v9, v9 row_ror:2 row_mask:0xf bank_mask:0xf bound_ctrl:1
	s_nop 1
	v_add_f32_dpp v9, v9, v9 row_ror:1 row_mask:0xf bank_mask:0xf bound_ctrl:1
	ds_bpermute_b32 v10, v3, v9
	s_waitcnt lgkmcnt(0)
	v_add_f32_e32 v9, v9, v10
	v_mov_b32_e32 v10, v9
	s_nop 1
	v_permlane32_swap_b32_e32 v9, v10
	v_add_f32_e32 v9, v9, v10
	v_fmamk_f32 v9, v9, 0x3c000000, v177
	v_cmp_gt_f32_e32 vcc, s16, v9
	v_mul_f32_e32 v10, 0x4b800000, v9
	s_nop 0
	v_cndmask_b32_e32 v9, v9, v10, vcc
	v_rsq_f32_e32 v9, v9
	s_nop 0
	v_mul_f32_e32 v10, 0x45800000, v9
	v_cndmask_b32_e32 v9, v9, v10, vcc
	v_mul_f32_e32 v8, v8, v9
	v_bfe_u32 v10, v8, 16, 1
	v_add3_u32 v8, v8, v10, s83
	v_add_u32_e32 v10, s5, v6
	v_mul_f32_e32 v7, v7, v9
	ds_write_b16_d16_hi v10, v8
	v_bfe_u32 v8, v7, 16, 1
	s_add_i32 s5, s5, 2
	v_add3_u32 v7, v7, v8, s83
	ds_write_b16_d16_hi v10, v7 offset:272
	s_waitcnt vmcnt(13)
	v_lshlrev_b32_e32 v8, 16, v38
	v_mul_f32_e32 v9, 0.5, v8
	v_mul_f32_e32 v8, 0x3f3504f3, v8
	v_fma_f32 v10, |v8|, s2, 1.0
	v_rcp_f32_e32 v10, v10
	v_and_b32_e32 v7, 0xffff0000, v38
	v_fmamk_f32 v11, v10, 0x3f87dc22, v176
	v_fmaak_f32 v11, v10, v11, 0x3fb5f0e3
	v_fmaak_f32 v11, v10, v11, 0xbe91a98e
	v_fmaak_f32 v11, v10, v11, 0x3e827906
	v_mul_f32_e32 v10, v10, v11
	v_mul_f32_e64 v11, |v8|, s3
	v_mul_f32_e64 v11, |v8|, v11
	v_exp_f32_e32 v11, v11
	s_nop 0
	v_fma_f32 v10, -v11, v10, 1.0
	v_bfi_b32 v8, s13, v10, v8
	v_mul_f32_e32 v10, 0.5, v7
	v_mul_f32_e32 v7, 0x3f3504f3, v7
	v_fma_f32 v11, |v7|, s2, 1.0
	v_rcp_f32_e32 v11, v11
	v_add_f32_e32 v8, 1.0, v8
	v_fmamk_f32 v12, v11, 0x3f87dc22, v176
	v_fmaak_f32 v12, v11, v12, 0x3fb5f0e3
	v_fmaak_f32 v12, v11, v12, 0xbe91a98e
	v_fmaak_f32 v12, v11, v12, 0x3e827906
	v_mul_f32_e32 v11, v11, v12
	v_mul_f32_e64 v12, |v7|, s3
	v_mul_f32_e64 v12, |v7|, v12
	v_exp_f32_e32 v12, v12
	s_nop 0
	v_fma_f32 v11, -v12, v11, 1.0
	v_bfi_b32 v7, s13, v11, v7
	v_add_f32_e32 v7, 1.0, v7
	v_mul_f32_e32 v11, v10, v7
	v_fmac_f32_e32 v11, v9, v8
	s_nop 1
	v_add_f32_dpp v11, v11, v11 row_ror:8 row_mask:0xf bank_mask:0xf bound_ctrl:1
	s_nop 1
	v_add_f32_dpp v11, v11, v11 row_ror:4 row_mask:0xf bank_mask:0xf bound_ctrl:1
	s_nop 1
	v_add_f32_dpp v11, v11, v11 row_ror:2 row_mask:0xf bank_mask:0xf bound_ctrl:1
	s_nop 1
	v_add_f32_dpp v11, v11, v11 row_ror:1 row_mask:0xf bank_mask:0xf bound_ctrl:1
	ds_bpermute_b32 v12, v3, v11
	s_waitcnt lgkmcnt(0)
	v_add_f32_e32 v11, v11, v12
	v_mov_b32_e32 v12, v11
	s_nop 1
	v_permlane32_swap_b32_e32 v11, v12
	v_add_f32_e32 v11, v11, v12
	v_mul_f32_e32 v11, 0x3c000000, v11
	v_fma_f32 v7, v10, v7, -v11
	v_fma_f32 v8, v9, v8, -v11
	v_mul_f32_e32 v9, v7, v7
	v_fmac_f32_e32 v9, v8, v8
	s_nop 1
	v_add_f32_dpp v9, v9, v9 row_ror:8 row_mask:0xf bank_mask:0xf bound_ctrl:1
	s_nop 1
	v_add_f32_dpp v9, v9, v9 row_ror:4 row_mask:0xf bank_mask:0xf bound_ctrl:1
	s_nop 1
	v_add_f32_dpp v9, v9, v9 row_ror:2 row_mask:0xf bank_mask:0xf bound_ctrl:1
	s_nop 1
	v_add_f32_dpp v9, v9, v9 row_ror:1 row_mask:0xf bank_mask:0xf bound_ctrl:1
	ds_bpermute_b32 v10, v3, v9
	s_waitcnt lgkmcnt(0)
	v_add_f32_e32 v9, v9, v10
	v_mov_b32_e32 v10, v9
	s_nop 1
	v_permlane32_swap_b32_e32 v9, v10
	v_add_f32_e32 v9, v9, v10
	v_fmamk_f32 v9, v9, 0x3c000000, v177
	v_cmp_gt_f32_e32 vcc, s16, v9
	v_mul_f32_e32 v10, 0x4b800000, v9
	s_nop 0
	v_cndmask_b32_e32 v9, v9, v10, vcc
	v_rsq_f32_e32 v9, v9
	s_nop 0
	v_mul_f32_e32 v10, 0x45800000, v9
	v_cndmask_b32_e32 v9, v9, v10, vcc
	v_mul_f32_e32 v8, v8, v9
	v_bfe_u32 v10, v8, 16, 1
	v_add3_u32 v8, v8, v10, s83
	v_add_u32_e32 v10, s5, v6
	v_mul_f32_e32 v7, v7, v9
	ds_write_b16_d16_hi v10, v8
	v_bfe_u32 v8, v7, 16, 1
	s_add_i32 s5, s5, 2
	v_add3_u32 v7, v7, v8, s83
	ds_write_b16_d16_hi v10, v7 offset:272
	s_waitcnt vmcnt(12)
; DI bf16 f2bf(float f) { unsigned u = __float_as_uint(f); u += 0x7fffu + ((u >> 16) & 1u); return (bf16)(u >> 16); }
; DI float gelu(float x) { return 0.5f * x * (1.f + erf_as(x * 0.70710678118654752f)); }
;   DI bf16* P() const { return (bf16*)(p.ws + WS_P); }
; DI void vgt_tile(const Ctx& c, int ti, bf16* lds) {
;     ...
;   for (int rr = 0; rr < 32; ++rr) {
;     const int t = wave * 32 + rr;
;     const unsigned u = *(const unsigned*)(c.P() + (size_t)(row0 + t) * LDP + C_V + g * 128 + 2 * lane);
;     const float a = gelu(__uint_as_float(u << 16)), b = gelu(__uint_as_float(u & 0xffff0000u));
;     const float mean = wave_sum(a + b) * (1.f / 128.f);
;     const float da = a - mean, db = b - mean;
;     const float rstd = rsqrtf(wave_sum(da * da + db * db) * (1.f / 128.f) + LN_EPS);
;     lds[(2 * lane) * LDT + t] = f2bf(da * rstd);
;     lds[(2 * lane + 1) * LDT + t] = f2bf(db * rstd);
;   }
	v_lshlrev_b32_e32 v8, 16, v39
	v_mul_f32_e32 v9, 0.5, v8
	v_mul_f32_e32 v8, 0x3f3504f3, v8
	v_fma_f32 v10, |v8|, s2, 1.0
	v_rcp_f32_e32 v10, v10
	v_and_b32_e32 v7, 0xffff0000, v39
	v_fmamk_f32 v11, v10, 0x3f87dc22, v176
	v_fmaak_f32 v11, v10, v11, 0x3fb5f0e3
	v_fmaak_f32 v11, v10, v11, 0xbe91a98e
	v_fmaak_f32 v11, v10, v11, 0x3e827906
	v_mul_f32_e32 v10, v10, v11
	v_mul_f32_e64 v11, |v8|, s3
	v_mul_f32_e64 v11, |v8|, v11
	v_exp_f32_e32 v11, v11
	s_nop 0
	v_fma_f32 v10, -v11, v10, 1.0
	v_bfi_b32 v8, s13, v10, v8
	v_mul_f32_e32 v10, 0.5, v7
	v_mul_f32_e32 v7, 0x3f3504f3, v7
	v_fma_f32 v11, |v7|, s2, 1.0
	v_rcp_f32_e32 v11, v11
	v_add_f32_e32 v8, 1.0, v8
	v_fmamk_f32 v12, v11, 0x3f87dc22, v176
	v_fmaak_f32 v12, v11, v12, 0x3fb5f0e3
	v_fmaak_f32 v12, v11, v12, 0xbe91a98e
	v_fmaak_f32 v12, v11, v12, 0x3e827906
	v_mul_f32_e32 v11, v11, v12
	v_mul_f32_e64 v12, |v7|, s3
	v_mul_f32_e64 v12, |v7|, v12
	v_exp_f32_e32 v12, v12
	s_nop 0
	v_fma_f32 v11, -v12, v11, 1.0
	v_bfi_b32 v7, s13, v11, v7
	v_add_f32_e32 v7, 1.0, v7
	v_mul_f32_e32 v11, v10, v7
	v_fmac_f32_e32 v11, v9, v8
	s_nop 1
	v_add_f32_dpp v11, v11, v11 row_ror:8 row_mask:0xf bank_mask:0xf bound_ctrl:1
	s_nop 1
	v_add_f32_dpp v11, v11, v11 row_ror:4 row_mask:0xf bank_mask:0xf bound_ctrl:1
	s_nop 1
	v_add_f32_dpp v11, v11, v11 row_ror:2 row_mask:0xf bank_mask:0xf bound_ctrl:1
	s_nop 1
	v_add_f32_dpp v11, v11, v11 row_ror:1 row_mask:0xf bank_mask:0xf bound_ctrl:1
	ds_bpermute_b32 v12, v3, v11
	s_waitcnt lgkmcnt(0)
	v_add_f32_e32 v11, v11, v12
	v_mov_b32_e32 v12, v11
	s_nop 1
	v_permlane32_swap_b32_e32 v11, v12
	v_add_f32_e32 v11, v11, v12
	v_mul_f32_e32 v11, 0x3c000000, v11
	v_fma_f32 v7, v10, v7, -v11
	v_fma_f32 v8, v9, v8, -v11
	v_mul_f32_e32 v9, v7, v7
	v_fmac_f32_e32 v9, v8, v8
	s_nop 1
	v_add_f32_dpp v9, v9, v9 row_ror:8 row_mask:0xf bank_mask:0xf bound_ctrl:1
	s_nop 1
	v_add_f32_dpp v9, v9, v9 row_ror:4 row_mask:0xf bank_mask:0xf bound_ctrl:1
	s_nop 1
	v_add_f32_dpp v9, v9, v9 row_ror:2 row_mask:0xf bank_mask:0xf bound_ctrl:1
	s_nop 1
	v_add_f32_dpp v9, v9, v9 row_ror:1 row_mask:0xf bank_mask:0xf bound_ctrl:1
	ds_bpermute_b32 v10, v3, v9
	s_waitcnt lgkmcnt(0)
	v_add_f32_e32 v9, v9, v10
	v_mov_b32_e32 v10, v9
	s_nop 1
	v_permlane32_swap_b32_e32 v9, v10
	v_add_f32_e32 v9, v9, v10
	v_fmamk_f32 v9, v9, 0x3c000000, v177
	v_cmp_gt_f32_e32 vcc, s16, v9
	v_mul_f32_e32 v10, 0x4b800000, v9
	s_nop 0
	v_cndmask_b32_e32 v9, v9, v10, vcc
	v_rsq_f32_e32 v9, v9
	s_nop 0
	v_mul_f32_e32 v10, 0x45800000, v9
	v_cndmask_b32_e32 v9, v9, v10, vcc
	v_mul_f32_e32 v8, v8, v9
	v_bfe_u32 v10, v8, 16, 1
	v_add3_u32 v8, v8, v10, s83
	v_add_u32_e32 v10, s5, v6
	v_mul_f32_e32 v7, v7, v9
	ds_write_b16_d16_hi v10, v8
	v_bfe_u32 v8, v7, 16, 1
	s_add_i32 s5, s5, 2
	v_add3_u32 v7, v7, v8, s83
	ds_write_b16_d16_hi v10, v7 offset:272
	s_waitcnt vmcnt(11)
	v_lshlrev_b32_e32 v8, 16, v40
	v_mul_f32_e32 v9, 0.5, v8
	v_mul_f32_e32 v8, 0x3f3504f3, v8
	v_fma_f32 v10, |v8|, s2, 1.0
	v_rcp_f32_e32 v10, v10
	v_and_b32_e32 v7, 0xffff0000, v40
	v_fmamk_f32 v11, v10, 0x3f87dc22, v176
	v_fmaak_f32 v11, v10, v11, 0x3fb5f0e3
	v_fmaak_f32 v11, v10, v11, 0xbe91a98e
	v_fmaak_f32 v11, v10, v11, 0x3e827906
	v_mul_f32_e32 v10, v10, v11
	v_mul_f32_e64 v11, |v8|, s3
	v_mul_f32_e64 v11, |v8|, v11
	v_exp_f32_e32 v11, v11
	s_nop 0
	v_fma_f32 v10, -v11, v10, 1.0
	v_bfi_b32 v8, s13, v10, v8
	v_mul_f32_e32 v10, 0.5, v7
	v_mul_f32_e32 v7, 0x3f3504f3, v7
	v_fma_f32 v11, |v7|, s2, 1.0
	v_rcp_f32_e32 v11, v11
	v_add_f32_e32 v8, 1.0, v8
	v_fmamk_f32 v12, v11, 0x3f87dc22, v176
	v_fmaak_f32 v12, v11, v12, 0x3fb5f0e3
	v_fmaak_f32 v12, v11, v12, 0xbe91a98e
	v_fmaak_f32 v12, v11, v12, 0x3e827906
	v_mul_f32_e32 v11, v11, v12
	v_mul_f32_e64 v12, |v7|, s3
	v_mul_f32_e64 v12, |v7|, v12
	v_exp_f32_e32 v12, v12
	s_nop 0
	v_fma_f32 v11, -v12, v11, 1.0
	v_bfi_b32 v7, s13, v11, v7
	v_add_f32_e32 v7, 1.0, v7
	v_mul_f32_e32 v11, v10, v7
	v_fmac_f32_e32 v11, v9, v8
	s_nop 1
	v_add_f32_dpp v11, v11, v11 row_ror:8 row_mask:0xf bank_mask:0xf bound_ctrl:1
	s_nop 1
	v_add_f32_dpp v11, v11, v11 row_ror:4 row_mask:0xf bank_mask:0xf bound_ctrl:1
	s_nop 1
	v_add_f32_dpp v11, v11, v11 row_ror:2 row_mask:0xf bank_mask:0xf bound_ctrl:1
	s_nop 1
	v_add_f32_dpp v11, v11, v11 row_ror:1 row_mask:0xf bank_mask:0xf bound_ctrl:1
	ds_bpermute_b32 v12, v3, v11
	s_waitcnt lgkmcnt(0)
	v_add_f32_e32 v11, v11, v12
	v_mov_b32_e32 v12, v11
	s_nop 1
	v_permlane32_swap_b32_e32 v11, v12
	v_add_f32_e32 v11, v11, v12
	v_mul_f32_e32 v11, 0x3c000000, v11
	v_fma_f32 v7, v10, v7, -v11
	v_fma_f32 v8, v9, v8, -v11
	v_mul_f32_e32 v9, v7, v7
	v_fmac_f32_e32 v9, v8, v8
	s_nop 1
	v_add_f32_dpp v9, v9, v9 row_ror:8 row_mask:0xf bank_mask:0xf bound_ctrl:1
	s_nop 1
	v_add_f32_dpp v9, v9, v9 row_ror:4 row_mask:0xf bank_mask:0xf bound_ctrl:1
	s_nop 1
	v_add_f32_dpp v9, v9, v9 row_ror:2 row_mask:0xf bank_mask:0xf bound_ctrl:1
	s_nop 1
	v_add_f32_dpp v9, v9, v9 row_ror:1 row_mask:0xf bank_mask:0xf bound_ctrl:1
	ds_bpermute_b32 v10, v3, v9
	s_waitcnt lgkmcnt(0)
	v_add_f32_e32 v9, v9, v10
	v_mov_b32_e32 v10, v9
	s_nop 1
	v_permlane32_swap_b32_e32 v9, v10
	v_add_f32_e32 v9, v9, v10
	v_fmamk_f32 v9, v9, 0x3c000000, v177
	v_cmp_gt_f32_e32 vcc, s16, v9
	v_mul_f32_e32 v10, 0x4b800000, v9
	s_nop 0
	v_cndmask_b32_e32 v9, v9, v10, vcc
	v_rsq_f32_e32 v9, v9
	s_nop 0
	v_mul_f32_e32 v10, 0x45800000, v9
	v_cndmask_b32_e32 v9, v9, v10, vcc
	v_mul_f32_e32 v8, v8, v9
	v_bfe_u32 v10, v8, 16, 1
	v_add3_u32 v8, v8, v10, s83
	v_add_u32_e32 v10, s5, v6
	v_mul_f32_e32 v7, v7, v9
	ds_write_b16_d16_hi v10, v8
	v_bfe_u32 v8, v7, 16, 1
	s_add_i32 s5, s5, 2
	v_add3_u32 v7, v7, v8, s83
	ds_write_b16_d16_hi v10, v7 offset:272
	s_waitcnt vmcnt(10)
; DI bf16 f2bf(float f) { unsigned u = __float_as_uint(f); u += 0x7fffu + ((u >> 16) & 1u); return (bf16)(u >> 16); }
; DI float gelu(float x) { return 0.5f * x * (1.f + erf_as(x * 0.70710678118654752f)); }
;   DI bf16* P() const { return (bf16*)(p.ws + WS_P); }
; DI void vgt_tile(const Ctx& c, int ti, bf16* lds) {
;     ...
;   for (int rr = 0; rr < 32; ++rr) {
;     const int t = wave * 32 + rr;
;     const unsigned u = *(const unsigned*)(c.P() + (size_t)(row0 + t) * LDP + C_V + g * 128 + 2 * lane);
;     const float a = gelu(__uint_as_float(u << 16)), b = gelu(__uint_as_float(u & 0xffff0000u));
;     const float mean = wave_sum(a + b) * (1.f / 128.f);
;     const float da = a - mean, db = b - mean;
;     const float rstd = rsqrtf(wave_sum(da * da + db * db) * (1.f / 128.f) + LN_EPS);
;     lds[(2 * lane) * LDT + t] = f2bf(da * rstd);
;     lds[(2 * lane + 1) * LDT + t] = f2bf(db * rstd);
;   }
	v_lshlrev_b32_e32 v8, 16, v41
	v_mul_f32_e32 v9, 0.5, v8
	v_mul_f32_e32 v8, 0x3f3504f3, v8
	v_fma_f32 v10, |v8|, s2, 1.0
	v_rcp_f32_e32 v10, v10
	v_and_b32_e32 v7, 0xffff0000, v41
	v_fmamk_f32 v11, v10, 0x3f87dc22, v176
	v_fmaak_f32 v11, v10, v11, 0x3fb5f0e3
	v_fmaak_f32 v11, v10, v11, 0xbe91a98e
	v_fmaak_f32 v11, v10, v11, 0x3e827906
	v_mul_f32_e32 v10, v10, v11
	v_mul_f32_e64 v11, |v8|, s3
	v_mul_f32_e64 v11, |v8|, v11
	v_exp_f32_e32 v11, v11
	s_nop 0
	v_fma_f32 v10, -v11, v10, 1.0
	v_bfi_b32 v8, s13, v10, v8
	v_mul_f32_e32 v10, 0.5, v7
	v_mul_f32_e32 v7, 0x3f3504f3, v7
	v_fma_f32 v11, |v7|, s2, 1.0
	v_rcp_f32_e32 v11, v11
	v_add_f32_e32 v8, 1.0, v8
	v_fmamk_f32 v12, v11, 0x3f87dc22, v176
	v_fmaak_f32 v12, v11, v12, 0x3fb5f0e3
	v_fmaak_f32 v12, v11, v12, 0xbe91a98e
	v_fmaak_f32 v12, v11, v12, 0x3e827906
	v_mul_f32_e32 v11, v11, v12
	v_mul_f32_e64 v12, |v7|, s3
	v_mul_f32_e64 v12, |v7|, v12
	v_exp_f32_e32 v12, v12
	s_nop 0
	v_fma_f32 v11, -v12, v11, 1.0
	v_bfi_b32 v7, s13, v11, v7
	v_add_f32_e32 v7, 1.0, v7
	v_mul_f32_e32 v11, v10, v7
	v_fmac_f32_e32 v11, v9, v8
	s_nop 1
	v_add_f32_dpp v11, v11, v11 row_ror:8 row_mask:0xf bank_mask:0xf bound_ctrl:1
	s_nop 1
	v_add_f32_dpp v11, v11, v11 row_ror:4 row_mask:0xf bank_mask:0xf bound_ctrl:1
	s_nop 1
	v_add_f32_dpp v11, v11, v11 row_ror:2 row_mask:0xf bank_mask:0xf bound_ctrl:1
	s_nop 1
	v_add_f32_dpp v11, v11, v11 row_ror:1 row_mask:0xf bank_mask:0xf bound_ctrl:1
	ds_bpermute_b32 v12, v3, v11
	s_waitcnt lgkmcnt(0)
	v_add_f32_e32 v11, v11, v12
	v_mov_b32_e32 v12, v11
	s_nop 1
	v_permlane32_swap_b32_e32 v11, v12
	v_add_f32_e32 v11, v11, v12
	v_mul_f32_e32 v11, 0x3c000000, v11
	v_fma_f32 v7, v10, v7, -v11
	v_fma_f32 v8, v9, v8, -v11
	v_mul_f32_e32 v9, v7, v7
	v_fmac_f32_e32 v9, v8, v8
	s_nop 1
	v_add_f32_dpp v9, v9, v9 row_ror:8 row_mask:0xf bank_mask:0xf bound_ctrl:1
	s_nop 1
	v_add_f32_dpp v9, v9, v9 row_ror:4 row_mask:0xf bank_mask:0xf bound_ctrl:1
	s_nop 1
	v_add_f32_dpp v9, v9, v9 row_ror:2 row_mask:0xf bank_mask:0xf bound_ctrl:1
	s_nop 1
	v_add_f32_dpp v9, v9, v9 row_ror:1 row_mask:0xf bank_mask:0xf bound_ctrl:1
	ds_bpermute_b32 v10, v3, v9
	s_waitcnt lgkmcnt(0)
	v_add_f32_e32 v9, v9, v10
	v_mov_b32_e32 v10, v9
	s_nop 1
	v_permlane32_swap_b32_e32 v9, v10
	v_add_f32_e32 v9, v9, v10
	v_fmamk_f32 v9, v9, 0x3c000000, v177
	v_cmp_gt_f32_e32 vcc, s16, v9
	v_mul_f32_e32 v10, 0x4b800000, v9
	s_nop 0
	v_cndmask_b32_e32 v9, v9, v10, vcc
	v_rsq_f32_e32 v9, v9
	s_nop 0
	v_mul_f32_e32 v10, 0x45800000, v9
	v_cndmask_b32_e32 v9, v9, v10, vcc
	v_mul_f32_e32 v8, v8, v9
	v_bfe_u32 v10, v8, 16, 1
	v_add3_u32 v8, v8, v10, s83
	v_add_u32_e32 v10, s5, v6
	v_mul_f32_e32 v7, v7, v9
	ds_write_b16_d16_hi v10, v8
	v_bfe_u32 v8, v7, 16, 1
	s_add_i32 s5, s5, 2
	v_add3_u32 v7, v7, v8, s83
	ds_write_b16_d16_hi v10, v7 offset:272
	s_waitcnt vmcnt(9)
	v_lshlrev_b32_e32 v8, 16, v42
	v_mul_f32_e32 v9, 0.5, v8
	v_mul_f32_e32 v8, 0x3f3504f3, v8
	v_fma_f32 v10, |v8|, s2, 1.0
	v_rcp_f32_e32 v10, v10
	v_and_b32_e32 v7, 0xffff0000, v42
	v_fmamk_f32 v11, v10, 0x3f87dc22, v176
	v_fmaak_f32 v11, v10, v11, 0x3fb5f0e3
	v_fmaak_f32 v11, v10, v11, 0xbe91a98e
	v_fmaak_f32 v11, v10, v11, 0x3e827906
	v_mul_f32_e32 v10, v10, v11
	v_mul_f32_e64 v11, |v8|, s3
	v_mul_f32_e64 v11, |v8|, v11
	v_exp_f32_e32 v11, v11
	s_nop 0
	v_fma_f32 v10, -v11, v10, 1.0
	v_bfi_b32 v8, s13, v10, v8
	v_mul_f32_e32 v10, 0.5, v7
	v_mul_f32_e32 v7, 0x3f3504f3, v7
	v_fma_f32 v11, |v7|, s2, 1.0
	v_rcp_f32_e32 v11, v11
	v_add_f32_e32 v8, 1.0, v8
	v_fmamk_f32 v12, v11, 0x3f87dc22, v176
	v_fmaak_f32 v12, v11, v12, 0x3fb5f0e3
	v_fmaak_f32 v12, v11, v12, 0xbe91a98e
	v_fmaak_f32 v12, v11, v12, 0x3e827906
	v_mul_f32_e32 v11, v11, v12
	v_mul_f32_e64 v12, |v7|, s3
	v_mul_f32_e64 v12, |v7|, v12
	v_exp_f32_e32 v12, v12
	s_nop 0
	v_fma_f32 v11, -v12, v11, 1.0
	v_bfi_b32 v7, s13, v11, v7
	v_add_f32_e32 v7, 1.0, v7
	v_mul_f32_e32 v11, v10, v7
	v_fmac_f32_e32 v11, v9, v8
	s_nop 1
	v_add_f32_dpp v11, v11, v11 row_ror:8 row_mask:0xf bank_mask:0xf bound_ctrl:1
	s_nop 1
	v_add_f32_dpp v11, v11, v11 row_ror:4 row_mask:0xf bank_mask:0xf bound_ctrl:1
	s_nop 1
	v_add_f32_dpp v11, v11, v11 row_ror:2 row_mask:0xf bank_mask:0xf bound_ctrl:1
	s_nop 1
	v_add_f32_dpp v11, v11, v11 row_ror:1 row_mask:0xf bank_mask:0xf bound_ctrl:1
	ds_bpermute_b32 v12, v3, v11
	s_waitcnt lgkmcnt(0)
	v_add_f32_e32 v11, v11, v12
	v_mov_b32_e32 v12, v11
	s_nop 1
	v_permlane32_swap_b32_e32 v11, v12
	v_add_f32_e32 v11, v11, v12
	v_mul_f32_e32 v11, 0x3c000000, v11
	v_fma_f32 v7, v10, v7, -v11
	v_fma_f32 v8, v9, v8, -v11
	v_mul_f32_e32 v9, v7, v7
	v_fmac_f32_e32 v9, v8, v8
	s_nop 1
	v_add_f32_dpp v9, v9, v9 row_ror:8 row_mask:0xf bank_mask:0xf bound_ctrl:1
	s_nop 1
	v_add_f32_dpp v9, v9, v9 row_ror:4 row_mask:0xf bank_mask:0xf bound_ctrl:1
	s_nop 1
	v_add_f32_dpp v9, v9, v9 row_ror:2 row_mask:0xf bank_mask:0xf bound_ctrl:1
	s_nop 1
	v_add_f32_dpp v9, v9, v9 row_ror:1 row_mask:0xf bank_mask:0xf bound_ctrl:1
	ds_bpermute_b32 v10, v3, v9
	s_waitcnt lgkmcnt(0)
	v_add_f32_e32 v9, v9, v10
	v_mov_b32_e32 v10, v9
	s_nop 1
	v_permlane32_swap_b32_e32 v9, v10
	v_add_f32_e32 v9, v9, v10
	v_fmamk_f32 v9, v9, 0x3c000000, v177
	v_cmp_gt_f32_e32 vcc, s16, v9
	v_mul_f32_e32 v10, 0x4b800000, v9
	s_nop 0
	v_cndmask_b32_e32 v9, v9, v10, vcc
	v_rsq_f32_e32 v9, v9
	s_nop 0
	v_mul_f32_e32 v10, 0x45800000, v9
	v_cndmask_b32_e32 v9, v9, v10, vcc
	v_mul_f32_e32 v8, v8, v9
	v_bfe_u32 v10, v8, 16, 1
	v_add3_u32 v8, v8, v10, s83
	v_add_u32_e32 v10, s5, v6
	v_mul_f32_e32 v7, v7, v9
	ds_write_b16_d16_hi v10, v8
	v_bfe_u32 v8, v7, 16, 1
	s_add_i32 s5, s5, 2
	v_add3_u32 v7, v7, v8, s83
	ds_write_b16_d16_hi v10, v7 offset:272
	s_waitcnt vmcnt(8)
; DI bf16 f2bf(float f) { unsigned u = __float_as_uint(f); u += 0x7fffu + ((u >> 16) & 1u); return (bf16)(u >> 16); }
; DI float gelu(float x) { return 0.5f * x * (1.f + erf_as(x * 0.70710678118654752f)); }
;   DI bf16* P() const { return (bf16*)(p.ws + WS_P); }
; DI void vgt_tile(const Ctx& c, int ti, bf16* lds) {
;     ...
;   for (int rr = 0; rr < 32; ++rr) {
;     const int t = wave * 32 + rr;
;     const unsigned u = *(const unsigned*)(c.P() + (size_t)(row0 + t) * LDP + C_V + g * 128 + 2 * lane);
;     const float a = gelu(__uint_as_float(u << 16)), b = gelu(__uint_as_float(u & 0xffff0000u));
;     const float mean = wave_sum(a + b) * (1.f / 128.f);
;     const float da = a - mean, db = b - mean;
;     const float rstd = rsqrtf(wave_sum(da * da + db * db) * (1.f / 128.f) + LN_EPS);
;     lds[(2 * lane) * LDT + t] = f2bf(da * rstd);
;     lds[(2 * lane + 1) * LDT + t] = f2bf(db * rstd);
;   }
	v_lshlrev_b32_e32 v8, 16, v43
	v_mul_f32_e32 v9, 0.5, v8
	v_mul_f32_e32 v8, 0x3f3504f3, v8
	v_fma_f32 v10, |v8|, s2, 1.0
	v_rcp_f32_e32 v10, v10
	v_and_b32_e32 v7, 0xffff0000, v43
	v_fmamk_f32 v11, v10, 0x3f87dc22, v176
	v_fmaak_f32 v11, v10, v11, 0x3fb5f0e3
	v_fmaak_f32 v11, v10, v11, 0xbe91a98e
	v_fmaak_f32 v11, v10, v11, 0x3e827906
	v_mul_f32_e32 v10, v10, v11
	v_mul_f32_e64 v11, |v8|, s3
	v_mul_f32_e64 v11, |v8|, v11
	v_exp_f32_e32 v11, v11
	s_nop 0
	v_fma_f32 v10, -v11, v10, 1.0
	v_bfi_b32 v8, s13, v10, v8
	v_mul_f32_e32 v10, 0.5, v7
	v_mul_f32_e32 v7, 0x3f3504f3, v7
	v_fma_f32 v11, |v7|, s2, 1.0
	v_rcp_f32_e32 v11, v11
	v_add_f32_e32 v8, 1.0, v8
	v_fmamk_f32 v12, v11, 0x3f87dc22, v176
	v_fmaak_f32 v12, v11, v12, 0x3fb5f0e3
	v_fmaak_f32 v12, v11, v12, 0xbe91a98e
	v_fmaak_f32 v12, v11, v12, 0x3e827906
	v_mul_f32_e32 v11, v11, v12
	v_mul_f32_e64 v12, |v7|, s3
	v_mul_f32_e64 v12, |v7|, v12
	v_exp_f32_e32 v12, v12
	s_nop 0
	v_fma_f32 v11, -v12, v11, 1.0
	v_bfi_b32 v7, s13, v11, v7
	v_add_f32_e32 v7, 1.0, v7
	v_mul_f32_e32 v11, v10, v7
	v_fmac_f32_e32 v11, v9, v8
	s_nop 1
	v_add_f32_dpp v11, v11, v11 row_ror:8 row_mask:0xf bank_mask:0xf bound_ctrl:1
	s_nop 1
	v_add_f32_dpp v11, v11, v11 row_ror:4 row_mask:0xf bank_mask:0xf bound_ctrl:1
	s_nop 1
	v_add_f32_dpp v11, v11, v11 row_ror:2 row_mask:0xf bank_mask:0xf bound_ctrl:1
	s_nop 1
	v_add_f32_dpp v11, v11, v11 row_ror:1 row_mask:0xf bank_mask:0xf bound_ctrl:1
	ds_bpermute_b32 v12, v3, v11
	s_waitcnt lgkmcnt(0)
	v_add_f32_e32 v11, v11, v12
	v_mov_b32_e32 v12, v11
	s_nop 1
	v_permlane32_swap_b32_e32 v11, v12
	v_add_f32_e32 v11, v11, v12
	v_mul_f32_e32 v11, 0x3c000000, v11
	v_fma_f32 v7, v10, v7, -v11
	v_fma_f32 v8, v9, v8, -v11
	v_mul_f32_e32 v9, v7, v7
	v_fmac_f32_e32 v9, v8, v8
	s_nop 1
	v_add_f32_dpp v9, v9, v9 row_ror:8 row_mask:0xf bank_mask:0xf bound_ctrl:1
	s_nop 1
	v_add_f32_dpp v9, v9, v9 row_ror:4 row_mask:0xf bank_mask:0xf bound_ctrl:1
	s_nop 1
	v_add_f32_dpp v9, v9, v9 row_ror:2 row_mask:0xf bank_mask:0xf bound_ctrl:1
	s_nop 1
	v_add_f32_dpp v9, v9, v9 row_ror:1 row_mask:0xf bank_mask:0xf bound_ctrl:1
	ds_bpermute_b32 v10, v3, v9
	s_waitcnt lgkmcnt(0)
	v_add_f32_e32 v9, v9, v10
	v_mov_b32_e32 v10, v9
	s_nop 1
	v_permlane32_swap_b32_e32 v9, v10
	v_add_f32_e32 v9, v9, v10
	v_fmamk_f32 v9, v9, 0x3c000000, v177
	v_cmp_gt_f32_e32 vcc, s16, v9
	v_mul_f32_e32 v10, 0x4b800000, v9
	s_nop 0
	v_cndmask_b32_e32 v9, v9, v10, vcc
	v_rsq_f32_e32 v9, v9
	s_nop 0
	v_mul_f32_e32 v10, 0x45800000, v9
	v_cndmask_b32_e32 v9, v9, v10, vcc
	v_mul_f32_e32 v8, v8, v9
	v_bfe_u32 v10, v8, 16, 1
	v_add3_u32 v8, v8, v10, s83
	v_add_u32_e32 v10, s5, v6
	v_mul_f32_e32 v7, v7, v9
	ds_write_b16_d16_hi v10, v8
	v_bfe_u32 v8, v7, 16, 1
	s_add_i32 s5, s5, 2
	v_add3_u32 v7, v7, v8, s83
	ds_write_b16_d16_hi v10, v7 offset:272
	s_waitcnt vmcnt(7)
	v_lshlrev_b32_e32 v8, 16, v44
	v_mul_f32_e32 v9, 0.5, v8
	v_mul_f32_e32 v8, 0x3f3504f3, v8
	v_fma_f32 v10, |v8|, s2, 1.0
	v_rcp_f32_e32 v10, v10
	v_and_b32_e32 v7, 0xffff0000, v44
	v_fmamk_f32 v11, v10, 0x3f87dc22, v176
	v_fmaak_f32 v11, v10, v11, 0x3fb5f0e3
	v_fmaak_f32 v11, v10, v11, 0xbe91a98e
	v_fmaak_f32 v11, v10, v11, 0x3e827906
	v_mul_f32_e32 v10, v10, v11
	v_mul_f32_e64 v11, |v8|, s3
	v_mul_f32_e64 v11, |v8|, v11
	v_exp_f32_e32 v11, v11
	s_nop 0
	v_fma_f32 v10, -v11, v10, 1.0
	v_bfi_b32 v8, s13, v10, v8
	v_mul_f32_e32 v10, 0.5, v7
	v_mul_f32_e32 v7, 0x3f3504f3, v7
	v_fma_f32 v11, |v7|, s2, 1.0
	v_rcp_f32_e32 v11, v11
	v_add_f32_e32 v8, 1.0, v8
	v_fmamk_f32 v12, v11, 0x3f87dc22, v176
	v_fmaak_f32 v12, v11, v12, 0x3fb5f0e3
	v_fmaak_f32 v12, v11, v12, 0xbe91a98e
	v_fmaak_f32 v12, v11, v12, 0x3e827906
	v_mul_f32_e32 v11, v11, v12
	v_mul_f32_e64 v12, |v7|, s3
	v_mul_f32_e64 v12, |v7|, v12
	v_exp_f32_e32 v12, v12
	s_nop 0
	v_fma_f32 v11, -v12, v11, 1.0
	v_bfi_b32 v7, s13, v11, v7
	v_add_f32_e32 v7, 1.0, v7
	v_mul_f32_e32 v11, v10, v7
	v_fmac_f32_e32 v11, v9, v8
	s_nop 1
	v_add_f32_dpp v11, v11, v11 row_ror:8 row_mask:0xf bank_mask:0xf bound_ctrl:1
	s_nop 1
	v_add_f32_dpp v11, v11, v11 row_ror:4 row_mask:0xf bank_mask:0xf bound_ctrl:1
	s_nop 1
	v_add_f32_dpp v11, v11, v11 row_ror:2 row_mask:0xf bank_mask:0xf bound_ctrl:1
	s_nop 1
	v_add_f32_dpp v11, v11, v11 row_ror:1 row_mask:0xf bank_mask:0xf bound_ctrl:1
	ds_bpermute_b32 v12, v3, v11
	s_waitcnt lgkmcnt(0)
	v_add_f32_e32 v11, v11, v12
	v_mov_b32_e32 v12, v11
	s_nop 1
	v_permlane32_swap_b32_e32 v11, v12
	v_add_f32_e32 v11, v11, v12
	v_mul_f32_e32 v11, 0x3c000000, v11
	v_fma_f32 v7, v10, v7, -v11
	v_fma_f32 v8, v9, v8, -v11
	v_mul_f32_e32 v9, v7, v7
	v_fmac_f32_e32 v9, v8, v8
	s_nop 1
	v_add_f32_dpp v9, v9, v9 row_ror:8 row_mask:0xf bank_mask:0xf bound_ctrl:1
	s_nop 1
	v_add_f32_dpp v9, v9, v9 row_ror:4 row_mask:0xf bank_mask:0xf bound_ctrl:1
	s_nop 1
	v_add_f32_dpp v9, v9, v9 row_ror:2 row_mask:0xf bank_mask:0xf bound_ctrl:1
	s_nop 1
	v_add_f32_dpp v9, v9, v9 row_ror:1 row_mask:0xf bank_mask:0xf bound_ctrl:1
	ds_bpermute_b32 v10, v3, v9
	s_waitcnt lgkmcnt(0)
	v_add_f32_e32 v9, v9, v10
	v_mov_b32_e32 v10, v9
	s_nop 1
	v_permlane32_swap_b32_e32 v9, v10
	v_add_f32_e32 v9, v9, v10
	v_fmamk_f32 v9, v9, 0x3c000000, v177
	v_cmp_gt_f32_e32 vcc, s16, v9
	v_mul_f32_e32 v10, 0x4b800000, v9
	s_nop 0
	v_cndmask_b32_e32 v9, v9, v10, vcc
	v_rsq_f32_e32 v9, v9
	s_nop 0
	v_mul_f32_e32 v10, 0x45800000, v9
	v_cndmask_b32_e32 v9, v9, v10, vcc
	v_mul_f32_e32 v8, v8, v9
	v_bfe_u32 v10, v8, 16, 1
	v_add3_u32 v8, v8, v10, s83
	v_add_u32_e32 v10, s5, v6
	v_mul_f32_e32 v7, v7, v9
	ds_write_b16_d16_hi v10, v8
	v_bfe_u32 v8, v7, 16, 1
	s_add_i32 s5, s5, 2
	v_add3_u32 v7, v7, v8, s83
	ds_write_b16_d16_hi v10, v7 offset:272
	s_waitcnt vmcnt(6)
; DI bf16 f2bf(float f) { unsigned u = __float_as_uint(f); u += 0x7fffu + ((u >> 16) & 1u); return (bf16)(u >> 16); }
; DI float gelu(float x) { return 0.5f * x * (1.f + erf_as(x * 0.70710678118654752f)); }
;   DI bf16* P() const { return (bf16*)(p.ws + WS_P); }
; DI void vgt_tile(const Ctx& c, int ti, bf16* lds) {
;     ...
;   for (int rr = 0; rr < 32; ++rr) {
;     const int t = wave * 32 + rr;
;     const unsigned u = *(const unsigned*)(c.P() + (size_t)(row0 + t) * LDP + C_V + g * 128 + 2 * lane);
;     const float a = gelu(__uint_as_float(u << 16)), b = gelu(__uint_as_float(u & 0xffff0000u));
;     const float mean = wave_sum(a + b) * (1.f / 128.f);
;     const float da = a - mean, db = b - mean;
;     const float rstd = rsqrtf(wave_sum(da * da + db * db) * (1.f / 128.f) + LN_EPS);
;     lds[(2 * lane) * LDT + t] = f2bf(da * rstd);
;     lds[(2 * lane + 1) * LDT + t] = f2bf(db * rstd);
;   }
	v_lshlrev_b32_e32 v8, 16, v45
	v_mul_f32_e32 v9, 0.5, v8
	v_mul_f32_e32 v8, 0x3f3504f3, v8
	v_fma_f32 v10, |v8|, s2, 1.0
	v_rcp_f32_e32 v10, v10
	v_and_b32_e32 v7, 0xffff0000, v45
	v_fmamk_f32 v11, v10, 0x3f87dc22, v176
	v_fmaak_f32 v11, v10, v11, 0x3fb5f0e3
	v_fmaak_f32 v11, v10, v11, 0xbe91a98e
	v_fmaak_f32 v11, v10, v11, 0x3e827906
	v_mul_f32_e32 v10, v10, v11
	v_mul_f32_e64 v11, |v8|, s3
	v_mul_f32_e64 v11, |v8|, v11
	v_exp_f32_e32 v11, v11
	s_nop 0
	v_fma_f32 v10, -v11, v10, 1.0
	v_bfi_b32 v8, s13, v10, v8
	v_mul_f32_e32 v10, 0.5, v7
	v_mul_f32_e32 v7, 0x3f3504f3, v7
	v_fma_f32 v11, |v7|, s2, 1.0
	v_rcp_f32_e32 v11, v11
	v_add_f32_e32 v8, 1.0, v8
	v_fmamk_f32 v12, v11, 0x3f87dc22, v176
	v_fmaak_f32 v12, v11, v12, 0x3fb5f0e3
	v_fmaak_f32 v12, v11, v12, 0xbe91a98e
	v_fmaak_f32 v12, v11, v12, 0x3e827906
	v_mul_f32_e32 v11, v11, v12
	v_mul_f32_e64 v12, |v7|, s3
	v_mul_f32_e64 v12, |v7|, v12
	v_exp_f32_e32 v12, v12
	s_nop 0
	v_fma_f32 v11, -v12, v11, 1.0
	v_bfi_b32 v7, s13, v11, v7
	v_add_f32_e32 v7, 1.0, v7
	v_mul_f32_e32 v11, v10, v7
	v_fmac_f32_e32 v11, v9, v8
	s_nop 1
	v_add_f32_dpp v11, v11, v11 row_ror:8 row_mask:0xf bank_mask:0xf bound_ctrl:1
	s_nop 1
	v_add_f32_dpp v11, v11, v11 row_ror:4 row_mask:0xf bank_mask:0xf bound_ctrl:1
	s_nop 1
	v_add_f32_dpp v11, v11, v11 row_ror:2 row_mask:0xf bank_mask:0xf bound_ctrl:1
	s_nop 1
	v_add_f32_dpp v11, v11, v11 row_ror:1 row_mask:0xf bank_mask:0xf bound_ctrl:1
	ds_bpermute_b32 v12, v3, v11
	s_waitcnt lgkmcnt(0)
	v_add_f32_e32 v11, v11, v12
	v_mov_b32_e32 v12, v11
	s_nop 1
	v_permlane32_swap_b32_e32 v11, v12
	v_add_f32_e32 v11, v11, v12
	v_mul_f32_e32 v11, 0x3c000000, v11
	v_fma_f32 v7, v10, v7, -v11
	v_fma_f32 v8, v9, v8, -v11
	v_mul_f32_e32 v9, v7, v7
	v_fmac_f32_e32 v9, v8, v8
	s_nop 1
	v_add_f32_dpp v9, v9, v9 row_ror:8 row_mask:0xf bank_mask:0xf bound_ctrl:1
	s_nop 1
	v_add_f32_dpp v9, v9, v9 row_ror:4 row_mask:0xf bank_mask:0xf bound_ctrl:1
	s_nop 1
	v_add_f32_dpp v9, v9, v9 row_ror:2 row_mask:0xf bank_mask:0xf bound_ctrl:1
	s_nop 1
	v_add_f32_dpp v9, v9, v9 row_ror:1 row_mask:0xf bank_mask:0xf bound_ctrl:1
	ds_bpermute_b32 v10, v3, v9
	s_waitcnt lgkmcnt(0)
	v_add_f32_e32 v9, v9, v10
	v_mov_b32_e32 v10, v9
	s_nop 1
	v_permlane32_swap_b32_e32 v9, v10
	v_add_f32_e32 v9, v9, v10
	v_fmamk_f32 v9, v9, 0x3c000000, v177
	v_cmp_gt_f32_e32 vcc, s16, v9
	v_mul_f32_e32 v10, 0x4b800000, v9
	s_nop 0
	v_cndmask_b32_e32 v9, v9, v10, vcc
	v_rsq_f32_e32 v9, v9
	s_nop 0
	v_mul_f32_e32 v10, 0x45800000, v9
	v_cndmask_b32_e32 v9, v9, v10, vcc
	v_mul_f32_e32 v8, v8, v9
	v_bfe_u32 v10, v8, 16, 1
	v_add3_u32 v8, v8, v10, s83
	v_add_u32_e32 v10, s5, v6
	v_mul_f32_e32 v7, v7, v9
	ds_write_b16_d16_hi v10, v8
	v_bfe_u32 v8, v7, 16, 1
	s_add_i32 s5, s5, 2
	v_add3_u32 v7, v7, v8, s83
	ds_write_b16_d16_hi v10, v7 offset:272
	s_waitcnt vmcnt(5)
	v_lshlrev_b32_e32 v8, 16, v46
	v_mul_f32_e32 v9, 0.5, v8
	v_mul_f32_e32 v8, 0x3f3504f3, v8
	v_fma_f32 v10, |v8|, s2, 1.0
	v_rcp_f32_e32 v10, v10
	v_and_b32_e32 v7, 0xffff0000, v46
	v_fmamk_f32 v11, v10, 0x3f87dc22, v176
	v_fmaak_f32 v11, v10, v11, 0x3fb5f0e3
	v_fmaak_f32 v11, v10, v11, 0xbe91a98e
	v_fmaak_f32 v11, v10, v11, 0x3e827906
	v_mul_f32_e32 v10, v10, v11
	v_mul_f32_e64 v11, |v8|, s3
	v_mul_f32_e64 v11, |v8|, v11
	v_exp_f32_e32 v11, v11
	s_nop 0
	v_fma_f32 v10, -v11, v10, 1.0
	v_bfi_b32 v8, s13, v10, v8
	v_mul_f32_e32 v10, 0.5, v7
	v_mul_f32_e32 v7, 0x3f3504f3, v7
	v_fma_f32 v11, |v7|, s2, 1.0
	v_rcp_f32_e32 v11, v11
	v_add_f32_e32 v8, 1.0, v8
	v_fmamk_f32 v12, v11, 0x3f87dc22, v176
	v_fmaak_f32 v12, v11, v12, 0x3fb5f0e3
	v_fmaak_f32 v12, v11, v12, 0xbe91a98e
	v_fmaak_f32 v12, v11, v12, 0x3e827906
	v_mul_f32_e32 v11, v11, v12
	v_mul_f32_e64 v12, |v7|, s3
	v_mul_f32_e64 v12, |v7|, v12
	v_exp_f32_e32 v12, v12
	s_nop 0
	v_fma_f32 v11, -v12, v11, 1.0
	v_bfi_b32 v7, s13, v11, v7
	v_add_f32_e32 v7, 1.0, v7
	v_mul_f32_e32 v11, v10, v7
	v_fmac_f32_e32 v11, v9, v8
	s_nop 1
	v_add_f32_dpp v11, v11, v11 row_ror:8 row_mask:0xf bank_mask:0xf bound_ctrl:1
	s_nop 1
	v_add_f32_dpp v11, v11, v11 row_ror:4 row_mask:0xf bank_mask:0xf bound_ctrl:1
	s_nop 1
	v_add_f32_dpp v11, v11, v11 row_ror:2 row_mask:0xf bank_mask:0xf bound_ctrl:1
	s_nop 1
	v_add_f32_dpp v11, v11, v11 row_ror:1 row_mask:0xf bank_mask:0xf bound_ctrl:1
	ds_bpermute_b32 v12, v3, v11
	s_waitcnt lgkmcnt(0)
	v_add_f32_e32 v11, v11, v12
	v_mov_b32_e32 v12, v11
	s_nop 1
	v_permlane32_swap_b32_e32 v11, v12
	v_add_f32_e32 v11, v11, v12
	v_mul_f32_e32 v11, 0x3c000000, v11
	v_fma_f32 v7, v10, v7, -v11
	v_fma_f32 v8, v9, v8, -v11
	v_mul_f32_e32 v9, v7, v7
	v_fmac_f32_e32 v9, v8, v8
	s_nop 1
	v_add_f32_dpp v9, v9, v9 row_ror:8 row_mask:0xf bank_mask:0xf bound_ctrl:1
	s_nop 1
	v_add_f32_dpp v9, v9, v9 row_ror:4 row_mask:0xf bank_mask:0xf bound_ctrl:1
	s_nop 1
	v_add_f32_dpp v9, v9, v9 row_ror:2 row_mask:0xf bank_mask:0xf bound_ctrl:1
	s_nop 1
	v_add_f32_dpp v9, v9, v9 row_ror:1 row_mask:0xf bank_mask:0xf bound_ctrl:1
	ds_bpermute_b32 v10, v3, v9
	s_waitcnt lgkmcnt(0)
	v_add_f32_e32 v9, v9, v10
	v_mov_b32_e32 v10, v9
	s_nop 1
	v_permlane32_swap_b32_e32 v9, v10
	v_add_f32_e32 v9, v9, v10
	v_fmamk_f32 v9, v9, 0x3c000000, v177
	v_cmp_gt_f32_e32 vcc, s16, v9
	v_mul_f32_e32 v10, 0x4b800000, v9
	s_nop 0
	v_cndmask_b32_e32 v9, v9, v10, vcc
	v_rsq_f32_e32 v9, v9
	s_nop 0
	v_mul_f32_e32 v10, 0x45800000, v9
	v_cndmask_b32_e32 v9, v9, v10, vcc
	v_mul_f32_e32 v8, v8, v9
	v_bfe_u32 v10, v8, 16, 1
	v_add3_u32 v8, v8, v10, s83
	v_add_u32_e32 v10, s5, v6
	v_mul_f32_e32 v7, v7, v9
	ds_write_b16_d16_hi v10, v8
	v_bfe_u32 v8, v7, 16, 1
	s_add_i32 s5, s5, 2
	v_add3_u32 v7, v7, v8, s83
	ds_write_b16_d16_hi v10, v7 offset:272
	s_waitcnt vmcnt(4)
; DI bf16 f2bf(float f) { unsigned u = __float_as_uint(f); u += 0x7fffu + ((u >> 16) & 1u); return (bf16)(u >> 16); }
; DI float gelu(float x) { return 0.5f * x * (1.f + erf_as(x * 0.70710678118654752f)); }
;   DI bf16* P() const { return (bf16*)(p.ws + WS_P); }
; DI void vgt_tile(const Ctx& c, int ti, bf16* lds) {
;     ...
;   for (int rr = 0; rr < 32; ++rr) {
;     const int t = wave * 32 + rr;
;     const unsigned u = *(const unsigned*)(c.P() + (size_t)(row0 + t) * LDP + C_V + g * 128 + 2 * lane);
;     const float a = gelu(__uint_as_float(u << 16)), b = gelu(__uint_as_float(u & 0xffff0000u));
;     const float mean = wave_sum(a + b) * (1.f / 128.f);
;     const float da = a - mean, db = b - mean;
;     const float rstd = rsqrtf(wave_sum(da * da + db * db) * (1.f / 128.f) + LN_EPS);
;     lds[(2 * lane) * LDT + t] = f2bf(da * rstd);
;     lds[(2 * lane + 1) * LDT + t] = f2bf(db * rstd);
;   }
	v_lshlrev_b32_e32 v8, 16, v47
	v_mul_f32_e32 v9, 0.5, v8
	v_mul_f32_e32 v8, 0x3f3504f3, v8
	v_fma_f32 v10, |v8|, s2, 1.0
	v_rcp_f32_e32 v10, v10
	v_and_b32_e32 v7, 0xffff0000, v47
	v_fmamk_f32 v11, v10, 0x3f87dc22, v176
	v_fmaak_f32 v11, v10, v11, 0x3fb5f0e3
	v_fmaak_f32 v11, v10, v11, 0xbe91a98e
	v_fmaak_f32 v11, v10, v11, 0x3e827906
	v_mul_f32_e32 v10, v10, v11
	v_mul_f32_e64 v11, |v8|, s3
	v_mul_f32_e64 v11, |v8|, v11
	v_exp_f32_e32 v11, v11
	s_nop 0
	v_fma_f32 v10, -v11, v10, 1.0
	v_bfi_b32 v8, s13, v10, v8
	v_mul_f32_e32 v10, 0.5, v7
	v_mul_f32_e32 v7, 0x3f3504f3, v7
	v_fma_f32 v11, |v7|, s2, 1.0
	v_rcp_f32_e32 v11, v11
	v_add_f32_e32 v8, 1.0, v8
	v_fmamk_f32 v12, v11, 0x3f87dc22, v176
	v_fmaak_f32 v12, v11, v12, 0x3fb5f0e3
	v_fmaak_f32 v12, v11, v12, 0xbe91a98e
	v_fmaak_f32 v12, v11, v12, 0x3e827906
	v_mul_f32_e32 v11, v11, v12
	v_mul_f32_e64 v12, |v7|, s3
	v_mul_f32_e64 v12, |v7|, v12
	v_exp_f32_e32 v12, v12
	s_nop 0
	v_fma_f32 v11, -v12, v11, 1.0
	v_bfi_b32 v7, s13, v11, v7
	v_add_f32_e32 v7, 1.0, v7
	v_mul_f32_e32 v11, v10, v7
	v_fmac_f32_e32 v11, v9, v8
	s_nop 1
	v_add_f32_dpp v11, v11, v11 row_ror:8 row_mask:0xf bank_mask:0xf bound_ctrl:1
	s_nop 1
	v_add_f32_dpp v11, v11, v11 row_ror:4 row_mask:0xf bank_mask:0xf bound_ctrl:1
	s_nop 1
	v_add_f32_dpp v11, v11, v11 row_ror:2 row_mask:0xf bank_mask:0xf bound_ctrl:1
	s_nop 1
	v_add_f32_dpp v11, v11, v11 row_ror:1 row_mask:0xf bank_mask:0xf bound_ctrl:1
	ds_bpermute_b32 v12, v3, v11
	s_waitcnt lgkmcnt(0)
	v_add_f32_e32 v11, v11, v12
	v_mov_b32_e32 v12, v11
	s_nop 1
	v_permlane32_swap_b32_e32 v11, v12
	v_add_f32_e32 v11, v11, v12
	v_mul_f32_e32 v11, 0x3c000000, v11
	v_fma_f32 v7, v10, v7, -v11
	v_fma_f32 v8, v9, v8, -v11
	v_mul_f32_e32 v9, v7, v7
	v_fmac_f32_e32 v9, v8, v8
	s_nop 1
	v_add_f32_dpp v9, v9, v9 row_ror:8 row_mask:0xf bank_mask:0xf bound_ctrl:1
	s_nop 1
	v_add_f32_dpp v9, v9, v9 row_ror:4 row_mask:0xf bank_mask:0xf bound_ctrl:1
	s_nop 1
	v_add_f32_dpp v9, v9, v9 row_ror:2 row_mask:0xf bank_mask:0xf bound_ctrl:1
	s_nop 1
	v_add_f32_dpp v9, v9, v9 row_ror:1 row_mask:0xf bank_mask:0xf bound_ctrl:1
	ds_bpermute_b32 v10, v3, v9
	s_waitcnt lgkmcnt(0)
	v_add_f32_e32 v9, v9, v10
	v_mov_b32_e32 v10, v9
	s_nop 1
	v_permlane32_swap_b32_e32 v9, v10
	v_add_f32_e32 v9, v9, v10
	v_fmamk_f32 v9, v9, 0x3c000000, v177
	v_cmp_gt_f32_e32 vcc, s16, v9
	v_mul_f32_e32 v10, 0x4b800000, v9
	s_nop 0
	v_cndmask_b32_e32 v9, v9, v10, vcc
	v_rsq_f32_e32 v9, v9
	s_nop 0
	v_mul_f32_e32 v10, 0x45800000, v9
	v_cndmask_b32_e32 v9, v9, v10, vcc
	v_mul_f32_e32 v8, v8, v9
	v_bfe_u32 v10, v8, 16, 1
	v_add3_u32 v8, v8, v10, s83
	v_add_u32_e32 v10, s5, v6
	v_mul_f32_e32 v7, v7, v9
	ds_write_b16_d16_hi v10, v8
	v_bfe_u32 v8, v7, 16, 1
	s_add_i32 s5, s5, 2
	v_add3_u32 v7, v7, v8, s83
	ds_write_b16_d16_hi v10, v7 offset:272
	s_waitcnt vmcnt(3)
	v_lshlrev_b32_e32 v8, 16, v48
	v_mul_f32_e32 v9, 0.5, v8
	v_mul_f32_e32 v8, 0x3f3504f3, v8
	v_fma_f32 v10, |v8|, s2, 1.0
	v_rcp_f32_e32 v10, v10
	v_and_b32_e32 v7, 0xffff0000, v48
	v_fmamk_f32 v11, v10, 0x3f87dc22, v176
	v_fmaak_f32 v11, v10, v11, 0x3fb5f0e3
	v_fmaak_f32 v11, v10, v11, 0xbe91a98e
	v_fmaak_f32 v11, v10, v11, 0x3e827906
	v_mul_f32_e32 v10, v10, v11
	v_mul_f32_e64 v11, |v8|, s3
	v_mul_f32_e64 v11, |v8|, v11
	v_exp_f32_e32 v11, v11
	s_nop 0
	v_fma_f32 v10, -v11, v10, 1.0
	v_bfi_b32 v8, s13, v10, v8
	v_mul_f32_e32 v10, 0.5, v7
	v_mul_f32_e32 v7, 0x3f3504f3, v7
	v_fma_f32 v11, |v7|, s2, 1.0
	v_rcp_f32_e32 v11, v11
	v_add_f32_e32 v8, 1.0, v8
	v_fmamk_f32 v12, v11, 0x3f87dc22, v176
	v_fmaak_f32 v12, v11, v12, 0x3fb5f0e3
	v_fmaak_f32 v12, v11, v12, 0xbe91a98e
	v_fmaak_f32 v12, v11, v12, 0x3e827906
	v_mul_f32_e32 v11, v11, v12
	v_mul_f32_e64 v12, |v7|, s3
	v_mul_f32_e64 v12, |v7|, v12
	v_exp_f32_e32 v12, v12
	s_nop 0
	v_fma_f32 v11, -v12, v11, 1.0
	v_bfi_b32 v7, s13, v11, v7
	v_add_f32_e32 v7, 1.0, v7
	v_mul_f32_e32 v11, v10, v7
	v_fmac_f32_e32 v11, v9, v8
	s_nop 1
	v_add_f32_dpp v11, v11, v11 row_ror:8 row_mask:0xf bank_mask:0xf bound_ctrl:1
	s_nop 1
	v_add_f32_dpp v11, v11, v11 row_ror:4 row_mask:0xf bank_mask:0xf bound_ctrl:1
	s_nop 1
	v_add_f32_dpp v11, v11, v11 row_ror:2 row_mask:0xf bank_mask:0xf bound_ctrl:1
	s_nop 1
	v_add_f32_dpp v11, v11, v11 row_ror:1 row_mask:0xf bank_mask:0xf bound_ctrl:1
	ds_bpermute_b32 v12, v3, v11
	s_waitcnt lgkmcnt(0)
	v_add_f32_e32 v11, v11, v12
	v_mov_b32_e32 v12, v11
	s_nop 1
	v_permlane32_swap_b32_e32 v11, v12
	v_add_f32_e32 v11, v11, v12
	v_mul_f32_e32 v11, 0x3c000000, v11
	v_fma_f32 v7, v10, v7, -v11
	v_fma_f32 v8, v9, v8, -v11
	v_mul_f32_e32 v9, v7, v7
	v_fmac_f32_e32 v9, v8, v8
	s_nop 1
	v_add_f32_dpp v9, v9, v9 row_ror:8 row_mask:0xf bank_mask:0xf bound_ctrl:1
	s_nop 1
	v_add_f32_dpp v9, v9, v9 row_ror:4 row_mask:0xf bank_mask:0xf bound_ctrl:1
	s_nop 1
	v_add_f32_dpp v9, v9, v9 row_ror:2 row_mask:0xf bank_mask:0xf bound_ctrl:1
	s_nop 1
	v_add_f32_dpp v9, v9, v9 row_ror:1 row_mask:0xf bank_mask:0xf bound_ctrl:1
	ds_bpermute_b32 v10, v3, v9
	s_waitcnt lgkmcnt(0)
	v_add_f32_e32 v9, v9, v10
	v_mov_b32_e32 v10, v9
	s_nop 1
	v_permlane32_swap_b32_e32 v9, v10
	v_add_f32_e32 v9, v9, v10
	v_fmamk_f32 v9, v9, 0x3c000000, v177
	v_cmp_gt_f32_e32 vcc, s16, v9
	v_mul_f32_e32 v10, 0x4b800000, v9
	s_nop 0
	v_cndmask_b32_e32 v9, v9, v10, vcc
	v_rsq_f32_e32 v9, v9
	s_nop 0
	v_mul_f32_e32 v10, 0x45800000, v9
	v_cndmask_b32_e32 v9, v9, v10, vcc
	v_mul_f32_e32 v8, v8, v9
	v_bfe_u32 v10, v8, 16, 1
	v_add3_u32 v8, v8, v10, s83
	v_add_u32_e32 v10, s5, v6
	v_mul_f32_e32 v7, v7, v9
	ds_write_b16_d16_hi v10, v8
	v_bfe_u32 v8, v7, 16, 1
	s_add_i32 s5, s5, 2
	v_add3_u32 v7, v7, v8, s83
	ds_write_b16_d16_hi v10, v7 offset:272
	s_waitcnt vmcnt(2)
; DI bf16 f2bf(float f) { unsigned u = __float_as_uint(f); u += 0x7fffu + ((u >> 16) & 1u); return (bf16)(u >> 16); }
; DI float gelu(float x) { return 0.5f * x * (1.f + erf_as(x * 0.70710678118654752f)); }
;   DI bf16* P() const { return (bf16*)(p.ws + WS_P); }
; DI void vgt_tile(const Ctx& c, int ti, bf16* lds) {
;     ...
;   for (int rr = 0; rr < 32; ++rr) {
;     const int t = wave * 32 + rr;
;     const unsigned u = *(const unsigned*)(c.P() + (size_t)(row0 + t) * LDP + C_V + g * 128 + 2 * lane);
;     const float a = gelu(__uint_as_float(u << 16)), b = gelu(__uint_as_float(u & 0xffff0000u));
;     const float mean = wave_sum(a + b) * (1.f / 128.f);
;     const float da = a - mean, db = b - mean;
;     const float rstd = rsqrtf(wave_sum(da * da + db * db) * (1.f / 128.f) + LN_EPS);
;     lds[(2 * lane) * LDT + t] = f2bf(da * rstd);
;     lds[(2 * lane + 1) * LDT + t] = f2bf(db * rstd);
;   }
	v_lshlrev_b32_e32 v8, 16, v49
	v_mul_f32_e32 v9, 0.5, v8
	v_mul_f32_e32 v8, 0x3f3504f3, v8
	v_fma_f32 v10, |v8|, s2, 1.0
	v_rcp_f32_e32 v10, v10
	v_and_b32_e32 v7, 0xffff0000, v49
	v_fmamk_f32 v11, v10, 0x3f87dc22, v176
	v_fmaak_f32 v11, v10, v11, 0x3fb5f0e3
	v_fmaak_f32 v11, v10, v11, 0xbe91a98e
	v_fmaak_f32 v11, v10, v11, 0x3e827906
	v_mul_f32_e32 v10, v10, v11
	v_mul_f32_e64 v11, |v8|, s3
	v_mul_f32_e64 v11, |v8|, v11
	v_exp_f32_e32 v11, v11
	s_nop 0
	v_fma_f32 v10, -v11, v10, 1.0
	v_bfi_b32 v8, s13, v10, v8
	v_mul_f32_e32 v10, 0.5, v7
	v_mul_f32_e32 v7, 0x3f3504f3, v7
	v_fma_f32 v11, |v7|, s2, 1.0
	v_rcp_f32_e32 v11, v11
	v_add_f32_e32 v8, 1.0, v8
	v_fmamk_f32 v12, v11, 0x3f87dc22, v176
	v_fmaak_f32 v12, v11, v12, 0x3fb5f0e3
	v_fmaak_f32 v12, v11, v12, 0xbe91a98e
	v_fmaak_f32 v12, v11, v12, 0x3e827906
	v_mul_f32_e32 v11, v11, v12
	v_mul_f32_e64 v12, |v7|, s3
	v_mul_f32_e64 v12, |v7|, v12
	v_exp_f32_e32 v12, v12
	s_nop 0
	v_fma_f32 v11, -v12, v11, 1.0
	v_bfi_b32 v7, s13, v11, v7
	v_add_f32_e32 v7, 1.0, v7
	v_mul_f32_e32 v11, v10, v7
	v_fmac_f32_e32 v11, v9, v8
	s_nop 1
	v_add_f32_dpp v11, v11, v11 row_ror:8 row_mask:0xf bank_mask:0xf bound_ctrl:1
	s_nop 1
	v_add_f32_dpp v11, v11, v11 row_ror:4 row_mask:0xf bank_mask:0xf bound_ctrl:1
	s_nop 1
	v_add_f32_dpp v11, v11, v11 row_ror:2 row_mask:0xf bank_mask:0xf bound_ctrl:1
	s_nop 1
	v_add_f32_dpp v11, v11, v11 row_ror:1 row_mask:0xf bank_mask:0xf bound_ctrl:1
	ds_bpermute_b32 v12, v3, v11
	s_waitcnt lgkmcnt(0)
	v_add_f32_e32 v11, v11, v12
	v_mov_b32_e32 v12, v11
	s_nop 1
	v_permlane32_swap_b32_e32 v11, v12
	v_add_f32_e32 v11, v11, v12
	v_mul_f32_e32 v11, 0x3c000000, v11
	v_fma_f32 v7, v10, v7, -v11
	v_fma_f32 v8, v9, v8, -v11
	v_mul_f32_e32 v9, v7, v7
	v_fmac_f32_e32 v9, v8, v8
	s_nop 1
	v_add_f32_dpp v9, v9, v9 row_ror:8 row_mask:0xf bank_mask:0xf bound_ctrl:1
	s_nop 1
	v_add_f32_dpp v9, v9, v9 row_ror:4 row_mask:0xf bank_mask:0xf bound_ctrl:1
	s_nop 1
	v_add_f32_dpp v9, v9, v9 row_ror:2 row_mask:0xf bank_mask:0xf bound_ctrl:1
	s_nop 1
	v_add_f32_dpp v9, v9, v9 row_ror:1 row_mask:0xf bank_mask:0xf bound_ctrl:1
	ds_bpermute_b32 v10, v3, v9
	s_waitcnt lgkmcnt(0)
	v_add_f32_e32 v9, v9, v10
	v_mov_b32_e32 v10, v9
	s_nop 1
	v_permlane32_swap_b32_e32 v9, v10
	v_add_f32_e32 v9, v9, v10
	v_fmamk_f32 v9, v9, 0x3c000000, v177
	v_cmp_gt_f32_e32 vcc, s16, v9
	v_mul_f32_e32 v10, 0x4b800000, v9
	s_nop 0
	v_cndmask_b32_e32 v9, v9, v10, vcc
	v_rsq_f32_e32 v9, v9
	s_nop 0
	v_mul_f32_e32 v10, 0x45800000, v9
	v_cndmask_b32_e32 v9, v9, v10, vcc
	v_mul_f32_e32 v8, v8, v9
	v_bfe_u32 v10, v8, 16, 1
	v_add3_u32 v8, v8, v10, s83
	v_add_u32_e32 v10, s5, v6
	v_mul_f32_e32 v7, v7, v9
	ds_write_b16_d16_hi v10, v8
	v_bfe_u32 v8, v7, 16, 1
	s_add_i32 s5, s5, 2
	v_add3_u32 v7, v7, v8, s83
	ds_write_b16_d16_hi v10, v7 offset:272
	s_waitcnt vmcnt(1)
	v_lshlrev_b32_e32 v8, 16, v50
	v_mul_f32_e32 v9, 0.5, v8
	v_mul_f32_e32 v8, 0x3f3504f3, v8
	v_fma_f32 v10, |v8|, s2, 1.0
	v_rcp_f32_e32 v10, v10
	v_and_b32_e32 v7, 0xffff0000, v50
	v_fmamk_f32 v11, v10, 0x3f87dc22, v176
	v_fmaak_f32 v11, v10, v11, 0x3fb5f0e3
	v_fmaak_f32 v11, v10, v11, 0xbe91a98e
	v_fmaak_f32 v11, v10, v11, 0x3e827906
	v_mul_f32_e32 v10, v10, v11
	v_mul_f32_e64 v11, |v8|, s3
	v_mul_f32_e64 v11, |v8|, v11
	v_exp_f32_e32 v11, v11
	s_nop 0
	v_fma_f32 v10, -v11, v10, 1.0
	v_bfi_b32 v8, s13, v10, v8
	v_mul_f32_e32 v10, 0.5, v7
	v_mul_f32_e32 v7, 0x3f3504f3, v7
	v_fma_f32 v11, |v7|, s2, 1.0
	v_rcp_f32_e32 v11, v11
	v_add_f32_e32 v8, 1.0, v8
	v_fmamk_f32 v12, v11, 0x3f87dc22, v176
	v_fmaak_f32 v12, v11, v12, 0x3fb5f0e3
	v_fmaak_f32 v12, v11, v12, 0xbe91a98e
	v_fmaak_f32 v12, v11, v12, 0x3e827906
	v_mul_f32_e32 v11, v11, v12
	v_mul_f32_e64 v12, |v7|, s3
	v_mul_f32_e64 v12, |v7|, v12
	v_exp_f32_e32 v12, v12
	s_nop 0
	v_fma_f32 v11, -v12, v11, 1.0
	v_bfi_b32 v7, s13, v11, v7
	v_add_f32_e32 v7, 1.0, v7
	v_mul_f32_e32 v11, v10, v7
	v_fmac_f32_e32 v11, v9, v8
	s_nop 1
	v_add_f32_dpp v11, v11, v11 row_ror:8 row_mask:0xf bank_mask:0xf bound_ctrl:1
	s_nop 1
	v_add_f32_dpp v11, v11, v11 row_ror:4 row_mask:0xf bank_mask:0xf bound_ctrl:1
	s_nop 1
	v_add_f32_dpp v11, v11, v11 row_ror:2 row_mask:0xf bank_mask:0xf bound_ctrl:1
	s_nop 1
	v_add_f32_dpp v11, v11, v11 row_ror:1 row_mask:0xf bank_mask:0xf bound_ctrl:1
	ds_bpermute_b32 v12, v3, v11
	s_waitcnt lgkmcnt(0)
	v_add_f32_e32 v11, v11, v12
	v_mov_b32_e32 v12, v11
	s_nop 1
	v_permlane32_swap_b32_e32 v11, v12
	v_add_f32_e32 v11, v11, v12
	v_mul_f32_e32 v11, 0x3c000000, v11
	v_fma_f32 v7, v10, v7, -v11
	v_fma_f32 v8, v9, v8, -v11
	v_mul_f32_e32 v9, v7, v7
	v_fmac_f32_e32 v9, v8, v8
	s_nop 1
	v_add_f32_dpp v9, v9, v9 row_ror:8 row_mask:0xf bank_mask:0xf bound_ctrl:1
	s_nop 1
	v_add_f32_dpp v9, v9, v9 row_ror:4 row_mask:0xf bank_mask:0xf bound_ctrl:1
	s_nop 1
	v_add_f32_dpp v9, v9, v9 row_ror:2 row_mask:0xf bank_mask:0xf bound_ctrl:1
	s_nop 1
	v_add_f32_dpp v9, v9, v9 row_ror:1 row_mask:0xf bank_mask:0xf bound_ctrl:1
	ds_bpermute_b32 v10, v3, v9
	s_waitcnt lgkmcnt(0)
; DI bf16 f2bf(float f) { unsigned u = __float_as_uint(f); u += 0x7fffu + ((u >> 16) & 1u); return (bf16)(u >> 16); }
; DI float gelu(float x) { return 0.5f * x * (1.f + erf_as(x * 0.70710678118654752f)); }
;   DI bf16* P() const { return (bf16*)(p.ws + WS_P); }
;   DI bf16* VGT() const { return (bf16*)(p.ws + WS_VGT); }
; DI void vgt_tile(const Ctx& c, int ti, bf16* lds) {
;     ...
;   for (int rr = 0; rr < 32; ++rr) {
;     const int t = wave * 32 + rr;
;     const unsigned u = *(const unsigned*)(c.P() + (size_t)(row0 + t) * LDP + C_V + g * 128 + 2 * lane);
;     const float a = gelu(__uint_as_float(u << 16)), b = gelu(__uint_as_float(u & 0xffff0000u));
;     const float mean = wave_sum(a + b) * (1.f / 128.f);
;     const float da = a - mean, db = b - mean;
;     const float rstd = rsqrtf(wave_sum(da * da + db * db) * (1.f / 128.f) + LN_EPS);
;     lds[(2 * lane) * LDT + t] = f2bf(da * rstd);
;     lds[(2 * lane + 1) * LDT + t] = f2bf(db * rstd);
;   }
;   __syncthreads();
;   {
;     const int d = tid >> 1, half = tid & 1;
;     bf16* dst = c.VGT() + ((size_t)ti * 128 + d) * 128 + half * 64;
;     const bf16* src = lds + d * LDT + half * 64;
; #pragma unroll
;     for (int i = 0; i < 8; ++i) *(u32x4*)(dst + i * 8) = *(const u32x4*)(src + i * 8);
;   }
;   __syncthreads();
	v_add_f32_e32 v9, v9, v10
	v_mov_b32_e32 v10, v9
	s_nop 1
	v_permlane32_swap_b32_e32 v9, v10
	v_add_f32_e32 v9, v9, v10
	v_fmamk_f32 v9, v9, 0x3c000000, v177
	v_cmp_gt_f32_e32 vcc, s16, v9
	v_mul_f32_e32 v10, 0x4b800000, v9
	s_nop 0
	v_cndmask_b32_e32 v9, v9, v10, vcc
	v_rsq_f32_e32 v9, v9
	s_nop 0
	v_mul_f32_e32 v10, 0x45800000, v9
	v_cndmask_b32_e32 v9, v9, v10, vcc
	v_mul_f32_e32 v8, v8, v9
	v_bfe_u32 v10, v8, 16, 1
	v_add3_u32 v8, v8, v10, s83
	v_add_u32_e32 v10, s5, v6
	v_mul_f32_e32 v7, v7, v9
	ds_write_b16_d16_hi v10, v8
	v_bfe_u32 v8, v7, 16, 1
	s_add_i32 s5, s5, 2
	v_add3_u32 v7, v7, v8, s83
	ds_write_b16_d16_hi v10, v7 offset:272
	s_waitcnt vmcnt(0)
	v_lshlrev_b32_e32 v8, 16, v51
	v_mul_f32_e32 v9, 0.5, v8
	v_mul_f32_e32 v8, 0x3f3504f3, v8
	v_fma_f32 v10, |v8|, s2, 1.0
	v_rcp_f32_e32 v10, v10
	v_and_b32_e32 v7, 0xffff0000, v51
	v_fmamk_f32 v11, v10, 0x3f87dc22, v176
	v_fmaak_f32 v11, v10, v11, 0x3fb5f0e3
	v_fmaak_f32 v11, v10, v11, 0xbe91a98e
	v_fmaak_f32 v11, v10, v11, 0x3e827906
	v_mul_f32_e32 v10, v10, v11
	v_mul_f32_e64 v11, |v8|, s3
	v_mul_f32_e64 v11, |v8|, v11
	v_exp_f32_e32 v11, v11
	s_nop 0
	v_fma_f32 v10, -v11, v10, 1.0
	v_bfi_b32 v8, s13, v10, v8
	v_mul_f32_e32 v10, 0.5, v7
	v_mul_f32_e32 v7, 0x3f3504f3, v7
	v_fma_f32 v11, |v7|, s2, 1.0
	v_rcp_f32_e32 v11, v11
	v_add_f32_e32 v8, 1.0, v8
	v_fmamk_f32 v12, v11, 0x3f87dc22, v176
	v_fmaak_f32 v12, v11, v12, 0x3fb5f0e3
	v_fmaak_f32 v12, v11, v12, 0xbe91a98e
	v_fmaak_f32 v12, v11, v12, 0x3e827906
	v_mul_f32_e32 v11, v11, v12
	v_mul_f32_e64 v12, |v7|, s3
	v_mul_f32_e64 v12, |v7|, v12
	v_exp_f32_e32 v12, v12
	s_nop 0
	v_fma_f32 v11, -v12, v11, 1.0
	v_bfi_b32 v7, s13, v11, v7
	v_add_f32_e32 v7, 1.0, v7
	v_mul_f32_e32 v11, v10, v7
	v_fmac_f32_e32 v11, v9, v8
	s_nop 1
	v_add_f32_dpp v11, v11, v11 row_ror:8 row_mask:0xf bank_mask:0xf bound_ctrl:1
	s_nop 1
	v_add_f32_dpp v11, v11, v11 row_ror:4 row_mask:0xf bank_mask:0xf bound_ctrl:1
	s_nop 1
	v_add_f32_dpp v11, v11, v11 row_ror:2 row_mask:0xf bank_mask:0xf bound_ctrl:1
	s_nop 1
	v_add_f32_dpp v11, v11, v11 row_ror:1 row_mask:0xf bank_mask:0xf bound_ctrl:1
	ds_bpermute_b32 v12, v3, v11
	s_waitcnt lgkmcnt(0)
	v_add_f32_e32 v11, v11, v12
	v_mov_b32_e32 v12, v11
	s_nop 1
	v_permlane32_swap_b32_e32 v11, v12
	v_add_f32_e32 v11, v11, v12
	v_mul_f32_e32 v11, 0x3c000000, v11
	v_fma_f32 v7, v10, v7, -v11
	v_fma_f32 v8, v9, v8, -v11
	v_mul_f32_e32 v9, v7, v7
	v_fmac_f32_e32 v9, v8, v8
	s_nop 1
	v_add_f32_dpp v9, v9, v9 row_ror:8 row_mask:0xf bank_mask:0xf bound_ctrl:1
	s_nop 1
	v_add_f32_dpp v9, v9, v9 row_ror:4 row_mask:0xf bank_mask:0xf bound_ctrl:1
	s_nop 1
	v_add_f32_dpp v9, v9, v9 row_ror:2 row_mask:0xf bank_mask:0xf bound_ctrl:1
	s_nop 1
	v_add_f32_dpp v9, v9, v9 row_ror:1 row_mask:0xf bank_mask:0xf bound_ctrl:1
	ds_bpermute_b32 v10, v3, v9
	s_waitcnt lgkmcnt(0)
	v_add_f32_e32 v9, v9, v10
	v_mov_b32_e32 v10, v9
	s_nop 1
	v_permlane32_swap_b32_e32 v9, v10
	v_add_f32_e32 v9, v9, v10
	v_fmamk_f32 v9, v9, 0x3c000000, v177
	v_cmp_gt_f32_e32 vcc, s16, v9
	v_mul_f32_e32 v10, 0x4b800000, v9
	s_nop 0
	v_cndmask_b32_e32 v9, v9, v10, vcc
	v_rsq_f32_e32 v9, v9
	s_nop 0
	v_mul_f32_e32 v10, 0x45800000, v9
	v_cndmask_b32_e32 v9, v9, v10, vcc
	v_mul_f32_e32 v8, v8, v9
	v_bfe_u32 v10, v8, 16, 1
	v_add3_u32 v8, v8, v10, s83
	v_add_u32_e32 v10, s5, v6
	v_mul_f32_e32 v7, v7, v9
	ds_write_b16_d16_hi v10, v8
	v_bfe_u32 v8, v7, 16, 1
	s_add_i32 s5, s5, 2
	v_add3_u32 v7, v7, v8, s83
	ds_write_b16_d16_hi v10, v7 offset:272
	s_ashr_i32 s5, s4, 31
	s_lshl_b64 s[6:7], s[4:5], 15
	v_readlane_b32 s2, v253, 13
	v_ashrrev_i32_e32 v3, 31, v2
	s_add_u32 s6, s2, s6
	v_readlane_b32 s2, v253, 14
	v_lshlrev_b32_e32 v0, 7, v0
	s_addc_u32 s7, s2, s7
	v_lshlrev_b64 v[4:5], 8, v[2:3]
	v_and_b32_e32 v0, 0x80, v0
	v_lshl_add_u64 v[4:5], s[6:7], 0, v[4:5]
	v_mad_u64_u32 v[20:21], s[6:7], v2, s79, v[0:1]
	s_waitcnt lgkmcnt(0)
	s_barrier
	v_lshl_add_u64 v[18:19], v[4:5], 0, v[0:1]
	ds_read_b128 v[2:5], v20
	ds_read_b128 v[6:9], v20 offset:16
	ds_read_b128 v[10:13], v20 offset:32
	ds_read_b128 v[14:17], v20 offset:48
	s_waitcnt lgkmcnt(3)
	global_store_dwordx4 v[18:19], v[2:5], off
	s_waitcnt lgkmcnt(2)
	global_store_dwordx4 v[18:19], v[6:9], off offset:16
	s_waitcnt lgkmcnt(1)
	global_store_dwordx4 v[18:19], v[10:13], off offset:32
	s_waitcnt lgkmcnt(0)
	global_store_dwordx4 v[18:19], v[14:17], off offset:48
	ds_read_b128 v[2:5], v20 offset:64
	s_waitcnt lgkmcnt(0)
	global_store_dwordx4 v[18:19], v[2:5], off offset:64
	ds_read_b128 v[2:5], v20 offset:80
	s_waitcnt lgkmcnt(0)
	global_store_dwordx4 v[18:19], v[2:5], off offset:80
	ds_read_b128 v[2:5], v20 offset:96
	s_waitcnt lgkmcnt(0)
	global_store_dwordx4 v[18:19], v[2:5], off offset:96
	ds_read_b128 v[2:5], v20 offset:112
	s_waitcnt lgkmcnt(0)
	global_store_dwordx4 v[18:19], v[2:5], off offset:112
	s_barrier
	s_branch .LBB0_312

; DI int otid() { int t = threadIdx.x; asm volatile("" : "+v"(t)); return t; }
; DI float bf2f(bf16 v) { return __uint_as_float(((unsigned)v) << 16); }
; DI bf16 f2bf(float f) { unsigned u = __float_as_uint(f); u += 0x7fffu + ((u >> 16) & 1u); return (bf16)(u >> 16); }
;   DI bf16* G() const { return (bf16*)(p.ws + WS_G); }
;   DI float* DEC() const { return (float*)(p.ws + WS_DEC); }
; DI void gla_g2(const Ctx& c) {
;   const int gt = blockIdx.x * NT + otid(), gs = gridDim.x * NT;
;   for (int i = gt; i < 16 * 8192; i += gs) {
;     const int e = i & 8191, kk = e & 63, q = i >> 13, h = q & 3, bd = q >> 2, dir = bd & 1;
;     float st = 0.f;
;     for (int c0 = 0; c0 < 132; c0 += 12) {
;       float dsv[12], dec[12]; bf16* pd[12];
; #pragma unroll
;       for (int j = 0; j < 12; ++j) {
;         const int ci = c0 + j;
;         const int cm = dir ? (131 - ci) : (ci < 4 ? 128 + ci : ci - 4);
;         const size_t sidx = (size_t)(bd * 132 + cm) * 4 + h;
;         pd[j] = c.G() + sidx * 8192 + e;
;         dsv[j] = bf2f(*pd[j]); dec[j] = c.DEC()[sidx * 64 + kk];
;       }
; #pragma unroll
;       for (int j = 0; j < 12; ++j) { *pd[j] = f2bf(st); st = dec[j] * st + dsv[j]; }
;     }
;   }
; }
.Lg2_entry:
	v_readlane_b32 s2, v252, 32
	v_lshrrev_b32_e32 v2, 6, v172
	s_nop 0
	v_readfirstlane_b32 s3, v2
	s_lshr_b32 s2, s2, 6
	s_add_i32 s2, s2, s3
	s_lshr_b32 s3, s2, 7
	s_and_b32 s7, s3, 3
	s_lshr_b32 s10, s3, 2
	s_and_b32 s6, s10, 1
	s_mul_i32 s10, s10, 0x210
	s_add_i32 s10, s10, s7
	s_and_b32 s2, s2, 127
	s_lshl_b32 s2, s2, 6
	v_mbcnt_lo_u32_b32 v3, -1, 0
	v_mbcnt_hi_u32_b32 v3, -1, v3
	v_add_lshl_u32 v2, v3, s2, 1
	v_lshlrev_b32_e32 v3, 2, v3
	v_readlane_b32 s24, v253, 19
	v_readlane_b32 s25, v253, 20
	v_readlane_b32 s26, v253, 17
	v_readlane_b32 s27, v253, 18
	s_lshl_b32 s12, s10, 14
	s_add_u32 s24, s24, s12
	s_addc_u32 s25, s25, 0
	s_lshl_b32 s12, s10, 8
	s_add_u32 s26, s26, s12
	s_addc_u32 s27, s27, 0
	v_mov_b32_e32 v5, 0
	s_mov_b32 s12, 0x800000
	s_cmp_eq_u32 s6, 1
	s_cselect_b32 s12, 0x830000, s12
	s_add_u32 s2, s24, s12
	s_addc_u32 s3, s25, 0
	s_lshr_b32 s12, s12, 6
	s_add_u32 s4, s26, s12
	s_addc_u32 s5, s27, 0
	global_load_ushort v20, v2, s[2:3]
	global_load_dword v44, v3, s[4:5]
	s_mov_b32 s12, 0x810000
	s_cmp_eq_u32 s6, 1
	s_cselect_b32 s12, 0x820000, s12
	s_add_u32 s2, s24, s12
	s_addc_u32 s3, s25, 0
	s_lshr_b32 s12, s12, 6
	s_add_u32 s4, s26, s12
	s_addc_u32 s5, s27, 0
	global_load_ushort v21, v2, s[2:3]
	global_load_dword v45, v3, s[4:5]
	s_mov_b32 s12, 0x820000
	s_cmp_eq_u32 s6, 1
	s_cselect_b32 s12, 0x810000, s12
	s_add_u32 s2, s24, s12
	s_addc_u32 s3, s25, 0
	s_lshr_b32 s12, s12, 6
	s_add_u32 s4, s26, s12
	s_addc_u32 s5, s27, 0
	global_load_ushort v22, v2, s[2:3]
	global_load_dword v46, v3, s[4:5]
	s_mov_b32 s12, 0x830000
	s_cmp_eq_u32 s6, 1
	s_cselect_b32 s12, 0x800000, s12
	s_add_u32 s2, s24, s12
	s_addc_u32 s3, s25, 0
	s_lshr_b32 s12, s12, 6
	s_add_u32 s4, s26, s12
	s_addc_u32 s5, s27, 0
	global_load_ushort v23, v2, s[2:3]
	global_load_dword v47, v3, s[4:5]
	s_mov_b32 s12, 0x0
	s_cmp_eq_u32 s6, 1
	s_cselect_b32 s12, 0x7f0000, s12
	s_add_u32 s2, s24, s12
	s_addc_u32 s3, s25, 0
	s_lshr_b32 s12, s12, 6
	s_add_u32 s4, s26, s12
	s_addc_u32 s5, s27, 0
	global_load_ushort v24, v2, s[2:3]
	global_load_dword v48, v3, s[4:5]
	s_mov_b32 s12, 0x10000
	s_cmp_eq_u32 s6, 1
	s_cselect_b32 s12, 0x7e0000, s12
	s_add_u32 s2, s24, s12
	s_addc_u32 s3, s25, 0
	s_lshr_b32 s12, s12, 6
	s_add_u32 s4, s26, s12
	s_addc_u32 s5, s27, 0
	global_load_ushort v25, v2, s[2:3]
	global_load_dword v49, v3, s[4:5]
	s_mov_b32 s12, 0x20000
	s_cmp_eq_u32 s6, 1
	s_cselect_b32 s12, 0x7d0000, s12
	s_add_u32 s2, s24, s12
	s_addc_u32 s3, s25, 0
	s_lshr_b32 s12, s12, 6
	s_add_u32 s4, s26, s12
	s_addc_u32 s5, s27, 0
	global_load_ushort v26, v2, s[2:3]
	global_load_dword v50, v3, s[4:5]
	s_mov_b32 s12, 0x30000
	s_cmp_eq_u32 s6, 1
	s_cselect_b32 s12, 0x7c0000, s12
	s_add_u32 s2, s24, s12
	s_addc_u32 s3, s25, 0
	s_lshr_b32 s12, s12, 6
	s_add_u32 s4, s26, s12
	s_addc_u32 s5, s27, 0
	global_load_ushort v27, v2, s[2:3]
	global_load_dword v51, v3, s[4:5]
	s_mov_b32 s12, 0x40000
	s_cmp_eq_u32 s6, 1
	s_cselect_b32 s12, 0x7b0000, s12
	s_add_u32 s2, s24, s12
	s_addc_u32 s3, s25, 0
	s_lshr_b32 s12, s12, 6
	s_add_u32 s4, s26, s12
	s_addc_u32 s5, s27, 0
	global_load_ushort v28, v2, s[2:3]
	global_load_dword v52, v3, s[4:5]
	s_mov_b32 s12, 0x50000
	s_cmp_eq_u32 s6, 1
	s_cselect_b32 s12, 0x7a0000, s12
	s_add_u32 s2, s24, s12
	s_addc_u32 s3, s25, 0
	s_lshr_b32 s12, s12, 6
	s_add_u32 s4, s26, s12
	s_addc_u32 s5, s27, 0
	global_load_ushort v29, v2, s[2:3]
	global_load_dword v53, v3, s[4:5]
	s_mov_b32 s12, 0x60000
	s_cmp_eq_u32 s6, 1
	s_cselect_b32 s12, 0x790000, s12
	s_add_u32 s2, s24, s12
	s_addc_u32 s3, s25, 0
	s_lshr_b32 s12, s12, 6
	s_add_u32 s4, s26, s12
	s_addc_u32 s5, s27, 0
	global_load_ushort v30, v2, s[2:3]
	global_load_dword v54, v3, s[4:5]
	s_mov_b32 s12, 0x70000
	s_cmp_eq_u32 s6, 1
	s_cselect_b32 s12, 0x780000, s12
	s_add_u32 s2, s24, s12
	s_addc_u32 s3, s25, 0
	s_lshr_b32 s12, s12, 6
	s_add_u32 s4, s26, s12
	s_addc_u32 s5, s27, 0
	global_load_ushort v31, v2, s[2:3]
	global_load_dword v55, v3, s[4:5]
	s_mov_b32 s12, 0x80000
	s_cmp_eq_u32 s6, 1
	s_cselect_b32 s12, 0x770000, s12
	s_add_u32 s2, s24, s12
	s_addc_u32 s3, s25, 0
	s_lshr_b32 s12, s12, 6
	s_add_u32 s4, s26, s12
	s_addc_u32 s5, s27, 0
	global_load_ushort v32, v2, s[2:3]
	global_load_dword v56, v3, s[4:5]
	s_mov_b32 s12, 0x90000
	s_cmp_eq_u32 s6, 1
	s_cselect_b32 s12, 0x760000, s12
	s_add_u32 s2, s24, s12
	s_addc_u32 s3, s25, 0
	s_lshr_b32 s12, s12, 6
	s_add_u32 s4, s26, s12
	s_addc_u32 s5, s27, 0
	global_load_ushort v33, v2, s[2:3]
	global_load_dword v57, v3, s[4:5]
	s_mov_b32 s12, 0xa0000
	s_cmp_eq_u32 s6, 1
	s_cselect_b32 s12, 0x750000, s12
	s_add_u32 s2, s24, s12
	s_addc_u32 s3, s25, 0
	s_lshr_b32 s12, s12, 6
	s_add_u32 s4, s26, s12
	s_addc_u32 s5, s27, 0
	global_load_ushort v34, v2, s[2:3]
	global_load_dword v58, v3, s[4:5]
	s_mov_b32 s12, 0xb0000
	s_cmp_eq_u32 s6, 1
	s_cselect_b32 s12, 0x740000, s12
	s_add_u32 s2, s24, s12
	s_addc_u32 s3, s25, 0
	s_lshr_b32 s12, s12, 6
	s_add_u32 s4, s26, s12
	s_addc_u32 s5, s27, 0
	global_load_ushort v35, v2, s[2:3]
	global_load_dword v59, v3, s[4:5]
	s_mov_b32 s12, 0xc0000
	s_cmp_eq_u32 s6, 1
	s_cselect_b32 s12, 0x730000, s12
	s_add_u32 s2, s24, s12
	s_addc_u32 s3, s25, 0
	s_lshr_b32 s12, s12, 6
	s_add_u32 s4, s26, s12
	s_addc_u32 s5, s27, 0
	global_load_ushort v36, v2, s[2:3]
	global_load_dword v60, v3, s[4:5]
	s_mov_b32 s12, 0xd0000
	s_cmp_eq_u32 s6, 1
	s_cselect_b32 s12, 0x720000, s12
	s_add_u32 s2, s24, s12
	s_addc_u32 s3, s25, 0
	s_lshr_b32 s12, s12, 6
	s_add_u32 s4, s26, s12
	s_addc_u32 s5, s27, 0
	global_load_ushort v37, v2, s[2:3]
	global_load_dword v61, v3, s[4:5]
	s_mov_b32 s12, 0xe0000
	s_cmp_eq_u32 s6, 1
	s_cselect_b32 s12, 0x710000, s12
	s_add_u32 s2, s24, s12
	s_addc_u32 s3, s25, 0
	s_lshr_b32 s12, s12, 6
	s_add_u32 s4, s26, s12
	s_addc_u32 s5, s27, 0
	global_load_ushort v38, v2, s[2:3]
	global_load_dword v62, v3, s[4:5]
	s_mov_b32 s12, 0xf0000
	s_cmp_eq_u32 s6, 1
	s_cselect_b32 s12, 0x700000, s12
	s_add_u32 s2, s24, s12
	s_addc_u32 s3, s25, 0
	s_lshr_b32 s12, s12, 6
	s_add_u32 s4, s26, s12
	s_addc_u32 s5, s27, 0
	global_load_ushort v39, v2, s[2:3]
	global_load_dword v63, v3, s[4:5]
	s_mov_b32 s12, 0x100000
	s_cmp_eq_u32 s6, 1
	s_cselect_b32 s12, 0x6f0000, s12
	s_add_u32 s2, s24, s12
	s_addc_u32 s3, s25, 0
	s_lshr_b32 s12, s12, 6
	s_add_u32 s4, s26, s12
	s_addc_u32 s5, s27, 0
	global_load_ushort v40, v2, s[2:3]
	global_load_dword v64, v3, s[4:5]
	s_waitcnt vmcnt(40)
; DI int otid() { int t = threadIdx.x; asm volatile("" : "+v"(t)); return t; }
; DI float bf2f(bf16 v) { return __uint_as_float(((unsigned)v) << 16); }
; DI bf16 f2bf(float f) { unsigned u = __float_as_uint(f); u += 0x7fffu + ((u >> 16) & 1u); return (bf16)(u >> 16); }
;   DI bf16* G() const { return (bf16*)(p.ws + WS_G); }
;   DI float* DEC() const { return (float*)(p.ws + WS_DEC); }
; DI void gla_g2(const Ctx& c) {
;   const int gt = blockIdx.x * NT + otid(), gs = gridDim.x * NT;
;   for (int i = gt; i < 16 * 8192; i += gs) {
;     const int e = i & 8191, kk = e & 63, q = i >> 13, h = q & 3, bd = q >> 2, dir = bd & 1;
;     float st = 0.f;
;     for (int c0 = 0; c0 < 132; c0 += 12) {
;       float dsv[12], dec[12]; bf16* pd[12];
; #pragma unroll
;       for (int j = 0; j < 12; ++j) {
;         const int ci = c0 + j;
;         const int cm = dir ? (131 - ci) : (ci < 4 ? 128 + ci : ci - 4);
;         const size_t sidx = (size_t)(bd * 132 + cm) * 4 + h;
;         pd[j] = c.G() + sidx * 8192 + e;
;         dsv[j] = bf2f(*pd[j]); dec[j] = c.DEC()[sidx * 64 + kk];
;       }
; #pragma unroll
;       for (int j = 0; j < 12; ++j) { *pd[j] = f2bf(st); st = dec[j] * st + dsv[j]; }
;     }
;   }
; }
	s_mov_b32 s12, 0x800000
	s_cmp_eq_u32 s6, 1
	s_cselect_b32 s12, 0x830000, s12
	s_add_u32 s2, s24, s12
	s_addc_u32 s3, s25, 0
	v_cvt_pk_bf16_f32 v6, v5, v5
	v_lshlrev_b32_e32 v20, 16, v20
	global_store_short v2, v6, s[2:3]
	v_fmac_f32_e32 v20, v44, v5
	v_mov_b32_e32 v5, v20
	s_mov_b32 s12, 0x110000
	s_cmp_eq_u32 s6, 1
	s_cselect_b32 s12, 0x6e0000, s12
	s_add_u32 s2, s24, s12
	s_addc_u32 s3, s25, 0
	s_lshr_b32 s12, s12, 6
	s_add_u32 s4, s26, s12
	s_addc_u32 s5, s27, 0
	global_load_ushort v41, v2, s[2:3]
	global_load_dword v65, v3, s[4:5]
	s_waitcnt vmcnt(41)
	s_mov_b32 s12, 0x810000
	s_cmp_eq_u32 s6, 1
	s_cselect_b32 s12, 0x820000, s12
	s_add_u32 s2, s24, s12
	s_addc_u32 s3, s25, 0
	v_cvt_pk_bf16_f32 v6, v5, v5
	v_lshlrev_b32_e32 v21, 16, v21
	global_store_short v2, v6, s[2:3]
	v_fmac_f32_e32 v21, v45, v5
	v_mov_b32_e32 v5, v21
	s_mov_b32 s12, 0x120000
	s_cmp_eq_u32 s6, 1
	s_cselect_b32 s12, 0x6d0000, s12
	s_add_u32 s2, s24, s12
	s_addc_u32 s3, s25, 0
	s_lshr_b32 s12, s12, 6
	s_add_u32 s4, s26, s12
	s_addc_u32 s5, s27, 0
	global_load_ushort v42, v2, s[2:3]
	global_load_dword v66, v3, s[4:5]
	s_waitcnt vmcnt(42)
	s_mov_b32 s12, 0x820000
	s_cmp_eq_u32 s6, 1
	s_cselect_b32 s12, 0x810000, s12
	s_add_u32 s2, s24, s12
	s_addc_u32 s3, s25, 0
	v_cvt_pk_bf16_f32 v6, v5, v5
	v_lshlrev_b32_e32 v22, 16, v22
	global_store_short v2, v6, s[2:3]
	v_fmac_f32_e32 v22, v46, v5
	v_mov_b32_e32 v5, v22
	s_mov_b32 s12, 0x130000
	s_cmp_eq_u32 s6, 1
	s_cselect_b32 s12, 0x6c0000, s12
	s_add_u32 s2, s24, s12
	s_addc_u32 s3, s25, 0
	s_lshr_b32 s12, s12, 6
	s_add_u32 s4, s26, s12
	s_addc_u32 s5, s27, 0
	global_load_ushort v43, v2, s[2:3]
	global_load_dword v67, v3, s[4:5]
	s_waitcnt vmcnt(43)
	s_mov_b32 s12, 0x830000
	s_cmp_eq_u32 s6, 1
	s_cselect_b32 s12, 0x800000, s12
	s_add_u32 s2, s24, s12
	s_addc_u32 s3, s25, 0
	v_cvt_pk_bf16_f32 v6, v5, v5
	v_lshlrev_b32_e32 v23, 16, v23
	global_store_short v2, v6, s[2:3]
	v_fmac_f32_e32 v23, v47, v5
	v_mov_b32_e32 v5, v23
	s_mov_b32 s12, 0x140000
	s_cmp_eq_u32 s6, 1
	s_cselect_b32 s12, 0x6b0000, s12
	s_add_u32 s2, s24, s12
	s_addc_u32 s3, s25, 0
	s_lshr_b32 s12, s12, 6
	s_add_u32 s4, s26, s12
	s_addc_u32 s5, s27, 0
	global_load_ushort v20, v2, s[2:3]
	global_load_dword v44, v3, s[4:5]
	s_waitcnt vmcnt(44)
	s_mov_b32 s12, 0x0
	s_cmp_eq_u32 s6, 1
	s_cselect_b32 s12, 0x7f0000, s12
	s_add_u32 s2, s24, s12
	s_addc_u32 s3, s25, 0
	v_cvt_pk_bf16_f32 v6, v5, v5
	v_lshlrev_b32_e32 v24, 16, v24
	global_store_short v2, v6, s[2:3]
	v_fmac_f32_e32 v24, v48, v5
	v_mov_b32_e32 v5, v24
	s_mov_b32 s12, 0x150000
	s_cmp_eq_u32 s6, 1
	s_cselect_b32 s12, 0x6a0000, s12
	s_add_u32 s2, s24, s12
	s_addc_u32 s3, s25, 0
	s_lshr_b32 s12, s12, 6
	s_add_u32 s4, s26, s12
	s_addc_u32 s5, s27, 0
	global_load_ushort v21, v2, s[2:3]
	global_load_dword v45, v3, s[4:5]
	s_waitcnt vmcnt(45)
	s_mov_b32 s12, 0x10000
	s_cmp_eq_u32 s6, 1
	s_cselect_b32 s12, 0x7e0000, s12
	s_add_u32 s2, s24, s12
	s_addc_u32 s3, s25, 0
	v_cvt_pk_bf16_f32 v6, v5, v5
	v_lshlrev_b32_e32 v25, 16, v25
	global_store_short v2, v6, s[2:3]
	v_fmac_f32_e32 v25, v49, v5
	v_mov_b32_e32 v5, v25
	s_mov_b32 s12, 0x160000
	s_cmp_eq_u32 s6, 1
	s_cselect_b32 s12, 0x690000, s12
	s_add_u32 s2, s24, s12
	s_addc_u32 s3, s25, 0
	s_lshr_b32 s12, s12, 6
	s_add_u32 s4, s26, s12
	s_addc_u32 s5, s27, 0
	global_load_ushort v22, v2, s[2:3]
	global_load_dword v46, v3, s[4:5]
	s_waitcnt vmcnt(46)
	s_mov_b32 s12, 0x20000
	s_cmp_eq_u32 s6, 1
	s_cselect_b32 s12, 0x7d0000, s12
	s_add_u32 s2, s24, s12
	s_addc_u32 s3, s25, 0
	v_cvt_pk_bf16_f32 v6, v5, v5
	v_lshlrev_b32_e32 v26, 16, v26
	global_store_short v2, v6, s[2:3]
	v_fmac_f32_e32 v26, v50, v5
	v_mov_b32_e32 v5, v26
	s_mov_b32 s12, 0x170000
	s_cmp_eq_u32 s6, 1
	s_cselect_b32 s12, 0x680000, s12
	s_add_u32 s2, s24, s12
	s_addc_u32 s3, s25, 0
	s_lshr_b32 s12, s12, 6
	s_add_u32 s4, s26, s12
	s_addc_u32 s5, s27, 0
	global_load_ushort v23, v2, s[2:3]
	global_load_dword v47, v3, s[4:5]
	s_waitcnt vmcnt(47)
	s_mov_b32 s12, 0x30000
	s_cmp_eq_u32 s6, 1
	s_cselect_b32 s12, 0x7c0000, s12
	s_add_u32 s2, s24, s12
	s_addc_u32 s3, s25, 0
	v_cvt_pk_bf16_f32 v6, v5, v5
	v_lshlrev_b32_e32 v27, 16, v27
	global_store_short v2, v6, s[2:3]
	v_fmac_f32_e32 v27, v51, v5
	v_mov_b32_e32 v5, v27
	s_mov_b32 s12, 0x180000
	s_cmp_eq_u32 s6, 1
	s_cselect_b32 s12, 0x670000, s12
	s_add_u32 s2, s24, s12
	s_addc_u32 s3, s25, 0
	s_lshr_b32 s12, s12, 6
	s_add_u32 s4, s26, s12
	s_addc_u32 s5, s27, 0
	global_load_ushort v24, v2, s[2:3]
	global_load_dword v48, v3, s[4:5]
	s_waitcnt vmcnt(48)
	s_mov_b32 s12, 0x40000
	s_cmp_eq_u32 s6, 1
	s_cselect_b32 s12, 0x7b0000, s12
	s_add_u32 s2, s24, s12
	s_addc_u32 s3, s25, 0
	v_cvt_pk_bf16_f32 v6, v5, v5
	v_lshlrev_b32_e32 v28, 16, v28
	global_store_short v2, v6, s[2:3]
	v_fmac_f32_e32 v28, v52, v5
	v_mov_b32_e32 v5, v28
	s_mov_b32 s12, 0x190000
	s_cmp_eq_u32 s6, 1
	s_cselect_b32 s12, 0x660000, s12
	s_add_u32 s2, s24, s12
	s_addc_u32 s3, s25, 0
	s_lshr_b32 s12, s12, 6
	s_add_u32 s4, s26, s12
	s_addc_u32 s5, s27, 0
	global_load_ushort v25, v2, s[2:3]
	global_load_dword v49, v3, s[4:5]
	s_waitcnt vmcnt(49)
	s_mov_b32 s12, 0x50000
	s_cmp_eq_u32 s6, 1
	s_cselect_b32 s12, 0x7a0000, s12
	s_add_u32 s2, s24, s12
	s_addc_u32 s3, s25, 0
	v_cvt_pk_bf16_f32 v6, v5, v5
	v_lshlrev_b32_e32 v29, 16, v29
	global_store_short v2, v6, s[2:3]
	v_fmac_f32_e32 v29, v53, v5
	v_mov_b32_e32 v5, v29
	s_mov_b32 s12, 0x1a0000
	s_cmp_eq_u32 s6, 1
	s_cselect_b32 s12, 0x650000, s12
	s_add_u32 s2, s24, s12
	s_addc_u32 s3, s25, 0
	s_lshr_b32 s12, s12, 6
	s_add_u32 s4, s26, s12
	s_addc_u32 s5, s27, 0
	global_load_ushort v26, v2, s[2:3]
	global_load_dword v50, v3, s[4:5]
	s_waitcnt vmcnt(50)
; DI int otid() { int t = threadIdx.x; asm volatile("" : "+v"(t)); return t; }
; DI float bf2f(bf16 v) { return __uint_as_float(((unsigned)v) << 16); }
; DI bf16 f2bf(float f) { unsigned u = __float_as_uint(f); u += 0x7fffu + ((u >> 16) & 1u); return (bf16)(u >> 16); }
;   DI bf16* G() const { return (bf16*)(p.ws + WS_G); }
;   DI float* DEC() const { return (float*)(p.ws + WS_DEC); }
; DI void gla_g2(const Ctx& c) {
;   const int gt = blockIdx.x * NT + otid(), gs = gridDim.x * NT;
;   for (int i = gt; i < 16 * 8192; i += gs) {
;     const int e = i & 8191, kk = e & 63, q = i >> 13, h = q & 3, bd = q >> 2, dir = bd & 1;
;     float st = 0.f;
;     for (int c0 = 0; c0 < 132; c0 += 12) {
;       float dsv[12], dec[12]; bf16* pd[12];
; #pragma unroll
;       for (int j = 0; j < 12; ++j) {
;         const int ci = c0 + j;
;         const int cm = dir ? (131 - ci) : (ci < 4 ? 128 + ci : ci - 4);
;         const size_t sidx = (size_t)(bd * 132 + cm) * 4 + h;
;         pd[j] = c.G() + sidx * 8192 + e;
;         dsv[j] = bf2f(*pd[j]); dec[j] = c.DEC()[sidx * 64 + kk];
;       }
; #pragma unroll
;       for (int j = 0; j < 12; ++j) { *pd[j] = f2bf(st); st = dec[j] * st + dsv[j]; }
;     }
;   }
; }
	s_mov_b32 s12, 0x60000
	s_cmp_eq_u32 s6, 1
	s_cselect_b32 s12, 0x790000, s12
	s_add_u32 s2, s24, s12
	s_addc_u32 s3, s25, 0
	v_cvt_pk_bf16_f32 v6, v5, v5
	v_lshlrev_b32_e32 v30, 16, v30
	global_store_short v2, v6, s[2:3]
	v_fmac_f32_e32 v30, v54, v5
	v_mov_b32_e32 v5, v30
	s_mov_b32 s12, 0x1b0000
	s_cmp_eq_u32 s6, 1
	s_cselect_b32 s12, 0x640000, s12
	s_add_u32 s2, s24, s12
	s_addc_u32 s3, s25, 0
	s_lshr_b32 s12, s12, 6
	s_add_u32 s4, s26, s12
	s_addc_u32 s5, s27, 0
	global_load_ushort v27, v2, s[2:3]
	global_load_dword v51, v3, s[4:5]
	s_waitcnt vmcnt(51)
	s_mov_b32 s12, 0x70000
	s_cmp_eq_u32 s6, 1
	s_cselect_b32 s12, 0x780000, s12
	s_add_u32 s2, s24, s12
	s_addc_u32 s3, s25, 0
	v_cvt_pk_bf16_f32 v6, v5, v5
	v_lshlrev_b32_e32 v31, 16, v31
	global_store_short v2, v6, s[2:3]
	v_fmac_f32_e32 v31, v55, v5
	v_mov_b32_e32 v5, v31
	s_mov_b32 s12, 0x1c0000
	s_cmp_eq_u32 s6, 1
	s_cselect_b32 s12, 0x630000, s12
	s_add_u32 s2, s24, s12
	s_addc_u32 s3, s25, 0
	s_lshr_b32 s12, s12, 6
	s_add_u32 s4, s26, s12
	s_addc_u32 s5, s27, 0
	global_load_ushort v28, v2, s[2:3]
	global_load_dword v52, v3, s[4:5]
	s_waitcnt vmcnt(52)
	s_mov_b32 s12, 0x80000
	s_cmp_eq_u32 s6, 1
	s_cselect_b32 s12, 0x770000, s12
	s_add_u32 s2, s24, s12
	s_addc_u32 s3, s25, 0
	v_cvt_pk_bf16_f32 v6, v5, v5
	v_lshlrev_b32_e32 v32, 16, v32
	global_store_short v2, v6, s[2:3]
	v_fmac_f32_e32 v32, v56, v5
	v_mov_b32_e32 v5, v32
	s_mov_b32 s12, 0x1d0000
	s_cmp_eq_u32 s6, 1
	s_cselect_b32 s12, 0x620000, s12
	s_add_u32 s2, s24, s12
	s_addc_u32 s3, s25, 0
	s_lshr_b32 s12, s12, 6
	s_add_u32 s4, s26, s12
	s_addc_u32 s5, s27, 0
	global_load_ushort v29, v2, s[2:3]
	global_load_dword v53, v3, s[4:5]
	s_waitcnt vmcnt(53)
	s_mov_b32 s12, 0x90000
	s_cmp_eq_u32 s6, 1
	s_cselect_b32 s12, 0x760000, s12
	s_add_u32 s2, s24, s12
	s_addc_u32 s3, s25, 0
	v_cvt_pk_bf16_f32 v6, v5, v5
	v_lshlrev_b32_e32 v33, 16, v33
	global_store_short v2, v6, s[2:3]
	v_fmac_f32_e32 v33, v57, v5
	v_mov_b32_e32 v5, v33
	s_mov_b32 s12, 0x1e0000
	s_cmp_eq_u32 s6, 1
	s_cselect_b32 s12, 0x610000, s12
	s_add_u32 s2, s24, s12
	s_addc_u32 s3, s25, 0
	s_lshr_b32 s12, s12, 6
	s_add_u32 s4, s26, s12
	s_addc_u32 s5, s27, 0
	global_load_ushort v30, v2, s[2:3]
	global_load_dword v54, v3, s[4:5]
	s_waitcnt vmcnt(54)
	s_mov_b32 s12, 0xa0000
	s_cmp_eq_u32 s6, 1
	s_cselect_b32 s12, 0x750000, s12
	s_add_u32 s2, s24, s12
	s_addc_u32 s3, s25, 0
	v_cvt_pk_bf16_f32 v6, v5, v5
	v_lshlrev_b32_e32 v34, 16, v34
	global_store_short v2, v6, s[2:3]
	v_fmac_f32_e32 v34, v58, v5
	v_mov_b32_e32 v5, v34
	s_mov_b32 s12, 0x1f0000
	s_cmp_eq_u32 s6, 1
	s_cselect_b32 s12, 0x600000, s12
	s_add_u32 s2, s24, s12
	s_addc_u32 s3, s25, 0
	s_lshr_b32 s12, s12, 6
	s_add_u32 s4, s26, s12
	s_addc_u32 s5, s27, 0
	global_load_ushort v31, v2, s[2:3]
	global_load_dword v55, v3, s[4:5]
	s_waitcnt vmcnt(55)
	s_mov_b32 s12, 0xb0000
	s_cmp_eq_u32 s6, 1
	s_cselect_b32 s12, 0x740000, s12
	s_add_u32 s2, s24, s12
	s_addc_u32 s3, s25, 0
	v_cvt_pk_bf16_f32 v6, v5, v5
	v_lshlrev_b32_e32 v35, 16, v35
	global_store_short v2, v6, s[2:3]
	v_fmac_f32_e32 v35, v59, v5
	v_mov_b32_e32 v5, v35
	s_mov_b32 s12, 0x200000
	s_cmp_eq_u32 s6, 1
	s_cselect_b32 s12, 0x5f0000, s12
	s_add_u32 s2, s24, s12
	s_addc_u32 s3, s25, 0
	s_lshr_b32 s12, s12, 6
	s_add_u32 s4, s26, s12
	s_addc_u32 s5, s27, 0
	global_load_ushort v32, v2, s[2:3]
	global_load_dword v56, v3, s[4:5]
	s_waitcnt vmcnt(56)
	s_mov_b32 s12, 0xc0000
	s_cmp_eq_u32 s6, 1
	s_cselect_b32 s12, 0x730000, s12
	s_add_u32 s2, s24, s12
	s_addc_u32 s3, s25, 0
	v_cvt_pk_bf16_f32 v6, v5, v5
	v_lshlrev_b32_e32 v36, 16, v36
	global_store_short v2, v6, s[2:3]
	v_fmac_f32_e32 v36, v60, v5
	v_mov_b32_e32 v5, v36
	s_mov_b32 s12, 0x210000
	s_cmp_eq_u32 s6, 1
	s_cselect_b32 s12, 0x5e0000, s12
	s_add_u32 s2, s24, s12
	s_addc_u32 s3, s25, 0
	s_lshr_b32 s12, s12, 6
	s_add_u32 s4, s26, s12
	s_addc_u32 s5, s27, 0
	global_load_ushort v33, v2, s[2:3]
	global_load_dword v57, v3, s[4:5]
	s_waitcnt vmcnt(57)
	s_mov_b32 s12, 0xd0000
	s_cmp_eq_u32 s6, 1
	s_cselect_b32 s12, 0x720000, s12
	s_add_u32 s2, s24, s12
	s_addc_u32 s3, s25, 0
	v_cvt_pk_bf16_f32 v6, v5, v5
	v_lshlrev_b32_e32 v37, 16, v37
	global_store_short v2, v6, s[2:3]
	v_fmac_f32_e32 v37, v61, v5
	v_mov_b32_e32 v5, v37
	s_mov_b32 s12, 0x220000
	s_cmp_eq_u32 s6, 1
	s_cselect_b32 s12, 0x5d0000, s12
	s_add_u32 s2, s24, s12
	s_addc_u32 s3, s25, 0
	s_lshr_b32 s12, s12, 6
	s_add_u32 s4, s26, s12
	s_addc_u32 s5, s27, 0
	global_load_ushort v34, v2, s[2:3]
	global_load_dword v58, v3, s[4:5]
	s_waitcnt vmcnt(58)
	s_mov_b32 s12, 0xe0000
	s_cmp_eq_u32 s6, 1
	s_cselect_b32 s12, 0x710000, s12
	s_add_u32 s2, s24, s12
	s_addc_u32 s3, s25, 0
	v_cvt_pk_bf16_f32 v6, v5, v5
	v_lshlrev_b32_e32 v38, 16, v38
	global_store_short v2, v6, s[2:3]
	v_fmac_f32_e32 v38, v62, v5
	v_mov_b32_e32 v5, v38
	s_mov_b32 s12, 0x230000
	s_cmp_eq_u32 s6, 1
	s_cselect_b32 s12, 0x5c0000, s12
	s_add_u32 s2, s24, s12
	s_addc_u32 s3, s25, 0
	s_lshr_b32 s12, s12, 6
	s_add_u32 s4, s26, s12
	s_addc_u32 s5, s27, 0
	global_load_ushort v35, v2, s[2:3]
	global_load_dword v59, v3, s[4:5]
	s_waitcnt vmcnt(59)
	s_mov_b32 s12, 0xf0000
	s_cmp_eq_u32 s6, 1
	s_cselect_b32 s12, 0x700000, s12
	s_add_u32 s2, s24, s12
	s_addc_u32 s3, s25, 0
	v_cvt_pk_bf16_f32 v6, v5, v5
	v_lshlrev_b32_e32 v39, 16, v39
	global_store_short v2, v6, s[2:3]
	v_fmac_f32_e32 v39, v63, v5
	v_mov_b32_e32 v5, v39
	s_mov_b32 s12, 0x240000
	s_cmp_eq_u32 s6, 1
	s_cselect_b32 s12, 0x5b0000, s12
	s_add_u32 s2, s24, s12
	s_addc_u32 s3, s25, 0
	s_lshr_b32 s12, s12, 6
	s_add_u32 s4, s26, s12
	s_addc_u32 s5, s27, 0
	global_load_ushort v36, v2, s[2:3]
	global_load_dword v60, v3, s[4:5]
	s_waitcnt vmcnt(60)
; DI int otid() { int t = threadIdx.x; asm volatile("" : "+v"(t)); return t; }
; DI float bf2f(bf16 v) { return __uint_as_float(((unsigned)v) << 16); }
; DI bf16 f2bf(float f) { unsigned u = __float_as_uint(f); u += 0x7fffu + ((u >> 16) & 1u); return (bf16)(u >> 16); }
;   DI bf16* G() const { return (bf16*)(p.ws + WS_G); }
;   DI float* DEC() const { return (float*)(p.ws + WS_DEC); }
; DI void gla_g2(const Ctx& c) {
;   const int gt = blockIdx.x * NT + otid(), gs = gridDim.x * NT;
;   for (int i = gt; i < 16 * 8192; i += gs) {
;     const int e = i & 8191, kk = e & 63, q = i >> 13, h = q & 3, bd = q >> 2, dir = bd & 1;
;     float st = 0.f;
;     for (int c0 = 0; c0 < 132; c0 += 12) {
;       float dsv[12], dec[12]; bf16* pd[12];
; #pragma unroll
;       for (int j = 0; j < 12; ++j) {
;         const int ci = c0 + j;
;         const int cm = dir ? (131 - ci) : (ci < 4 ? 128 + ci : ci - 4);
;         const size_t sidx = (size_t)(bd * 132 + cm) * 4 + h;
;         pd[j] = c.G() + sidx * 8192 + e;
;         dsv[j] = bf2f(*pd[j]); dec[j] = c.DEC()[sidx * 64 + kk];
;       }
; #pragma unroll
;       for (int j = 0; j < 12; ++j) { *pd[j] = f2bf(st); st = dec[j] * st + dsv[j]; }
;     }
;   }
; }
	s_mov_b32 s12, 0x100000
	s_cmp_eq_u32 s6, 1
	s_cselect_b32 s12, 0x6f0000, s12
	s_add_u32 s2, s24, s12
	s_addc_u32 s3, s25, 0
	v_cvt_pk_bf16_f32 v6, v5, v5
	v_lshlrev_b32_e32 v40, 16, v40
	global_store_short v2, v6, s[2:3]
	v_fmac_f32_e32 v40, v64, v5
	v_mov_b32_e32 v5, v40
	s_mov_b32 s12, 0x250000
	s_cmp_eq_u32 s6, 1
	s_cselect_b32 s12, 0x5a0000, s12
	s_add_u32 s2, s24, s12
	s_addc_u32 s3, s25, 0
	s_lshr_b32 s12, s12, 6
	s_add_u32 s4, s26, s12
	s_addc_u32 s5, s27, 0
	global_load_ushort v37, v2, s[2:3]
	global_load_dword v61, v3, s[4:5]
	s_waitcnt vmcnt(60)
	s_mov_b32 s12, 0x110000
	s_cmp_eq_u32 s6, 1
	s_cselect_b32 s12, 0x6e0000, s12
	s_add_u32 s2, s24, s12
	s_addc_u32 s3, s25, 0
	v_cvt_pk_bf16_f32 v6, v5, v5
	v_lshlrev_b32_e32 v41, 16, v41
	global_store_short v2, v6, s[2:3]
	v_fmac_f32_e32 v41, v65, v5
	v_mov_b32_e32 v5, v41
	s_mov_b32 s12, 0x260000
	s_cmp_eq_u32 s6, 1
	s_cselect_b32 s12, 0x590000, s12
	s_add_u32 s2, s24, s12
	s_addc_u32 s3, s25, 0
	s_lshr_b32 s12, s12, 6
	s_add_u32 s4, s26, s12
	s_addc_u32 s5, s27, 0
	global_load_ushort v38, v2, s[2:3]
	global_load_dword v62, v3, s[4:5]
	s_waitcnt vmcnt(60)
	s_mov_b32 s12, 0x120000
	s_cmp_eq_u32 s6, 1
	s_cselect_b32 s12, 0x6d0000, s12
	s_add_u32 s2, s24, s12
	s_addc_u32 s3, s25, 0
	v_cvt_pk_bf16_f32 v6, v5, v5
	v_lshlrev_b32_e32 v42, 16, v42
	global_store_short v2, v6, s[2:3]
	v_fmac_f32_e32 v42, v66, v5
	v_mov_b32_e32 v5, v42
	s_mov_b32 s12, 0x270000
	s_cmp_eq_u32 s6, 1
	s_cselect_b32 s12, 0x580000, s12
	s_add_u32 s2, s24, s12
	s_addc_u32 s3, s25, 0
	s_lshr_b32 s12, s12, 6
	s_add_u32 s4, s26, s12
	s_addc_u32 s5, s27, 0
	global_load_ushort v39, v2, s[2:3]
	global_load_dword v63, v3, s[4:5]
	s_waitcnt vmcnt(60)
	s_mov_b32 s12, 0x130000
	s_cmp_eq_u32 s6, 1
	s_cselect_b32 s12, 0x6c0000, s12
	s_add_u32 s2, s24, s12
	s_addc_u32 s3, s25, 0
	v_cvt_pk_bf16_f32 v6, v5, v5
	v_lshlrev_b32_e32 v43, 16, v43
	global_store_short v2, v6, s[2:3]
	v_fmac_f32_e32 v43, v67, v5
	v_mov_b32_e32 v5, v43
	s_mov_b32 s12, 0x280000
	s_cmp_eq_u32 s6, 1
	s_cselect_b32 s12, 0x570000, s12
	s_add_u32 s2, s24, s12
	s_addc_u32 s3, s25, 0
	s_lshr_b32 s12, s12, 6
	s_add_u32 s4, s26, s12
	s_addc_u32 s5, s27, 0
	global_load_ushort v40, v2, s[2:3]
	global_load_dword v64, v3, s[4:5]
	s_waitcnt vmcnt(60)
	s_mov_b32 s12, 0x140000
	s_cmp_eq_u32 s6, 1
	s_cselect_b32 s12, 0x6b0000, s12
	s_add_u32 s2, s24, s12
	s_addc_u32 s3, s25, 0
	v_cvt_pk_bf16_f32 v6, v5, v5
	v_lshlrev_b32_e32 v20, 16, v20
	global_store_short v2, v6, s[2:3]
	v_fmac_f32_e32 v20, v44, v5
	v_mov_b32_e32 v5, v20
	s_mov_b32 s12, 0x290000
	s_cmp_eq_u32 s6, 1
	s_cselect_b32 s12, 0x560000, s12
	s_add_u32 s2, s24, s12
	s_addc_u32 s3, s25, 0
	s_lshr_b32 s12, s12, 6
	s_add_u32 s4, s26, s12
	s_addc_u32 s5, s27, 0
	global_load_ushort v41, v2, s[2:3]
	global_load_dword v65, v3, s[4:5]
	s_waitcnt vmcnt(60)
	s_mov_b32 s12, 0x150000
	s_cmp_eq_u32 s6, 1
	s_cselect_b32 s12, 0x6a0000, s12
	s_add_u32 s2, s24, s12
	s_addc_u32 s3, s25, 0
	v_cvt_pk_bf16_f32 v6, v5, v5
	v_lshlrev_b32_e32 v21, 16, v21
	global_store_short v2, v6, s[2:3]
	v_fmac_f32_e32 v21, v45, v5
	v_mov_b32_e32 v5, v21
	s_mov_b32 s12, 0x2a0000
	s_cmp_eq_u32 s6, 1
	s_cselect_b32 s12, 0x550000, s12
	s_add_u32 s2, s24, s12
	s_addc_u32 s3, s25, 0
	s_lshr_b32 s12, s12, 6
	s_add_u32 s4, s26, s12
	s_addc_u32 s5, s27, 0
	global_load_ushort v42, v2, s[2:3]
	global_load_dword v66, v3, s[4:5]
	s_waitcnt vmcnt(60)
	s_mov_b32 s12, 0x160000
	s_cmp_eq_u32 s6, 1
	s_cselect_b32 s12, 0x690000, s12
	s_add_u32 s2, s24, s12
	s_addc_u32 s3, s25, 0
	v_cvt_pk_bf16_f32 v6, v5, v5
	v_lshlrev_b32_e32 v22, 16, v22
	global_store_short v2, v6, s[2:3]
	v_fmac_f32_e32 v22, v46, v5
	v_mov_b32_e32 v5, v22
	s_mov_b32 s12, 0x2b0000
	s_cmp_eq_u32 s6, 1
	s_cselect_b32 s12, 0x540000, s12
	s_add_u32 s2, s24, s12
	s_addc_u32 s3, s25, 0
	s_lshr_b32 s12, s12, 6
	s_add_u32 s4, s26, s12
	s_addc_u32 s5, s27, 0
	global_load_ushort v43, v2, s[2:3]
	global_load_dword v67, v3, s[4:5]
	s_waitcnt vmcnt(60)
	s_mov_b32 s12, 0x170000
	s_cmp_eq_u32 s6, 1
	s_cselect_b32 s12, 0x680000, s12
	s_add_u32 s2, s24, s12
	s_addc_u32 s3, s25, 0
	v_cvt_pk_bf16_f32 v6, v5, v5
	v_lshlrev_b32_e32 v23, 16, v23
	global_store_short v2, v6, s[2:3]
	v_fmac_f32_e32 v23, v47, v5
	v_mov_b32_e32 v5, v23
	s_mov_b32 s12, 0x2c0000
	s_cmp_eq_u32 s6, 1
	s_cselect_b32 s12, 0x530000, s12
	s_add_u32 s2, s24, s12
	s_addc_u32 s3, s25, 0
	s_lshr_b32 s12, s12, 6
	s_add_u32 s4, s26, s12
	s_addc_u32 s5, s27, 0
	global_load_ushort v20, v2, s[2:3]
	global_load_dword v44, v3, s[4:5]
	s_waitcnt vmcnt(60)
	s_mov_b32 s12, 0x180000
	s_cmp_eq_u32 s6, 1
	s_cselect_b32 s12, 0x670000, s12
	s_add_u32 s2, s24, s12
	s_addc_u32 s3, s25, 0
	v_cvt_pk_bf16_f32 v6, v5, v5
	v_lshlrev_b32_e32 v24, 16, v24
	global_store_short v2, v6, s[2:3]
	v_fmac_f32_e32 v24, v48, v5
	v_mov_b32_e32 v5, v24
	s_mov_b32 s12, 0x2d0000
	s_cmp_eq_u32 s6, 1
	s_cselect_b32 s12, 0x520000, s12
	s_add_u32 s2, s24, s12
	s_addc_u32 s3, s25, 0
	s_lshr_b32 s12, s12, 6
	s_add_u32 s4, s26, s12
	s_addc_u32 s5, s27, 0
	global_load_ushort v21, v2, s[2:3]
	global_load_dword v45, v3, s[4:5]
	s_waitcnt vmcnt(60)
	s_mov_b32 s12, 0x190000
	s_cmp_eq_u32 s6, 1
	s_cselect_b32 s12, 0x660000, s12
	s_add_u32 s2, s24, s12
	s_addc_u32 s3, s25, 0
	v_cvt_pk_bf16_f32 v6, v5, v5
	v_lshlrev_b32_e32 v25, 16, v25
	global_store_short v2, v6, s[2:3]
	v_fmac_f32_e32 v25, v49, v5
	v_mov_b32_e32 v5, v25
	s_mov_b32 s12, 0x2e0000
	s_cmp_eq_u32 s6, 1
	s_cselect_b32 s12, 0x510000, s12
	s_add_u32 s2, s24, s12
	s_addc_u32 s3, s25, 0
	s_lshr_b32 s12, s12, 6
	s_add_u32 s4, s26, s12
	s_addc_u32 s5, s27, 0
	global_load_ushort v22, v2, s[2:3]
	global_load_dword v46, v3, s[4:5]
	s_waitcnt vmcnt(60)
; DI int otid() { int t = threadIdx.x; asm volatile("" : "+v"(t)); return t; }
; DI float bf2f(bf16 v) { return __uint_as_float(((unsigned)v) << 16); }
; DI bf16 f2bf(float f) { unsigned u = __float_as_uint(f); u += 0x7fffu + ((u >> 16) & 1u); return (bf16)(u >> 16); }
;   DI bf16* G() const { return (bf16*)(p.ws + WS_G); }
;   DI float* DEC() const { return (float*)(p.ws + WS_DEC); }
; DI void gla_g2(const Ctx& c) {
;   const int gt = blockIdx.x * NT + otid(), gs = gridDim.x * NT;
;   for (int i = gt; i < 16 * 8192; i += gs) {
;     const int e = i & 8191, kk = e & 63, q = i >> 13, h = q & 3, bd = q >> 2, dir = bd & 1;
;     float st = 0.f;
;     for (int c0 = 0; c0 < 132; c0 += 12) {
;       float dsv[12], dec[12]; bf16* pd[12];
; #pragma unroll
;       for (int j = 0; j < 12; ++j) {
;         const int ci = c0 + j;
;         const int cm = dir ? (131 - ci) : (ci < 4 ? 128 + ci : ci - 4);
;         const size_t sidx = (size_t)(bd * 132 + cm) * 4 + h;
;         pd[j] = c.G() + sidx * 8192 + e;
;         dsv[j] = bf2f(*pd[j]); dec[j] = c.DEC()[sidx * 64 + kk];
;       }
; #pragma unroll
;       for (int j = 0; j < 12; ++j) { *pd[j] = f2bf(st); st = dec[j] * st + dsv[j]; }
;     }
;   }
; }
	s_mov_b32 s12, 0x1a0000
	s_cmp_eq_u32 s6, 1
	s_cselect_b32 s12, 0x650000, s12
	s_add_u32 s2, s24, s12
	s_addc_u32 s3, s25, 0
	v_cvt_pk_bf16_f32 v6, v5, v5
	v_lshlrev_b32_e32 v26, 16, v26
	global_store_short v2, v6, s[2:3]
	v_fmac_f32_e32 v26, v50, v5
	v_mov_b32_e32 v5, v26
	s_mov_b32 s12, 0x2f0000
	s_cmp_eq_u32 s6, 1
	s_cselect_b32 s12, 0x500000, s12
	s_add_u32 s2, s24, s12
	s_addc_u32 s3, s25, 0
	s_lshr_b32 s12, s12, 6
	s_add_u32 s4, s26, s12
	s_addc_u32 s5, s27, 0
	global_load_ushort v23, v2, s[2:3]
	global_load_dword v47, v3, s[4:5]
	s_waitcnt vmcnt(60)
	s_mov_b32 s12, 0x1b0000
	s_cmp_eq_u32 s6, 1
	s_cselect_b32 s12, 0x640000, s12
	s_add_u32 s2, s24, s12
	s_addc_u32 s3, s25, 0
	v_cvt_pk_bf16_f32 v6, v5, v5
	v_lshlrev_b32_e32 v27, 16, v27
	global_store_short v2, v6, s[2:3]
	v_fmac_f32_e32 v27, v51, v5
	v_mov_b32_e32 v5, v27
	s_mov_b32 s12, 0x300000
	s_cmp_eq_u32 s6, 1
	s_cselect_b32 s12, 0x4f0000, s12
	s_add_u32 s2, s24, s12
	s_addc_u32 s3, s25, 0
	s_lshr_b32 s12, s12, 6
	s_add_u32 s4, s26, s12
	s_addc_u32 s5, s27, 0
	global_load_ushort v24, v2, s[2:3]
	global_load_dword v48, v3, s[4:5]
	s_waitcnt vmcnt(60)
	s_mov_b32 s12, 0x1c0000
	s_cmp_eq_u32 s6, 1
	s_cselect_b32 s12, 0x630000, s12
	s_add_u32 s2, s24, s12
	s_addc_u32 s3, s25, 0
	v_cvt_pk_bf16_f32 v6, v5, v5
	v_lshlrev_b32_e32 v28, 16, v28
	global_store_short v2, v6, s[2:3]
	v_fmac_f32_e32 v28, v52, v5
	v_mov_b32_e32 v5, v28
	s_mov_b32 s12, 0x310000
	s_cmp_eq_u32 s6, 1
	s_cselect_b32 s12, 0x4e0000, s12
	s_add_u32 s2, s24, s12
	s_addc_u32 s3, s25, 0
	s_lshr_b32 s12, s12, 6
	s_add_u32 s4, s26, s12
	s_addc_u32 s5, s27, 0
	global_load_ushort v25, v2, s[2:3]
	global_load_dword v49, v3, s[4:5]
	s_waitcnt vmcnt(60)
	s_mov_b32 s12, 0x1d0000
	s_cmp_eq_u32 s6, 1
	s_cselect_b32 s12, 0x620000, s12
	s_add_u32 s2, s24, s12
	s_addc_u32 s3, s25, 0
	v_cvt_pk_bf16_f32 v6, v5, v5
	v_lshlrev_b32_e32 v29, 16, v29
	global_store_short v2, v6, s[2:3]
	v_fmac_f32_e32 v29, v53, v5
	v_mov_b32_e32 v5, v29
	s_mov_b32 s12, 0x320000
	s_cmp_eq_u32 s6, 1
	s_cselect_b32 s12, 0x4d0000, s12
	s_add_u32 s2, s24, s12
	s_addc_u32 s3, s25, 0
	s_lshr_b32 s12, s12, 6
	s_add_u32 s4, s26, s12
	s_addc_u32 s5, s27, 0
	global_load_ushort v26, v2, s[2:3]
	global_load_dword v50, v3, s[4:5]
	s_waitcnt vmcnt(60)
	s_mov_b32 s12, 0x1e0000
	s_cmp_eq_u32 s6, 1
	s_cselect_b32 s12, 0x610000, s12
	s_add_u32 s2, s24, s12
	s_addc_u32 s3, s25, 0
	v_cvt_pk_bf16_f32 v6, v5, v5
	v_lshlrev_b32_e32 v30, 16, v30
	global_store_short v2, v6, s[2:3]
	v_fmac_f32_e32 v30, v54, v5
	v_mov_b32_e32 v5, v30
	s_mov_b32 s12, 0x330000
	s_cmp_eq_u32 s6, 1
	s_cselect_b32 s12, 0x4c0000, s12
	s_add_u32 s2, s24, s12
	s_addc_u32 s3, s25, 0
	s_lshr_b32 s12, s12, 6
	s_add_u32 s4, s26, s12
	s_addc_u32 s5, s27, 0
	global_load_ushort v27, v2, s[2:3]
	global_load_dword v51, v3, s[4:5]
	s_waitcnt vmcnt(60)
	s_mov_b32 s12, 0x1f0000
	s_cmp_eq_u32 s6, 1
	s_cselect_b32 s12, 0x600000, s12
	s_add_u32 s2, s24, s12
	s_addc_u32 s3, s25, 0
	v_cvt_pk_bf16_f32 v6, v5, v5
	v_lshlrev_b32_e32 v31, 16, v31
	global_store_short v2, v6, s[2:3]
	v_fmac_f32_e32 v31, v55, v5
	v_mov_b32_e32 v5, v31
	s_mov_b32 s12, 0x340000
	s_cmp_eq_u32 s6, 1
	s_cselect_b32 s12, 0x4b0000, s12
	s_add_u32 s2, s24, s12
	s_addc_u32 s3, s25, 0
	s_lshr_b32 s12, s12, 6
	s_add_u32 s4, s26, s12
	s_addc_u32 s5, s27, 0
	global_load_ushort v28, v2, s[2:3]
	global_load_dword v52, v3, s[4:5]
	s_waitcnt vmcnt(60)
	s_mov_b32 s12, 0x200000
	s_cmp_eq_u32 s6, 1
	s_cselect_b32 s12, 0x5f0000, s12
	s_add_u32 s2, s24, s12
	s_addc_u32 s3, s25, 0
	v_cvt_pk_bf16_f32 v6, v5, v5
	v_lshlrev_b32_e32 v32, 16, v32
	global_store_short v2, v6, s[2:3]
	v_fmac_f32_e32 v32, v56, v5
	v_mov_b32_e32 v5, v32
	s_mov_b32 s12, 0x350000
	s_cmp_eq_u32 s6, 1
	s_cselect_b32 s12, 0x4a0000, s12
	s_add_u32 s2, s24, s12
	s_addc_u32 s3, s25, 0
	s_lshr_b32 s12, s12, 6
	s_add_u32 s4, s26, s12
	s_addc_u32 s5, s27, 0
	global_load_ushort v29, v2, s[2:3]
	global_load_dword v53, v3, s[4:5]
	s_waitcnt vmcnt(60)
	s_mov_b32 s12, 0x210000
	s_cmp_eq_u32 s6, 1
	s_cselect_b32 s12, 0x5e0000, s12
	s_add_u32 s2, s24, s12
	s_addc_u32 s3, s25, 0
	v_cvt_pk_bf16_f32 v6, v5, v5
	v_lshlrev_b32_e32 v33, 16, v33
	global_store_short v2, v6, s[2:3]
	v_fmac_f32_e32 v33, v57, v5
	v_mov_b32_e32 v5, v33
	s_mov_b32 s12, 0x360000
	s_cmp_eq_u32 s6, 1
	s_cselect_b32 s12, 0x490000, s12
	s_add_u32 s2, s24, s12
	s_addc_u32 s3, s25, 0
	s_lshr_b32 s12, s12, 6
	s_add_u32 s4, s26, s12
	s_addc_u32 s5, s27, 0
	global_load_ushort v30, v2, s[2:3]
	global_load_dword v54, v3, s[4:5]
	s_waitcnt vmcnt(60)
	s_mov_b32 s12, 0x220000
	s_cmp_eq_u32 s6, 1
	s_cselect_b32 s12, 0x5d0000, s12
	s_add_u32 s2, s24, s12
	s_addc_u32 s3, s25, 0
	v_cvt_pk_bf16_f32 v6, v5, v5
	v_lshlrev_b32_e32 v34, 16, v34
	global_store_short v2, v6, s[2:3]
	v_fmac_f32_e32 v34, v58, v5
	v_mov_b32_e32 v5, v34
	s_mov_b32 s12, 0x370000
	s_cmp_eq_u32 s6, 1
	s_cselect_b32 s12, 0x480000, s12
	s_add_u32 s2, s24, s12
	s_addc_u32 s3, s25, 0
	s_lshr_b32 s12, s12, 6
	s_add_u32 s4, s26, s12
	s_addc_u32 s5, s27, 0
	global_load_ushort v31, v2, s[2:3]
	global_load_dword v55, v3, s[4:5]
	s_waitcnt vmcnt(60)
	s_mov_b32 s12, 0x230000
	s_cmp_eq_u32 s6, 1
	s_cselect_b32 s12, 0x5c0000, s12
	s_add_u32 s2, s24, s12
	s_addc_u32 s3, s25, 0
	v_cvt_pk_bf16_f32 v6, v5, v5
	v_lshlrev_b32_e32 v35, 16, v35
	global_store_short v2, v6, s[2:3]
	v_fmac_f32_e32 v35, v59, v5
	v_mov_b32_e32 v5, v35
	s_mov_b32 s12, 0x380000
	s_cmp_eq_u32 s6, 1
	s_cselect_b32 s12, 0x470000, s12
	s_add_u32 s2, s24, s12
	s_addc_u32 s3, s25, 0
	s_lshr_b32 s12, s12, 6
	s_add_u32 s4, s26, s12
	s_addc_u32 s5, s27, 0
	global_load_ushort v32, v2, s[2:3]
	global_load_dword v56, v3, s[4:5]
	s_waitcnt vmcnt(60)
; DI int otid() { int t = threadIdx.x; asm volatile("" : "+v"(t)); return t; }
; DI float bf2f(bf16 v) { return __uint_as_float(((unsigned)v) << 16); }
; DI bf16 f2bf(float f) { unsigned u = __float_as_uint(f); u += 0x7fffu + ((u >> 16) & 1u); return (bf16)(u >> 16); }
;   DI bf16* G() const { return (bf16*)(p.ws + WS_G); }
;   DI float* DEC() const { return (float*)(p.ws + WS_DEC); }
; DI void gla_g2(const Ctx& c) {
;   const int gt = blockIdx.x * NT + otid(), gs = gridDim.x * NT;
;   for (int i = gt; i < 16 * 8192; i += gs) {
;     const int e = i & 8191, kk = e & 63, q = i >> 13, h = q & 3, bd = q >> 2, dir = bd & 1;
;     float st = 0.f;
;     for (int c0 = 0; c0 < 132; c0 += 12) {
;       float dsv[12], dec[12]; bf16* pd[12];
; #pragma unroll
;       for (int j = 0; j < 12; ++j) {
;         const int ci = c0 + j;
;         const int cm = dir ? (131 - ci) : (ci < 4 ? 128 + ci : ci - 4);
;         const size_t sidx = (size_t)(bd * 132 + cm) * 4 + h;
;         pd[j] = c.G() + sidx * 8192 + e;
;         dsv[j] = bf2f(*pd[j]); dec[j] = c.DEC()[sidx * 64 + kk];
;       }
; #pragma unroll
;       for (int j = 0; j < 12; ++j) { *pd[j] = f2bf(st); st = dec[j] * st + dsv[j]; }
;     }
;   }
; }
	s_mov_b32 s12, 0x240000
	s_cmp_eq_u32 s6, 1
	s_cselect_b32 s12, 0x5b0000, s12
	s_add_u32 s2, s24, s12
	s_addc_u32 s3, s25, 0
	v_cvt_pk_bf16_f32 v6, v5, v5
	v_lshlrev_b32_e32 v36, 16, v36
	global_store_short v2, v6, s[2:3]
	v_fmac_f32_e32 v36, v60, v5
	v_mov_b32_e32 v5, v36
	s_mov_b32 s12, 0x390000
	s_cmp_eq_u32 s6, 1
	s_cselect_b32 s12, 0x460000, s12
	s_add_u32 s2, s24, s12
	s_addc_u32 s3, s25, 0
	s_lshr_b32 s12, s12, 6
	s_add_u32 s4, s26, s12
	s_addc_u32 s5, s27, 0
	global_load_ushort v33, v2, s[2:3]
	global_load_dword v57, v3, s[4:5]
	s_waitcnt vmcnt(60)
	s_mov_b32 s12, 0x250000
	s_cmp_eq_u32 s6, 1
	s_cselect_b32 s12, 0x5a0000, s12
	s_add_u32 s2, s24, s12
	s_addc_u32 s3, s25, 0
	v_cvt_pk_bf16_f32 v6, v5, v5
	v_lshlrev_b32_e32 v37, 16, v37
	global_store_short v2, v6, s[2:3]
	v_fmac_f32_e32 v37, v61, v5
	v_mov_b32_e32 v5, v37
	s_mov_b32 s12, 0x3a0000
	s_cmp_eq_u32 s6, 1
	s_cselect_b32 s12, 0x450000, s12
	s_add_u32 s2, s24, s12
	s_addc_u32 s3, s25, 0
	s_lshr_b32 s12, s12, 6
	s_add_u32 s4, s26, s12
	s_addc_u32 s5, s27, 0
	global_load_ushort v34, v2, s[2:3]
	global_load_dword v58, v3, s[4:5]
	s_waitcnt vmcnt(60)
	s_mov_b32 s12, 0x260000
	s_cmp_eq_u32 s6, 1
	s_cselect_b32 s12, 0x590000, s12
	s_add_u32 s2, s24, s12
	s_addc_u32 s3, s25, 0
	v_cvt_pk_bf16_f32 v6, v5, v5
	v_lshlrev_b32_e32 v38, 16, v38
	global_store_short v2, v6, s[2:3]
	v_fmac_f32_e32 v38, v62, v5
	v_mov_b32_e32 v5, v38
	s_mov_b32 s12, 0x3b0000
	s_cmp_eq_u32 s6, 1
	s_cselect_b32 s12, 0x440000, s12
	s_add_u32 s2, s24, s12
	s_addc_u32 s3, s25, 0
	s_lshr_b32 s12, s12, 6
	s_add_u32 s4, s26, s12
	s_addc_u32 s5, s27, 0
	global_load_ushort v35, v2, s[2:3]
	global_load_dword v59, v3, s[4:5]
	s_waitcnt vmcnt(60)
	s_mov_b32 s12, 0x270000
	s_cmp_eq_u32 s6, 1
	s_cselect_b32 s12, 0x580000, s12
	s_add_u32 s2, s24, s12
	s_addc_u32 s3, s25, 0
	v_cvt_pk_bf16_f32 v6, v5, v5
	v_lshlrev_b32_e32 v39, 16, v39
	global_store_short v2, v6, s[2:3]
	v_fmac_f32_e32 v39, v63, v5
	v_mov_b32_e32 v5, v39
	s_mov_b32 s12, 0x3c0000
	s_cmp_eq_u32 s6, 1
	s_cselect_b32 s12, 0x430000, s12
	s_add_u32 s2, s24, s12
	s_addc_u32 s3, s25, 0
	s_lshr_b32 s12, s12, 6
	s_add_u32 s4, s26, s12
	s_addc_u32 s5, s27, 0
	global_load_ushort v36, v2, s[2:3]
	global_load_dword v60, v3, s[4:5]
	s_waitcnt vmcnt(60)
	s_mov_b32 s12, 0x280000
	s_cmp_eq_u32 s6, 1
	s_cselect_b32 s12, 0x570000, s12
	s_add_u32 s2, s24, s12
	s_addc_u32 s3, s25, 0
	v_cvt_pk_bf16_f32 v6, v5, v5
	v_lshlrev_b32_e32 v40, 16, v40
	global_store_short v2, v6, s[2:3]
	v_fmac_f32_e32 v40, v64, v5
	v_mov_b32_e32 v5, v40
	s_mov_b32 s12, 0x3d0000
	s_cmp_eq_u32 s6, 1
	s_cselect_b32 s12, 0x420000, s12
	s_add_u32 s2, s24, s12
	s_addc_u32 s3, s25, 0
	s_lshr_b32 s12, s12, 6
	s_add_u32 s4, s26, s12
	s_addc_u32 s5, s27, 0
	global_load_ushort v37, v2, s[2:3]
	global_load_dword v61, v3, s[4:5]
	s_waitcnt vmcnt(60)
	s_mov_b32 s12, 0x290000
	s_cmp_eq_u32 s6, 1
	s_cselect_b32 s12, 0x560000, s12
	s_add_u32 s2, s24, s12
	s_addc_u32 s3, s25, 0
	v_cvt_pk_bf16_f32 v6, v5, v5
	v_lshlrev_b32_e32 v41, 16, v41
	global_store_short v2, v6, s[2:3]
	v_fmac_f32_e32 v41, v65, v5
	v_mov_b32_e32 v5, v41
	s_mov_b32 s12, 0x3e0000
	s_cmp_eq_u32 s6, 1
	s_cselect_b32 s12, 0x410000, s12
	s_add_u32 s2, s24, s12
	s_addc_u32 s3, s25, 0
	s_lshr_b32 s12, s12, 6
	s_add_u32 s4, s26, s12
	s_addc_u32 s5, s27, 0
	global_load_ushort v38, v2, s[2:3]
	global_load_dword v62, v3, s[4:5]
	s_waitcnt vmcnt(60)
	s_mov_b32 s12, 0x2a0000
	s_cmp_eq_u32 s6, 1
	s_cselect_b32 s12, 0x550000, s12
	s_add_u32 s2, s24, s12
	s_addc_u32 s3, s25, 0
	v_cvt_pk_bf16_f32 v6, v5, v5
	v_lshlrev_b32_e32 v42, 16, v42
	global_store_short v2, v6, s[2:3]
	v_fmac_f32_e32 v42, v66, v5
	v_mov_b32_e32 v5, v42
	s_mov_b32 s12, 0x3f0000
	s_cmp_eq_u32 s6, 1
	s_cselect_b32 s12, 0x400000, s12
	s_add_u32 s2, s24, s12
	s_addc_u32 s3, s25, 0
	s_lshr_b32 s12, s12, 6
	s_add_u32 s4, s26, s12
	s_addc_u32 s5, s27, 0
	global_load_ushort v39, v2, s[2:3]
	global_load_dword v63, v3, s[4:5]
	s_waitcnt vmcnt(60)
	s_mov_b32 s12, 0x2b0000
	s_cmp_eq_u32 s6, 1
	s_cselect_b32 s12, 0x540000, s12
	s_add_u32 s2, s24, s12
	s_addc_u32 s3, s25, 0
	v_cvt_pk_bf16_f32 v6, v5, v5
	v_lshlrev_b32_e32 v43, 16, v43
	global_store_short v2, v6, s[2:3]
	v_fmac_f32_e32 v43, v67, v5
	v_mov_b32_e32 v5, v43
	s_mov_b32 s12, 0x400000
	s_cmp_eq_u32 s6, 1
	s_cselect_b32 s12, 0x3f0000, s12
	s_add_u32 s2, s24, s12
	s_addc_u32 s3, s25, 0
	s_lshr_b32 s12, s12, 6
	s_add_u32 s4, s26, s12
	s_addc_u32 s5, s27, 0
	global_load_ushort v40, v2, s[2:3]
	global_load_dword v64, v3, s[4:5]
	s_waitcnt vmcnt(60)
	s_mov_b32 s12, 0x2c0000
	s_cmp_eq_u32 s6, 1
	s_cselect_b32 s12, 0x530000, s12
	s_add_u32 s2, s24, s12
	s_addc_u32 s3, s25, 0
	v_cvt_pk_bf16_f32 v6, v5, v5
	v_lshlrev_b32_e32 v20, 16, v20
	global_store_short v2, v6, s[2:3]
	v_fmac_f32_e32 v20, v44, v5
	v_mov_b32_e32 v5, v20
	s_mov_b32 s12, 0x410000
	s_cmp_eq_u32 s6, 1
	s_cselect_b32 s12, 0x3e0000, s12
	s_add_u32 s2, s24, s12
	s_addc_u32 s3, s25, 0
	s_lshr_b32 s12, s12, 6
	s_add_u32 s4, s26, s12
	s_addc_u32 s5, s27, 0
	global_load_ushort v41, v2, s[2:3]
	global_load_dword v65, v3, s[4:5]
	s_waitcnt vmcnt(60)
	s_mov_b32 s12, 0x2d0000
	s_cmp_eq_u32 s6, 1
	s_cselect_b32 s12, 0x520000, s12
	s_add_u32 s2, s24, s12
	s_addc_u32 s3, s25, 0
	v_cvt_pk_bf16_f32 v6, v5, v5
	v_lshlrev_b32_e32 v21, 16, v21
	global_store_short v2, v6, s[2:3]
	v_fmac_f32_e32 v21, v45, v5
	v_mov_b32_e32 v5, v21
	s_mov_b32 s12, 0x420000
	s_cmp_eq_u32 s6, 1
	s_cselect_b32 s12, 0x3d0000, s12
	s_add_u32 s2, s24, s12
	s_addc_u32 s3, s25, 0
	s_lshr_b32 s12, s12, 6
	s_add_u32 s4, s26, s12
	s_addc_u32 s5, s27, 0
	global_load_ushort v42, v2, s[2:3]
	global_load_dword v66, v3, s[4:5]
	s_waitcnt vmcnt(60)
; DI int otid() { int t = threadIdx.x; asm volatile("" : "+v"(t)); return t; }
; DI float bf2f(bf16 v) { return __uint_as_float(((unsigned)v) << 16); }
; DI bf16 f2bf(float f) { unsigned u = __float_as_uint(f); u += 0x7fffu + ((u >> 16) & 1u); return (bf16)(u >> 16); }
;   DI bf16* G() const { return (bf16*)(p.ws + WS_G); }
;   DI float* DEC() const { return (float*)(p.ws + WS_DEC); }
; DI void gla_g2(const Ctx& c) {
;   const int gt = blockIdx.x * NT + otid(), gs = gridDim.x * NT;
;   for (int i = gt; i < 16 * 8192; i += gs) {
;     const int e = i & 8191, kk = e & 63, q = i >> 13, h = q & 3, bd = q >> 2, dir = bd & 1;
;     float st = 0.f;
;     for (int c0 = 0; c0 < 132; c0 += 12) {
;       float dsv[12], dec[12]; bf16* pd[12];
; #pragma unroll
;       for (int j = 0; j < 12; ++j) {
;         const int ci = c0 + j;
;         const int cm = dir ? (131 - ci) : (ci < 4 ? 128 + ci : ci - 4);
;         const size_t sidx = (size_t)(bd * 132 + cm) * 4 + h;
;         pd[j] = c.G() + sidx * 8192 + e;
;         dsv[j] = bf2f(*pd[j]); dec[j] = c.DEC()[sidx * 64 + kk];
;       }
; #pragma unroll
;       for (int j = 0; j < 12; ++j) { *pd[j] = f2bf(st); st = dec[j] * st + dsv[j]; }
;     }
;   }
; }
	s_mov_b32 s12, 0x2e0000
	s_cmp_eq_u32 s6, 1
	s_cselect_b32 s12, 0x510000, s12
	s_add_u32 s2, s24, s12
	s_addc_u32 s3, s25, 0
	v_cvt_pk_bf16_f32 v6, v5, v5
	v_lshlrev_b32_e32 v22, 16, v22
	global_store_short v2, v6, s[2:3]
	v_fmac_f32_e32 v22, v46, v5
	v_mov_b32_e32 v5, v22
	s_mov_b32 s12, 0x430000
	s_cmp_eq_u32 s6, 1
	s_cselect_b32 s12, 0x3c0000, s12
	s_add_u32 s2, s24, s12
	s_addc_u32 s3, s25, 0
	s_lshr_b32 s12, s12, 6
	s_add_u32 s4, s26, s12
	s_addc_u32 s5, s27, 0
	global_load_ushort v43, v2, s[2:3]
	global_load_dword v67, v3, s[4:5]
	s_waitcnt vmcnt(60)
	s_mov_b32 s12, 0x2f0000
	s_cmp_eq_u32 s6, 1
	s_cselect_b32 s12, 0x500000, s12
	s_add_u32 s2, s24, s12
	s_addc_u32 s3, s25, 0
	v_cvt_pk_bf16_f32 v6, v5, v5
	v_lshlrev_b32_e32 v23, 16, v23
	global_store_short v2, v6, s[2:3]
	v_fmac_f32_e32 v23, v47, v5
	v_mov_b32_e32 v5, v23
	s_mov_b32 s12, 0x440000
	s_cmp_eq_u32 s6, 1
	s_cselect_b32 s12, 0x3b0000, s12
	s_add_u32 s2, s24, s12
	s_addc_u32 s3, s25, 0
	s_lshr_b32 s12, s12, 6
	s_add_u32 s4, s26, s12
	s_addc_u32 s5, s27, 0
	global_load_ushort v20, v2, s[2:3]
	global_load_dword v44, v3, s[4:5]
	s_waitcnt vmcnt(60)
	s_mov_b32 s12, 0x300000
	s_cmp_eq_u32 s6, 1
	s_cselect_b32 s12, 0x4f0000, s12
	s_add_u32 s2, s24, s12
	s_addc_u32 s3, s25, 0
	v_cvt_pk_bf16_f32 v6, v5, v5
	v_lshlrev_b32_e32 v24, 16, v24
	global_store_short v2, v6, s[2:3]
	v_fmac_f32_e32 v24, v48, v5
	v_mov_b32_e32 v5, v24
	s_mov_b32 s12, 0x450000
	s_cmp_eq_u32 s6, 1
	s_cselect_b32 s12, 0x3a0000, s12
	s_add_u32 s2, s24, s12
	s_addc_u32 s3, s25, 0
	s_lshr_b32 s12, s12, 6
	s_add_u32 s4, s26, s12
	s_addc_u32 s5, s27, 0
	global_load_ushort v21, v2, s[2:3]
	global_load_dword v45, v3, s[4:5]
	s_waitcnt vmcnt(60)
	s_mov_b32 s12, 0x310000
	s_cmp_eq_u32 s6, 1
	s_cselect_b32 s12, 0x4e0000, s12
	s_add_u32 s2, s24, s12
	s_addc_u32 s3, s25, 0
	v_cvt_pk_bf16_f32 v6, v5, v5
	v_lshlrev_b32_e32 v25, 16, v25
	global_store_short v2, v6, s[2:3]
	v_fmac_f32_e32 v25, v49, v5
	v_mov_b32_e32 v5, v25
	s_mov_b32 s12, 0x460000
	s_cmp_eq_u32 s6, 1
	s_cselect_b32 s12, 0x390000, s12
	s_add_u32 s2, s24, s12
	s_addc_u32 s3, s25, 0
	s_lshr_b32 s12, s12, 6
	s_add_u32 s4, s26, s12
	s_addc_u32 s5, s27, 0
	global_load_ushort v22, v2, s[2:3]
	global_load_dword v46, v3, s[4:5]
	s_waitcnt vmcnt(60)
	s_mov_b32 s12, 0x320000
	s_cmp_eq_u32 s6, 1
	s_cselect_b32 s12, 0x4d0000, s12
	s_add_u32 s2, s24, s12
	s_addc_u32 s3, s25, 0
	v_cvt_pk_bf16_f32 v6, v5, v5
	v_lshlrev_b32_e32 v26, 16, v26
	global_store_short v2, v6, s[2:3]
	v_fmac_f32_e32 v26, v50, v5
	v_mov_b32_e32 v5, v26
	s_mov_b32 s12, 0x470000
	s_cmp_eq_u32 s6, 1
	s_cselect_b32 s12, 0x380000, s12
	s_add_u32 s2, s24, s12
	s_addc_u32 s3, s25, 0
	s_lshr_b32 s12, s12, 6
	s_add_u32 s4, s26, s12
	s_addc_u32 s5, s27, 0
	global_load_ushort v23, v2, s[2:3]
	global_load_dword v47, v3, s[4:5]
	s_waitcnt vmcnt(60)
	s_mov_b32 s12, 0x330000
	s_cmp_eq_u32 s6, 1
	s_cselect_b32 s12, 0x4c0000, s12
	s_add_u32 s2, s24, s12
	s_addc_u32 s3, s25, 0
	v_cvt_pk_bf16_f32 v6, v5, v5
	v_lshlrev_b32_e32 v27, 16, v27
	global_store_short v2, v6, s[2:3]
	v_fmac_f32_e32 v27, v51, v5
	v_mov_b32_e32 v5, v27
	s_mov_b32 s12, 0x480000
	s_cmp_eq_u32 s6, 1
	s_cselect_b32 s12, 0x370000, s12
	s_add_u32 s2, s24, s12
	s_addc_u32 s3, s25, 0
	s_lshr_b32 s12, s12, 6
	s_add_u32 s4, s26, s12
	s_addc_u32 s5, s27, 0
	global_load_ushort v24, v2, s[2:3]
	global_load_dword v48, v3, s[4:5]
	s_waitcnt vmcnt(60)
	s_mov_b32 s12, 0x340000
	s_cmp_eq_u32 s6, 1
	s_cselect_b32 s12, 0x4b0000, s12
	s_add_u32 s2, s24, s12
	s_addc_u32 s3, s25, 0
	v_cvt_pk_bf16_f32 v6, v5, v5
	v_lshlrev_b32_e32 v28, 16, v28
	global_store_short v2, v6, s[2:3]
	v_fmac_f32_e32 v28, v52, v5
	v_mov_b32_e32 v5, v28
	s_mov_b32 s12, 0x490000
	s_cmp_eq_u32 s6, 1
	s_cselect_b32 s12, 0x360000, s12
	s_add_u32 s2, s24, s12
	s_addc_u32 s3, s25, 0
	s_lshr_b32 s12, s12, 6
	s_add_u32 s4, s26, s12
	s_addc_u32 s5, s27, 0
	global_load_ushort v25, v2, s[2:3]
	global_load_dword v49, v3, s[4:5]
	s_waitcnt vmcnt(60)
	s_mov_b32 s12, 0x350000
	s_cmp_eq_u32 s6, 1
	s_cselect_b32 s12, 0x4a0000, s12
	s_add_u32 s2, s24, s12
	s_addc_u32 s3, s25, 0
	v_cvt_pk_bf16_f32 v6, v5, v5
	v_lshlrev_b32_e32 v29, 16, v29
	global_store_short v2, v6, s[2:3]
	v_fmac_f32_e32 v29, v53, v5
	v_mov_b32_e32 v5, v29
	s_mov_b32 s12, 0x4a0000
	s_cmp_eq_u32 s6, 1
	s_cselect_b32 s12, 0x350000, s12
	s_add_u32 s2, s24, s12
	s_addc_u32 s3, s25, 0
	s_lshr_b32 s12, s12, 6
	s_add_u32 s4, s26, s12
	s_addc_u32 s5, s27, 0
	global_load_ushort v26, v2, s[2:3]
	global_load_dword v50, v3, s[4:5]
	s_waitcnt vmcnt(60)
	s_mov_b32 s12, 0x360000
	s_cmp_eq_u32 s6, 1
	s_cselect_b32 s12, 0x490000, s12
	s_add_u32 s2, s24, s12
	s_addc_u32 s3, s25, 0
	v_cvt_pk_bf16_f32 v6, v5, v5
	v_lshlrev_b32_e32 v30, 16, v30
	global_store_short v2, v6, s[2:3]
	v_fmac_f32_e32 v30, v54, v5
	v_mov_b32_e32 v5, v30
	s_mov_b32 s12, 0x4b0000
	s_cmp_eq_u32 s6, 1
	s_cselect_b32 s12, 0x340000, s12
	s_add_u32 s2, s24, s12
	s_addc_u32 s3, s25, 0
	s_lshr_b32 s12, s12, 6
	s_add_u32 s4, s26, s12
	s_addc_u32 s5, s27, 0
	global_load_ushort v27, v2, s[2:3]
	global_load_dword v51, v3, s[4:5]
	s_waitcnt vmcnt(60)
	s_mov_b32 s12, 0x370000
	s_cmp_eq_u32 s6, 1
	s_cselect_b32 s12, 0x480000, s12
	s_add_u32 s2, s24, s12
	s_addc_u32 s3, s25, 0
	v_cvt_pk_bf16_f32 v6, v5, v5
	v_lshlrev_b32_e32 v31, 16, v31
	global_store_short v2, v6, s[2:3]
	v_fmac_f32_e32 v31, v55, v5
	v_mov_b32_e32 v5, v31
	s_mov_b32 s12, 0x4c0000
	s_cmp_eq_u32 s6, 1
	s_cselect_b32 s12, 0x330000, s12
	s_add_u32 s2, s24, s12
	s_addc_u32 s3, s25, 0
	s_lshr_b32 s12, s12, 6
	s_add_u32 s4, s26, s12
	s_addc_u32 s5, s27, 0
	global_load_ushort v28, v2, s[2:3]
	global_load_dword v52, v3, s[4:5]
	s_waitcnt vmcnt(60)
; DI int otid() { int t = threadIdx.x; asm volatile("" : "+v"(t)); return t; }
; DI float bf2f(bf16 v) { return __uint_as_float(((unsigned)v) << 16); }
; DI bf16 f2bf(float f) { unsigned u = __float_as_uint(f); u += 0x7fffu + ((u >> 16) & 1u); return (bf16)(u >> 16); }
;   DI bf16* G() const { return (bf16*)(p.ws + WS_G); }
;   DI float* DEC() const { return (float*)(p.ws + WS_DEC); }
; DI void gla_g2(const Ctx& c) {
;   const int gt = blockIdx.x * NT + otid(), gs = gridDim.x * NT;
;   for (int i = gt; i < 16 * 8192; i += gs) {
;     const int e = i & 8191, kk = e & 63, q = i >> 13, h = q & 3, bd = q >> 2, dir = bd & 1;
;     float st = 0.f;
;     for (int c0 = 0; c0 < 132; c0 += 12) {
;       float dsv[12], dec[12]; bf16* pd[12];
; #pragma unroll
;       for (int j = 0; j < 12; ++j) {
;         const int ci = c0 + j;
;         const int cm = dir ? (131 - ci) : (ci < 4 ? 128 + ci : ci - 4);
;         const size_t sidx = (size_t)(bd * 132 + cm) * 4 + h;
;         pd[j] = c.G() + sidx * 8192 + e;
;         dsv[j] = bf2f(*pd[j]); dec[j] = c.DEC()[sidx * 64 + kk];
;       }
; #pragma unroll
;       for (int j = 0; j < 12; ++j) { *pd[j] = f2bf(st); st = dec[j] * st + dsv[j]; }
;     }
;   }
; }
	s_mov_b32 s12, 0x380000
	s_cmp_eq_u32 s6, 1
	s_cselect_b32 s12, 0x470000, s12
	s_add_u32 s2, s24, s12
	s_addc_u32 s3, s25, 0
	v_cvt_pk_bf16_f32 v6, v5, v5
	v_lshlrev_b32_e32 v32, 16, v32
	global_store_short v2, v6, s[2:3]
	v_fmac_f32_e32 v32, v56, v5
	v_mov_b32_e32 v5, v32
	s_mov_b32 s12, 0x4d0000
	s_cmp_eq_u32 s6, 1
	s_cselect_b32 s12, 0x320000, s12
	s_add_u32 s2, s24, s12
	s_addc_u32 s3, s25, 0
	s_lshr_b32 s12, s12, 6
	s_add_u32 s4, s26, s12
	s_addc_u32 s5, s27, 0
	global_load_ushort v29, v2, s[2:3]
	global_load_dword v53, v3, s[4:5]
	s_waitcnt vmcnt(60)
	s_mov_b32 s12, 0x390000
	s_cmp_eq_u32 s6, 1
	s_cselect_b32 s12, 0x460000, s12
	s_add_u32 s2, s24, s12
	s_addc_u32 s3, s25, 0
	v_cvt_pk_bf16_f32 v6, v5, v5
	v_lshlrev_b32_e32 v33, 16, v33
	global_store_short v2, v6, s[2:3]
	v_fmac_f32_e32 v33, v57, v5
	v_mov_b32_e32 v5, v33
	s_mov_b32 s12, 0x4e0000
	s_cmp_eq_u32 s6, 1
	s_cselect_b32 s12, 0x310000, s12
	s_add_u32 s2, s24, s12
	s_addc_u32 s3, s25, 0
	s_lshr_b32 s12, s12, 6
	s_add_u32 s4, s26, s12
	s_addc_u32 s5, s27, 0
	global_load_ushort v30, v2, s[2:3]
	global_load_dword v54, v3, s[4:5]
	s_waitcnt vmcnt(60)
	s_mov_b32 s12, 0x3a0000
	s_cmp_eq_u32 s6, 1
	s_cselect_b32 s12, 0x450000, s12
	s_add_u32 s2, s24, s12
	s_addc_u32 s3, s25, 0
	v_cvt_pk_bf16_f32 v6, v5, v5
	v_lshlrev_b32_e32 v34, 16, v34
	global_store_short v2, v6, s[2:3]
	v_fmac_f32_e32 v34, v58, v5
	v_mov_b32_e32 v5, v34
	s_mov_b32 s12, 0x4f0000
	s_cmp_eq_u32 s6, 1
	s_cselect_b32 s12, 0x300000, s12
	s_add_u32 s2, s24, s12
	s_addc_u32 s3, s25, 0
	s_lshr_b32 s12, s12, 6
	s_add_u32 s4, s26, s12
	s_addc_u32 s5, s27, 0
	global_load_ushort v31, v2, s[2:3]
	global_load_dword v55, v3, s[4:5]
	s_waitcnt vmcnt(60)
	s_mov_b32 s12, 0x3b0000
	s_cmp_eq_u32 s6, 1
	s_cselect_b32 s12, 0x440000, s12
	s_add_u32 s2, s24, s12
	s_addc_u32 s3, s25, 0
	v_cvt_pk_bf16_f32 v6, v5, v5
	v_lshlrev_b32_e32 v35, 16, v35
	global_store_short v2, v6, s[2:3]
	v_fmac_f32_e32 v35, v59, v5
	v_mov_b32_e32 v5, v35
	s_mov_b32 s12, 0x500000
	s_cmp_eq_u32 s6, 1
	s_cselect_b32 s12, 0x2f0000, s12
	s_add_u32 s2, s24, s12
	s_addc_u32 s3, s25, 0
	s_lshr_b32 s12, s12, 6
	s_add_u32 s4, s26, s12
	s_addc_u32 s5, s27, 0
	global_load_ushort v32, v2, s[2:3]
	global_load_dword v56, v3, s[4:5]
	s_waitcnt vmcnt(60)
	s_mov_b32 s12, 0x3c0000
	s_cmp_eq_u32 s6, 1
	s_cselect_b32 s12, 0x430000, s12
	s_add_u32 s2, s24, s12
	s_addc_u32 s3, s25, 0
	v_cvt_pk_bf16_f32 v6, v5, v5
	v_lshlrev_b32_e32 v36, 16, v36
	global_store_short v2, v6, s[2:3]
	v_fmac_f32_e32 v36, v60, v5
	v_mov_b32_e32 v5, v36
	s_mov_b32 s12, 0x510000
	s_cmp_eq_u32 s6, 1
	s_cselect_b32 s12, 0x2e0000, s12
	s_add_u32 s2, s24, s12
	s_addc_u32 s3, s25, 0
	s_lshr_b32 s12, s12, 6
	s_add_u32 s4, s26, s12
	s_addc_u32 s5, s27, 0
	global_load_ushort v33, v2, s[2:3]
	global_load_dword v57, v3, s[4:5]
	s_waitcnt vmcnt(60)
	s_mov_b32 s12, 0x3d0000
	s_cmp_eq_u32 s6, 1
	s_cselect_b32 s12, 0x420000, s12
	s_add_u32 s2, s24, s12
	s_addc_u32 s3, s25, 0
	v_cvt_pk_bf16_f32 v6, v5, v5
	v_lshlrev_b32_e32 v37, 16, v37
	global_store_short v2, v6, s[2:3]
	v_fmac_f32_e32 v37, v61, v5
	v_mov_b32_e32 v5, v37
	s_mov_b32 s12, 0x520000
	s_cmp_eq_u32 s6, 1
	s_cselect_b32 s12, 0x2d0000, s12
	s_add_u32 s2, s24, s12
	s_addc_u32 s3, s25, 0
	s_lshr_b32 s12, s12, 6
	s_add_u32 s4, s26, s12
	s_addc_u32 s5, s27, 0
	global_load_ushort v34, v2, s[2:3]
	global_load_dword v58, v3, s[4:5]
	s_waitcnt vmcnt(60)
	s_mov_b32 s12, 0x3e0000
	s_cmp_eq_u32 s6, 1
	s_cselect_b32 s12, 0x410000, s12
	s_add_u32 s2, s24, s12
	s_addc_u32 s3, s25, 0
	v_cvt_pk_bf16_f32 v6, v5, v5
	v_lshlrev_b32_e32 v38, 16, v38
	global_store_short v2, v6, s[2:3]
	v_fmac_f32_e32 v38, v62, v5
	v_mov_b32_e32 v5, v38
	s_mov_b32 s12, 0x530000
	s_cmp_eq_u32 s6, 1
	s_cselect_b32 s12, 0x2c0000, s12
	s_add_u32 s2, s24, s12
	s_addc_u32 s3, s25, 0
	s_lshr_b32 s12, s12, 6
	s_add_u32 s4, s26, s12
	s_addc_u32 s5, s27, 0
	global_load_ushort v35, v2, s[2:3]
	global_load_dword v59, v3, s[4:5]
	s_waitcnt vmcnt(60)
	s_mov_b32 s12, 0x3f0000
	s_cmp_eq_u32 s6, 1
	s_cselect_b32 s12, 0x400000, s12
	s_add_u32 s2, s24, s12
	s_addc_u32 s3, s25, 0
	v_cvt_pk_bf16_f32 v6, v5, v5
	v_lshlrev_b32_e32 v39, 16, v39
	global_store_short v2, v6, s[2:3]
	v_fmac_f32_e32 v39, v63, v5
	v_mov_b32_e32 v5, v39
	s_mov_b32 s12, 0x540000
	s_cmp_eq_u32 s6, 1
	s_cselect_b32 s12, 0x2b0000, s12
	s_add_u32 s2, s24, s12
	s_addc_u32 s3, s25, 0
	s_lshr_b32 s12, s12, 6
	s_add_u32 s4, s26, s12
	s_addc_u32 s5, s27, 0
	global_load_ushort v36, v2, s[2:3]
	global_load_dword v60, v3, s[4:5]
	s_waitcnt vmcnt(60)
	s_mov_b32 s12, 0x400000
	s_cmp_eq_u32 s6, 1
	s_cselect_b32 s12, 0x3f0000, s12
	s_add_u32 s2, s24, s12
	s_addc_u32 s3, s25, 0
	v_cvt_pk_bf16_f32 v6, v5, v5
	v_lshlrev_b32_e32 v40, 16, v40
	global_store_short v2, v6, s[2:3]
	v_fmac_f32_e32 v40, v64, v5
	v_mov_b32_e32 v5, v40
	s_mov_b32 s12, 0x550000
	s_cmp_eq_u32 s6, 1
	s_cselect_b32 s12, 0x2a0000, s12
	s_add_u32 s2, s24, s12
	s_addc_u32 s3, s25, 0
	s_lshr_b32 s12, s12, 6
	s_add_u32 s4, s26, s12
	s_addc_u32 s5, s27, 0
	global_load_ushort v37, v2, s[2:3]
	global_load_dword v61, v3, s[4:5]
	s_waitcnt vmcnt(60)
	s_mov_b32 s12, 0x410000
	s_cmp_eq_u32 s6, 1
	s_cselect_b32 s12, 0x3e0000, s12
	s_add_u32 s2, s24, s12
	s_addc_u32 s3, s25, 0
	v_cvt_pk_bf16_f32 v6, v5, v5
	v_lshlrev_b32_e32 v41, 16, v41
	global_store_short v2, v6, s[2:3]
	v_fmac_f32_e32 v41, v65, v5
	v_mov_b32_e32 v5, v41
	s_mov_b32 s12, 0x560000
	s_cmp_eq_u32 s6, 1
	s_cselect_b32 s12, 0x290000, s12
	s_add_u32 s2, s24, s12
	s_addc_u32 s3, s25, 0
	s_lshr_b32 s12, s12, 6
	s_add_u32 s4, s26, s12
	s_addc_u32 s5, s27, 0
	global_load_ushort v38, v2, s[2:3]
	global_load_dword v62, v3, s[4:5]
	s_waitcnt vmcnt(60)
; DI int otid() { int t = threadIdx.x; asm volatile("" : "+v"(t)); return t; }
; DI float bf2f(bf16 v) { return __uint_as_float(((unsigned)v) << 16); }
; DI bf16 f2bf(float f) { unsigned u = __float_as_uint(f); u += 0x7fffu + ((u >> 16) & 1u); return (bf16)(u >> 16); }
;   DI bf16* G() const { return (bf16*)(p.ws + WS_G); }
;   DI float* DEC() const { return (float*)(p.ws + WS_DEC); }
; DI void gla_g2(const Ctx& c) {
;   const int gt = blockIdx.x * NT + otid(), gs = gridDim.x * NT;
;   for (int i = gt; i < 16 * 8192; i += gs) {
;     const int e = i & 8191, kk = e & 63, q = i >> 13, h = q & 3, bd = q >> 2, dir = bd & 1;
;     float st = 0.f;
;     for (int c0 = 0; c0 < 132; c0 += 12) {
;       float dsv[12], dec[12]; bf16* pd[12];
; #pragma unroll
;       for (int j = 0; j < 12; ++j) {
;         const int ci = c0 + j;
;         const int cm = dir ? (131 - ci) : (ci < 4 ? 128 + ci : ci - 4);
;         const size_t sidx = (size_t)(bd * 132 + cm) * 4 + h;
;         pd[j] = c.G() + sidx * 8192 + e;
;         dsv[j] = bf2f(*pd[j]); dec[j] = c.DEC()[sidx * 64 + kk];
;       }
; #pragma unroll
;       for (int j = 0; j < 12; ++j) { *pd[j] = f2bf(st); st = dec[j] * st + dsv[j]; }
;     }
;   }
; }
	s_mov_b32 s12, 0x420000
	s_cmp_eq_u32 s6, 1
	s_cselect_b32 s12, 0x3d0000, s12
	s_add_u32 s2, s24, s12
	s_addc_u32 s3, s25, 0
	v_cvt_pk_bf16_f32 v6, v5, v5
	v_lshlrev_b32_e32 v42, 16, v42
	global_store_short v2, v6, s[2:3]
	v_fmac_f32_e32 v42, v66, v5
	v_mov_b32_e32 v5, v42
	s_mov_b32 s12, 0x570000
	s_cmp_eq_u32 s6, 1
	s_cselect_b32 s12, 0x280000, s12
	s_add_u32 s2, s24, s12
	s_addc_u32 s3, s25, 0
	s_lshr_b32 s12, s12, 6
	s_add_u32 s4, s26, s12
	s_addc_u32 s5, s27, 0
	global_load_ushort v39, v2, s[2:3]
	global_load_dword v63, v3, s[4:5]
	s_waitcnt vmcnt(60)
	s_mov_b32 s12, 0x430000
	s_cmp_eq_u32 s6, 1
	s_cselect_b32 s12, 0x3c0000, s12
	s_add_u32 s2, s24, s12
	s_addc_u32 s3, s25, 0
	v_cvt_pk_bf16_f32 v6, v5, v5
	v_lshlrev_b32_e32 v43, 16, v43
	global_store_short v2, v6, s[2:3]
	v_fmac_f32_e32 v43, v67, v5
	v_mov_b32_e32 v5, v43
	s_mov_b32 s12, 0x580000
	s_cmp_eq_u32 s6, 1
	s_cselect_b32 s12, 0x270000, s12
	s_add_u32 s2, s24, s12
	s_addc_u32 s3, s25, 0
	s_lshr_b32 s12, s12, 6
	s_add_u32 s4, s26, s12
	s_addc_u32 s5, s27, 0
	global_load_ushort v40, v2, s[2:3]
	global_load_dword v64, v3, s[4:5]
	s_waitcnt vmcnt(60)
	s_mov_b32 s12, 0x440000
	s_cmp_eq_u32 s6, 1
	s_cselect_b32 s12, 0x3b0000, s12
	s_add_u32 s2, s24, s12
	s_addc_u32 s3, s25, 0
	v_cvt_pk_bf16_f32 v6, v5, v5
	v_lshlrev_b32_e32 v20, 16, v20
	global_store_short v2, v6, s[2:3]
	v_fmac_f32_e32 v20, v44, v5
	v_mov_b32_e32 v5, v20
	s_mov_b32 s12, 0x590000
	s_cmp_eq_u32 s6, 1
	s_cselect_b32 s12, 0x260000, s12
	s_add_u32 s2, s24, s12
	s_addc_u32 s3, s25, 0
	s_lshr_b32 s12, s12, 6
	s_add_u32 s4, s26, s12
	s_addc_u32 s5, s27, 0
	global_load_ushort v41, v2, s[2:3]
	global_load_dword v65, v3, s[4:5]
	s_waitcnt vmcnt(60)
	s_mov_b32 s12, 0x450000
	s_cmp_eq_u32 s6, 1
	s_cselect_b32 s12, 0x3a0000, s12
	s_add_u32 s2, s24, s12
	s_addc_u32 s3, s25, 0
	v_cvt_pk_bf16_f32 v6, v5, v5
	v_lshlrev_b32_e32 v21, 16, v21
	global_store_short v2, v6, s[2:3]
	v_fmac_f32_e32 v21, v45, v5
	v_mov_b32_e32 v5, v21
	s_mov_b32 s12, 0x5a0000
	s_cmp_eq_u32 s6, 1
	s_cselect_b32 s12, 0x250000, s12
	s_add_u32 s2, s24, s12
	s_addc_u32 s3, s25, 0
	s_lshr_b32 s12, s12, 6
	s_add_u32 s4, s26, s12
	s_addc_u32 s5, s27, 0
	global_load_ushort v42, v2, s[2:3]
	global_load_dword v66, v3, s[4:5]
	s_waitcnt vmcnt(60)
	s_mov_b32 s12, 0x460000
	s_cmp_eq_u32 s6, 1
	s_cselect_b32 s12, 0x390000, s12
	s_add_u32 s2, s24, s12
	s_addc_u32 s3, s25, 0
	v_cvt_pk_bf16_f32 v6, v5, v5
	v_lshlrev_b32_e32 v22, 16, v22
	global_store_short v2, v6, s[2:3]
	v_fmac_f32_e32 v22, v46, v5
	v_mov_b32_e32 v5, v22
	s_mov_b32 s12, 0x5b0000
	s_cmp_eq_u32 s6, 1
	s_cselect_b32 s12, 0x240000, s12
	s_add_u32 s2, s24, s12
	s_addc_u32 s3, s25, 0
	s_lshr_b32 s12, s12, 6
	s_add_u32 s4, s26, s12
	s_addc_u32 s5, s27, 0
	global_load_ushort v43, v2, s[2:3]
	global_load_dword v67, v3, s[4:5]
	s_waitcnt vmcnt(60)
	s_mov_b32 s12, 0x470000
	s_cmp_eq_u32 s6, 1
	s_cselect_b32 s12, 0x380000, s12
	s_add_u32 s2, s24, s12
	s_addc_u32 s3, s25, 0
	v_cvt_pk_bf16_f32 v6, v5, v5
	v_lshlrev_b32_e32 v23, 16, v23
	global_store_short v2, v6, s[2:3]
	v_fmac_f32_e32 v23, v47, v5
	v_mov_b32_e32 v5, v23
	s_mov_b32 s12, 0x5c0000
	s_cmp_eq_u32 s6, 1
	s_cselect_b32 s12, 0x230000, s12
	s_add_u32 s2, s24, s12
	s_addc_u32 s3, s25, 0
	s_lshr_b32 s12, s12, 6
	s_add_u32 s4, s26, s12
	s_addc_u32 s5, s27, 0
	global_load_ushort v20, v2, s[2:3]
	global_load_dword v44, v3, s[4:5]
	s_waitcnt vmcnt(60)
	s_mov_b32 s12, 0x480000
	s_cmp_eq_u32 s6, 1
	s_cselect_b32 s12, 0x370000, s12
	s_add_u32 s2, s24, s12
	s_addc_u32 s3, s25, 0
	v_cvt_pk_bf16_f32 v6, v5, v5
	v_lshlrev_b32_e32 v24, 16, v24
	global_store_short v2, v6, s[2:3]
	v_fmac_f32_e32 v24, v48, v5
	v_mov_b32_e32 v5, v24
	s_mov_b32 s12, 0x5d0000
	s_cmp_eq_u32 s6, 1
	s_cselect_b32 s12, 0x220000, s12
	s_add_u32 s2, s24, s12
	s_addc_u32 s3, s25, 0
	s_lshr_b32 s12, s12, 6
	s_add_u32 s4, s26, s12
	s_addc_u32 s5, s27, 0
	global_load_ushort v21, v2, s[2:3]
	global_load_dword v45, v3, s[4:5]
	s_waitcnt vmcnt(60)
	s_mov_b32 s12, 0x490000
	s_cmp_eq_u32 s6, 1
	s_cselect_b32 s12, 0x360000, s12
	s_add_u32 s2, s24, s12
	s_addc_u32 s3, s25, 0
	v_cvt_pk_bf16_f32 v6, v5, v5
	v_lshlrev_b32_e32 v25, 16, v25
	global_store_short v2, v6, s[2:3]
	v_fmac_f32_e32 v25, v49, v5
	v_mov_b32_e32 v5, v25
	s_mov_b32 s12, 0x5e0000
	s_cmp_eq_u32 s6, 1
	s_cselect_b32 s12, 0x210000, s12
	s_add_u32 s2, s24, s12
	s_addc_u32 s3, s25, 0
	s_lshr_b32 s12, s12, 6
	s_add_u32 s4, s26, s12
	s_addc_u32 s5, s27, 0
	global_load_ushort v22, v2, s[2:3]
	global_load_dword v46, v3, s[4:5]
	s_waitcnt vmcnt(60)
	s_mov_b32 s12, 0x4a0000
	s_cmp_eq_u32 s6, 1
	s_cselect_b32 s12, 0x350000, s12
	s_add_u32 s2, s24, s12
	s_addc_u32 s3, s25, 0
	v_cvt_pk_bf16_f32 v6, v5, v5
	v_lshlrev_b32_e32 v26, 16, v26
	global_store_short v2, v6, s[2:3]
	v_fmac_f32_e32 v26, v50, v5
	v_mov_b32_e32 v5, v26
	s_mov_b32 s12, 0x5f0000
	s_cmp_eq_u32 s6, 1
	s_cselect_b32 s12, 0x200000, s12
	s_add_u32 s2, s24, s12
	s_addc_u32 s3, s25, 0
	s_lshr_b32 s12, s12, 6
	s_add_u32 s4, s26, s12
	s_addc_u32 s5, s27, 0
	global_load_ushort v23, v2, s[2:3]
	global_load_dword v47, v3, s[4:5]
	s_waitcnt vmcnt(60)
	s_mov_b32 s12, 0x4b0000
	s_cmp_eq_u32 s6, 1
	s_cselect_b32 s12, 0x340000, s12
	s_add_u32 s2, s24, s12
	s_addc_u32 s3, s25, 0
	v_cvt_pk_bf16_f32 v6, v5, v5
	v_lshlrev_b32_e32 v27, 16, v27
	global_store_short v2, v6, s[2:3]
	v_fmac_f32_e32 v27, v51, v5
	v_mov_b32_e32 v5, v27
	s_mov_b32 s12, 0x600000
	s_cmp_eq_u32 s6, 1
	s_cselect_b32 s12, 0x1f0000, s12
	s_add_u32 s2, s24, s12
	s_addc_u32 s3, s25, 0
	s_lshr_b32 s12, s12, 6
	s_add_u32 s4, s26, s12
	s_addc_u32 s5, s27, 0
	global_load_ushort v24, v2, s[2:3]
	global_load_dword v48, v3, s[4:5]
	s_waitcnt vmcnt(60)
; DI int otid() { int t = threadIdx.x; asm volatile("" : "+v"(t)); return t; }
; DI float bf2f(bf16 v) { return __uint_as_float(((unsigned)v) << 16); }
; DI bf16 f2bf(float f) { unsigned u = __float_as_uint(f); u += 0x7fffu + ((u >> 16) & 1u); return (bf16)(u >> 16); }
;   DI bf16* G() const { return (bf16*)(p.ws + WS_G); }
;   DI float* DEC() const { return (float*)(p.ws + WS_DEC); }
; DI void gla_g2(const Ctx& c) {
;   const int gt = blockIdx.x * NT + otid(), gs = gridDim.x * NT;
;   for (int i = gt; i < 16 * 8192; i += gs) {
;     const int e = i & 8191, kk = e & 63, q = i >> 13, h = q & 3, bd = q >> 2, dir = bd & 1;
;     float st = 0.f;
;     for (int c0 = 0; c0 < 132; c0 += 12) {
;       float dsv[12], dec[12]; bf16* pd[12];
; #pragma unroll
;       for (int j = 0; j < 12; ++j) {
;         const int ci = c0 + j;
;         const int cm = dir ? (131 - ci) : (ci < 4 ? 128 + ci : ci - 4);
;         const size_t sidx = (size_t)(bd * 132 + cm) * 4 + h;
;         pd[j] = c.G() + sidx * 8192 + e;
;         dsv[j] = bf2f(*pd[j]); dec[j] = c.DEC()[sidx * 64 + kk];
;       }
; #pragma unroll
;       for (int j = 0; j < 12; ++j) { *pd[j] = f2bf(st); st = dec[j] * st + dsv[j]; }
;     }
;   }
; }
	s_mov_b32 s12, 0x4c0000
	s_cmp_eq_u32 s6, 1
	s_cselect_b32 s12, 0x330000, s12
	s_add_u32 s2, s24, s12
	s_addc_u32 s3, s25, 0
	v_cvt_pk_bf16_f32 v6, v5, v5
	v_lshlrev_b32_e32 v28, 16, v28
	global_store_short v2, v6, s[2:3]
	v_fmac_f32_e32 v28, v52, v5
	v_mov_b32_e32 v5, v28
	s_mov_b32 s12, 0x610000
	s_cmp_eq_u32 s6, 1
	s_cselect_b32 s12, 0x1e0000, s12
	s_add_u32 s2, s24, s12
	s_addc_u32 s3, s25, 0
	s_lshr_b32 s12, s12, 6
	s_add_u32 s4, s26, s12
	s_addc_u32 s5, s27, 0
	global_load_ushort v25, v2, s[2:3]
	global_load_dword v49, v3, s[4:5]
	s_waitcnt vmcnt(60)
	s_mov_b32 s12, 0x4d0000
	s_cmp_eq_u32 s6, 1
	s_cselect_b32 s12, 0x320000, s12
	s_add_u32 s2, s24, s12
	s_addc_u32 s3, s25, 0
	v_cvt_pk_bf16_f32 v6, v5, v5
	v_lshlrev_b32_e32 v29, 16, v29
	global_store_short v2, v6, s[2:3]
	v_fmac_f32_e32 v29, v53, v5
	v_mov_b32_e32 v5, v29
	s_mov_b32 s12, 0x620000
	s_cmp_eq_u32 s6, 1
	s_cselect_b32 s12, 0x1d0000, s12
	s_add_u32 s2, s24, s12
	s_addc_u32 s3, s25, 0
	s_lshr_b32 s12, s12, 6
	s_add_u32 s4, s26, s12
	s_addc_u32 s5, s27, 0
	global_load_ushort v26, v2, s[2:3]
	global_load_dword v50, v3, s[4:5]
	s_waitcnt vmcnt(60)
	s_mov_b32 s12, 0x4e0000
	s_cmp_eq_u32 s6, 1
	s_cselect_b32 s12, 0x310000, s12
	s_add_u32 s2, s24, s12
	s_addc_u32 s3, s25, 0
	v_cvt_pk_bf16_f32 v6, v5, v5
	v_lshlrev_b32_e32 v30, 16, v30
	global_store_short v2, v6, s[2:3]
	v_fmac_f32_e32 v30, v54, v5
	v_mov_b32_e32 v5, v30
	s_mov_b32 s12, 0x630000
	s_cmp_eq_u32 s6, 1
	s_cselect_b32 s12, 0x1c0000, s12
	s_add_u32 s2, s24, s12
	s_addc_u32 s3, s25, 0
	s_lshr_b32 s12, s12, 6
	s_add_u32 s4, s26, s12
	s_addc_u32 s5, s27, 0
	global_load_ushort v27, v2, s[2:3]
	global_load_dword v51, v3, s[4:5]
	s_waitcnt vmcnt(60)
	s_mov_b32 s12, 0x4f0000
	s_cmp_eq_u32 s6, 1
	s_cselect_b32 s12, 0x300000, s12
	s_add_u32 s2, s24, s12
	s_addc_u32 s3, s25, 0
	v_cvt_pk_bf16_f32 v6, v5, v5
	v_lshlrev_b32_e32 v31, 16, v31
	global_store_short v2, v6, s[2:3]
	v_fmac_f32_e32 v31, v55, v5
	v_mov_b32_e32 v5, v31
	s_mov_b32 s12, 0x640000
	s_cmp_eq_u32 s6, 1
	s_cselect_b32 s12, 0x1b0000, s12
	s_add_u32 s2, s24, s12
	s_addc_u32 s3, s25, 0
	s_lshr_b32 s12, s12, 6
	s_add_u32 s4, s26, s12
	s_addc_u32 s5, s27, 0
	global_load_ushort v28, v2, s[2:3]
	global_load_dword v52, v3, s[4:5]
	s_waitcnt vmcnt(60)
	s_mov_b32 s12, 0x500000
	s_cmp_eq_u32 s6, 1
	s_cselect_b32 s12, 0x2f0000, s12
	s_add_u32 s2, s24, s12
	s_addc_u32 s3, s25, 0
	v_cvt_pk_bf16_f32 v6, v5, v5
	v_lshlrev_b32_e32 v32, 16, v32
	global_store_short v2, v6, s[2:3]
	v_fmac_f32_e32 v32, v56, v5
	v_mov_b32_e32 v5, v32
	s_mov_b32 s12, 0x650000
	s_cmp_eq_u32 s6, 1
	s_cselect_b32 s12, 0x1a0000, s12
	s_add_u32 s2, s24, s12
	s_addc_u32 s3, s25, 0
	s_lshr_b32 s12, s12, 6
	s_add_u32 s4, s26, s12
	s_addc_u32 s5, s27, 0
	global_load_ushort v29, v2, s[2:3]
	global_load_dword v53, v3, s[4:5]
	s_waitcnt vmcnt(60)
	s_mov_b32 s12, 0x510000
	s_cmp_eq_u32 s6, 1
	s_cselect_b32 s12, 0x2e0000, s12
	s_add_u32 s2, s24, s12
	s_addc_u32 s3, s25, 0
	v_cvt_pk_bf16_f32 v6, v5, v5
	v_lshlrev_b32_e32 v33, 16, v33
	global_store_short v2, v6, s[2:3]
	v_fmac_f32_e32 v33, v57, v5
	v_mov_b32_e32 v5, v33
	s_mov_b32 s12, 0x660000
	s_cmp_eq_u32 s6, 1
	s_cselect_b32 s12, 0x190000, s12
	s_add_u32 s2, s24, s12
	s_addc_u32 s3, s25, 0
	s_lshr_b32 s12, s12, 6
	s_add_u32 s4, s26, s12
	s_addc_u32 s5, s27, 0
	global_load_ushort v30, v2, s[2:3]
	global_load_dword v54, v3, s[4:5]
	s_waitcnt vmcnt(60)
	s_mov_b32 s12, 0x520000
	s_cmp_eq_u32 s6, 1
	s_cselect_b32 s12, 0x2d0000, s12
	s_add_u32 s2, s24, s12
	s_addc_u32 s3, s25, 0
	v_cvt_pk_bf16_f32 v6, v5, v5
	v_lshlrev_b32_e32 v34, 16, v34
	global_store_short v2, v6, s[2:3]
	v_fmac_f32_e32 v34, v58, v5
	v_mov_b32_e32 v5, v34
	s_mov_b32 s12, 0x670000
	s_cmp_eq_u32 s6, 1
	s_cselect_b32 s12, 0x180000, s12
	s_add_u32 s2, s24, s12
	s_addc_u32 s3, s25, 0
	s_lshr_b32 s12, s12, 6
	s_add_u32 s4, s26, s12
	s_addc_u32 s5, s27, 0
	global_load_ushort v31, v2, s[2:3]
	global_load_dword v55, v3, s[4:5]
	s_waitcnt vmcnt(60)
	s_mov_b32 s12, 0x530000
	s_cmp_eq_u32 s6, 1
	s_cselect_b32 s12, 0x2c0000, s12
	s_add_u32 s2, s24, s12
	s_addc_u32 s3, s25, 0
	v_cvt_pk_bf16_f32 v6, v5, v5
	v_lshlrev_b32_e32 v35, 16, v35
	global_store_short v2, v6, s[2:3]
	v_fmac_f32_e32 v35, v59, v5
	v_mov_b32_e32 v5, v35
	s_mov_b32 s12, 0x680000
	s_cmp_eq_u32 s6, 1
	s_cselect_b32 s12, 0x170000, s12
	s_add_u32 s2, s24, s12
	s_addc_u32 s3, s25, 0
	s_lshr_b32 s12, s12, 6
	s_add_u32 s4, s26, s12
	s_addc_u32 s5, s27, 0
	global_load_ushort v32, v2, s[2:3]
	global_load_dword v56, v3, s[4:5]
	s_waitcnt vmcnt(60)
	s_mov_b32 s12, 0x540000
	s_cmp_eq_u32 s6, 1
	s_cselect_b32 s12, 0x2b0000, s12
	s_add_u32 s2, s24, s12
	s_addc_u32 s3, s25, 0
	v_cvt_pk_bf16_f32 v6, v5, v5
	v_lshlrev_b32_e32 v36, 16, v36
	global_store_short v2, v6, s[2:3]
	v_fmac_f32_e32 v36, v60, v5
	v_mov_b32_e32 v5, v36
	s_mov_b32 s12, 0x690000
	s_cmp_eq_u32 s6, 1
	s_cselect_b32 s12, 0x160000, s12
	s_add_u32 s2, s24, s12
	s_addc_u32 s3, s25, 0
	s_lshr_b32 s12, s12, 6
	s_add_u32 s4, s26, s12
	s_addc_u32 s5, s27, 0
	global_load_ushort v33, v2, s[2:3]
	global_load_dword v57, v3, s[4:5]
	s_waitcnt vmcnt(60)
	s_mov_b32 s12, 0x550000
	s_cmp_eq_u32 s6, 1
	s_cselect_b32 s12, 0x2a0000, s12
	s_add_u32 s2, s24, s12
	s_addc_u32 s3, s25, 0
	v_cvt_pk_bf16_f32 v6, v5, v5
	v_lshlrev_b32_e32 v37, 16, v37
	global_store_short v2, v6, s[2:3]
	v_fmac_f32_e32 v37, v61, v5
	v_mov_b32_e32 v5, v37
	s_mov_b32 s12, 0x6a0000
	s_cmp_eq_u32 s6, 1
	s_cselect_b32 s12, 0x150000, s12
	s_add_u32 s2, s24, s12
	s_addc_u32 s3, s25, 0
	s_lshr_b32 s12, s12, 6
	s_add_u32 s4, s26, s12
	s_addc_u32 s5, s27, 0
	global_load_ushort v34, v2, s[2:3]
	global_load_dword v58, v3, s[4:5]
	s_waitcnt vmcnt(60)
; DI int otid() { int t = threadIdx.x; asm volatile("" : "+v"(t)); return t; }
; DI float bf2f(bf16 v) { return __uint_as_float(((unsigned)v) << 16); }
; DI bf16 f2bf(float f) { unsigned u = __float_as_uint(f); u += 0x7fffu + ((u >> 16) & 1u); return (bf16)(u >> 16); }
;   DI bf16* G() const { return (bf16*)(p.ws + WS_G); }
;   DI float* DEC() const { return (float*)(p.ws + WS_DEC); }
; DI void gla_g2(const Ctx& c) {
;   const int gt = blockIdx.x * NT + otid(), gs = gridDim.x * NT;
;   for (int i = gt; i < 16 * 8192; i += gs) {
;     const int e = i & 8191, kk = e & 63, q = i >> 13, h = q & 3, bd = q >> 2, dir = bd & 1;
;     float st = 0.f;
;     for (int c0 = 0; c0 < 132; c0 += 12) {
;       float dsv[12], dec[12]; bf16* pd[12];
; #pragma unroll
;       for (int j = 0; j < 12; ++j) {
;         const int ci = c0 + j;
;         const int cm = dir ? (131 - ci) : (ci < 4 ? 128 + ci : ci - 4);
;         const size_t sidx = (size_t)(bd * 132 + cm) * 4 + h;
;         pd[j] = c.G() + sidx * 8192 + e;
;         dsv[j] = bf2f(*pd[j]); dec[j] = c.DEC()[sidx * 64 + kk];
;       }
; #pragma unroll
;       for (int j = 0; j < 12; ++j) { *pd[j] = f2bf(st); st = dec[j] * st + dsv[j]; }
;     }
;   }
; }
	s_mov_b32 s12, 0x560000
	s_cmp_eq_u32 s6, 1
	s_cselect_b32 s12, 0x290000, s12
	s_add_u32 s2, s24, s12
	s_addc_u32 s3, s25, 0
	v_cvt_pk_bf16_f32 v6, v5, v5
	v_lshlrev_b32_e32 v38, 16, v38
	global_store_short v2, v6, s[2:3]
	v_fmac_f32_e32 v38, v62, v5
	v_mov_b32_e32 v5, v38
	s_mov_b32 s12, 0x6b0000
	s_cmp_eq_u32 s6, 1
	s_cselect_b32 s12, 0x140000, s12
	s_add_u32 s2, s24, s12
	s_addc_u32 s3, s25, 0
	s_lshr_b32 s12, s12, 6
	s_add_u32 s4, s26, s12
	s_addc_u32 s5, s27, 0
	global_load_ushort v35, v2, s[2:3]
	global_load_dword v59, v3, s[4:5]
	s_waitcnt vmcnt(60)
	s_mov_b32 s12, 0x570000
	s_cmp_eq_u32 s6, 1
	s_cselect_b32 s12, 0x280000, s12
	s_add_u32 s2, s24, s12
	s_addc_u32 s3, s25, 0
	v_cvt_pk_bf16_f32 v6, v5, v5
	v_lshlrev_b32_e32 v39, 16, v39
	global_store_short v2, v6, s[2:3]
	v_fmac_f32_e32 v39, v63, v5
	v_mov_b32_e32 v5, v39
	s_mov_b32 s12, 0x6c0000
	s_cmp_eq_u32 s6, 1
	s_cselect_b32 s12, 0x130000, s12
	s_add_u32 s2, s24, s12
	s_addc_u32 s3, s25, 0
	s_lshr_b32 s12, s12, 6
	s_add_u32 s4, s26, s12
	s_addc_u32 s5, s27, 0
	global_load_ushort v36, v2, s[2:3]
	global_load_dword v60, v3, s[4:5]
	s_waitcnt vmcnt(60)
	s_mov_b32 s12, 0x580000
	s_cmp_eq_u32 s6, 1
	s_cselect_b32 s12, 0x270000, s12
	s_add_u32 s2, s24, s12
	s_addc_u32 s3, s25, 0
	v_cvt_pk_bf16_f32 v6, v5, v5
	v_lshlrev_b32_e32 v40, 16, v40
	global_store_short v2, v6, s[2:3]
	v_fmac_f32_e32 v40, v64, v5
	v_mov_b32_e32 v5, v40
	s_mov_b32 s12, 0x6d0000
	s_cmp_eq_u32 s6, 1
	s_cselect_b32 s12, 0x120000, s12
	s_add_u32 s2, s24, s12
	s_addc_u32 s3, s25, 0
	s_lshr_b32 s12, s12, 6
	s_add_u32 s4, s26, s12
	s_addc_u32 s5, s27, 0
	global_load_ushort v37, v2, s[2:3]
	global_load_dword v61, v3, s[4:5]
	s_waitcnt vmcnt(60)
	s_mov_b32 s12, 0x590000
	s_cmp_eq_u32 s6, 1
	s_cselect_b32 s12, 0x260000, s12
	s_add_u32 s2, s24, s12
	s_addc_u32 s3, s25, 0
	v_cvt_pk_bf16_f32 v6, v5, v5
	v_lshlrev_b32_e32 v41, 16, v41
	global_store_short v2, v6, s[2:3]
	v_fmac_f32_e32 v41, v65, v5
	v_mov_b32_e32 v5, v41
	s_mov_b32 s12, 0x6e0000
	s_cmp_eq_u32 s6, 1
	s_cselect_b32 s12, 0x110000, s12
	s_add_u32 s2, s24, s12
	s_addc_u32 s3, s25, 0
	s_lshr_b32 s12, s12, 6
	s_add_u32 s4, s26, s12
	s_addc_u32 s5, s27, 0
	global_load_ushort v38, v2, s[2:3]
	global_load_dword v62, v3, s[4:5]
	s_waitcnt vmcnt(60)
	s_mov_b32 s12, 0x5a0000
	s_cmp_eq_u32 s6, 1
	s_cselect_b32 s12, 0x250000, s12
	s_add_u32 s2, s24, s12
	s_addc_u32 s3, s25, 0
	v_cvt_pk_bf16_f32 v6, v5, v5
	v_lshlrev_b32_e32 v42, 16, v42
	global_store_short v2, v6, s[2:3]
	v_fmac_f32_e32 v42, v66, v5
	v_mov_b32_e32 v5, v42
	s_mov_b32 s12, 0x6f0000
	s_cmp_eq_u32 s6, 1
	s_cselect_b32 s12, 0x100000, s12
	s_add_u32 s2, s24, s12
	s_addc_u32 s3, s25, 0
	s_lshr_b32 s12, s12, 6
	s_add_u32 s4, s26, s12
	s_addc_u32 s5, s27, 0
	global_load_ushort v39, v2, s[2:3]
	global_load_dword v63, v3, s[4:5]
	s_waitcnt vmcnt(60)
	s_mov_b32 s12, 0x5b0000
	s_cmp_eq_u32 s6, 1
	s_cselect_b32 s12, 0x240000, s12
	s_add_u32 s2, s24, s12
	s_addc_u32 s3, s25, 0
	v_cvt_pk_bf16_f32 v6, v5, v5
	v_lshlrev_b32_e32 v43, 16, v43
	global_store_short v2, v6, s[2:3]
	v_fmac_f32_e32 v43, v67, v5
	v_mov_b32_e32 v5, v43
	s_mov_b32 s12, 0x700000
	s_cmp_eq_u32 s6, 1
	s_cselect_b32 s12, 0xf0000, s12
	s_add_u32 s2, s24, s12
	s_addc_u32 s3, s25, 0
	s_lshr_b32 s12, s12, 6
	s_add_u32 s4, s26, s12
	s_addc_u32 s5, s27, 0
	global_load_ushort v40, v2, s[2:3]
	global_load_dword v64, v3, s[4:5]
	s_waitcnt vmcnt(60)
	s_mov_b32 s12, 0x5c0000
	s_cmp_eq_u32 s6, 1
	s_cselect_b32 s12, 0x230000, s12
	s_add_u32 s2, s24, s12
	s_addc_u32 s3, s25, 0
	v_cvt_pk_bf16_f32 v6, v5, v5
	v_lshlrev_b32_e32 v20, 16, v20
	global_store_short v2, v6, s[2:3]
	v_fmac_f32_e32 v20, v44, v5
	v_mov_b32_e32 v5, v20
	s_mov_b32 s12, 0x710000
	s_cmp_eq_u32 s6, 1
	s_cselect_b32 s12, 0xe0000, s12
	s_add_u32 s2, s24, s12
	s_addc_u32 s3, s25, 0
	s_lshr_b32 s12, s12, 6
	s_add_u32 s4, s26, s12
	s_addc_u32 s5, s27, 0
	global_load_ushort v41, v2, s[2:3]
	global_load_dword v65, v3, s[4:5]
	s_waitcnt vmcnt(60)
	s_mov_b32 s12, 0x5d0000
	s_cmp_eq_u32 s6, 1
	s_cselect_b32 s12, 0x220000, s12
	s_add_u32 s2, s24, s12
	s_addc_u32 s3, s25, 0
	v_cvt_pk_bf16_f32 v6, v5, v5
	v_lshlrev_b32_e32 v21, 16, v21
	global_store_short v2, v6, s[2:3]
	v_fmac_f32_e32 v21, v45, v5
	v_mov_b32_e32 v5, v21
	s_mov_b32 s12, 0x720000
	s_cmp_eq_u32 s6, 1
	s_cselect_b32 s12, 0xd0000, s12
	s_add_u32 s2, s24, s12
	s_addc_u32 s3, s25, 0
	s_lshr_b32 s12, s12, 6
	s_add_u32 s4, s26, s12
	s_addc_u32 s5, s27, 0
	global_load_ushort v42, v2, s[2:3]
	global_load_dword v66, v3, s[4:5]
	s_waitcnt vmcnt(60)
	s_mov_b32 s12, 0x5e0000
	s_cmp_eq_u32 s6, 1
	s_cselect_b32 s12, 0x210000, s12
	s_add_u32 s2, s24, s12
	s_addc_u32 s3, s25, 0
	v_cvt_pk_bf16_f32 v6, v5, v5
	v_lshlrev_b32_e32 v22, 16, v22
	global_store_short v2, v6, s[2:3]
	v_fmac_f32_e32 v22, v46, v5
	v_mov_b32_e32 v5, v22
	s_mov_b32 s12, 0x730000
	s_cmp_eq_u32 s6, 1
	s_cselect_b32 s12, 0xc0000, s12
	s_add_u32 s2, s24, s12
	s_addc_u32 s3, s25, 0
	s_lshr_b32 s12, s12, 6
	s_add_u32 s4, s26, s12
	s_addc_u32 s5, s27, 0
	global_load_ushort v43, v2, s[2:3]
	global_load_dword v67, v3, s[4:5]
	s_waitcnt vmcnt(60)
	s_mov_b32 s12, 0x5f0000
	s_cmp_eq_u32 s6, 1
	s_cselect_b32 s12, 0x200000, s12
	s_add_u32 s2, s24, s12
	s_addc_u32 s3, s25, 0
	v_cvt_pk_bf16_f32 v6, v5, v5
	v_lshlrev_b32_e32 v23, 16, v23
	global_store_short v2, v6, s[2:3]
	v_fmac_f32_e32 v23, v47, v5
	v_mov_b32_e32 v5, v23
	s_mov_b32 s12, 0x740000
	s_cmp_eq_u32 s6, 1
	s_cselect_b32 s12, 0xb0000, s12
	s_add_u32 s2, s24, s12
	s_addc_u32 s3, s25, 0
	s_lshr_b32 s12, s12, 6
	s_add_u32 s4, s26, s12
	s_addc_u32 s5, s27, 0
	global_load_ushort v20, v2, s[2:3]
	global_load_dword v44, v3, s[4:5]
	s_waitcnt vmcnt(60)
; DI int otid() { int t = threadIdx.x; asm volatile("" : "+v"(t)); return t; }
; DI float bf2f(bf16 v) { return __uint_as_float(((unsigned)v) << 16); }
; DI bf16 f2bf(float f) { unsigned u = __float_as_uint(f); u += 0x7fffu + ((u >> 16) & 1u); return (bf16)(u >> 16); }
;   DI bf16* G() const { return (bf16*)(p.ws + WS_G); }
;   DI float* DEC() const { return (float*)(p.ws + WS_DEC); }
; DI void gla_g2(const Ctx& c) {
;   const int gt = blockIdx.x * NT + otid(), gs = gridDim.x * NT;
;   for (int i = gt; i < 16 * 8192; i += gs) {
;     const int e = i & 8191, kk = e & 63, q = i >> 13, h = q & 3, bd = q >> 2, dir = bd & 1;
;     float st = 0.f;
;     for (int c0 = 0; c0 < 132; c0 += 12) {
;       float dsv[12], dec[12]; bf16* pd[12];
; #pragma unroll
;       for (int j = 0; j < 12; ++j) {
;         const int ci = c0 + j;
;         const int cm = dir ? (131 - ci) : (ci < 4 ? 128 + ci : ci - 4);
;         const size_t sidx = (size_t)(bd * 132 + cm) * 4 + h;
;         pd[j] = c.G() + sidx * 8192 + e;
;         dsv[j] = bf2f(*pd[j]); dec[j] = c.DEC()[sidx * 64 + kk];
;       }
; #pragma unroll
;       for (int j = 0; j < 12; ++j) { *pd[j] = f2bf(st); st = dec[j] * st + dsv[j]; }
;     }
;   }
; }
	s_mov_b32 s12, 0x600000
	s_cmp_eq_u32 s6, 1
	s_cselect_b32 s12, 0x1f0000, s12
	s_add_u32 s2, s24, s12
	s_addc_u32 s3, s25, 0
	v_cvt_pk_bf16_f32 v6, v5, v5
	v_lshlrev_b32_e32 v24, 16, v24
	global_store_short v2, v6, s[2:3]
	v_fmac_f32_e32 v24, v48, v5
	v_mov_b32_e32 v5, v24
	s_mov_b32 s12, 0x750000
	s_cmp_eq_u32 s6, 1
	s_cselect_b32 s12, 0xa0000, s12
	s_add_u32 s2, s24, s12
	s_addc_u32 s3, s25, 0
	s_lshr_b32 s12, s12, 6
	s_add_u32 s4, s26, s12
	s_addc_u32 s5, s27, 0
	global_load_ushort v21, v2, s[2:3]
	global_load_dword v45, v3, s[4:5]
	s_waitcnt vmcnt(60)
	s_mov_b32 s12, 0x610000
	s_cmp_eq_u32 s6, 1
	s_cselect_b32 s12, 0x1e0000, s12
	s_add_u32 s2, s24, s12
	s_addc_u32 s3, s25, 0
	v_cvt_pk_bf16_f32 v6, v5, v5
	v_lshlrev_b32_e32 v25, 16, v25
	global_store_short v2, v6, s[2:3]
	v_fmac_f32_e32 v25, v49, v5
	v_mov_b32_e32 v5, v25
	s_mov_b32 s12, 0x760000
	s_cmp_eq_u32 s6, 1
	s_cselect_b32 s12, 0x90000, s12
	s_add_u32 s2, s24, s12
	s_addc_u32 s3, s25, 0
	s_lshr_b32 s12, s12, 6
	s_add_u32 s4, s26, s12
	s_addc_u32 s5, s27, 0
	global_load_ushort v22, v2, s[2:3]
	global_load_dword v46, v3, s[4:5]
	s_waitcnt vmcnt(60)
	s_mov_b32 s12, 0x620000
	s_cmp_eq_u32 s6, 1
	s_cselect_b32 s12, 0x1d0000, s12
	s_add_u32 s2, s24, s12
	s_addc_u32 s3, s25, 0
	v_cvt_pk_bf16_f32 v6, v5, v5
	v_lshlrev_b32_e32 v26, 16, v26
	global_store_short v2, v6, s[2:3]
	v_fmac_f32_e32 v26, v50, v5
	v_mov_b32_e32 v5, v26
	s_mov_b32 s12, 0x770000
	s_cmp_eq_u32 s6, 1
	s_cselect_b32 s12, 0x80000, s12
	s_add_u32 s2, s24, s12
	s_addc_u32 s3, s25, 0
	s_lshr_b32 s12, s12, 6
	s_add_u32 s4, s26, s12
	s_addc_u32 s5, s27, 0
	global_load_ushort v23, v2, s[2:3]
	global_load_dword v47, v3, s[4:5]
	s_waitcnt vmcnt(60)
	s_mov_b32 s12, 0x630000
	s_cmp_eq_u32 s6, 1
	s_cselect_b32 s12, 0x1c0000, s12
	s_add_u32 s2, s24, s12
	s_addc_u32 s3, s25, 0
	v_cvt_pk_bf16_f32 v6, v5, v5
	v_lshlrev_b32_e32 v27, 16, v27
	global_store_short v2, v6, s[2:3]
	v_fmac_f32_e32 v27, v51, v5
	v_mov_b32_e32 v5, v27
	s_mov_b32 s12, 0x780000
	s_cmp_eq_u32 s6, 1
	s_cselect_b32 s12, 0x70000, s12
	s_add_u32 s2, s24, s12
	s_addc_u32 s3, s25, 0
	s_lshr_b32 s12, s12, 6
	s_add_u32 s4, s26, s12
	s_addc_u32 s5, s27, 0
	global_load_ushort v24, v2, s[2:3]
	global_load_dword v48, v3, s[4:5]
	s_waitcnt vmcnt(60)
	s_mov_b32 s12, 0x640000
	s_cmp_eq_u32 s6, 1
	s_cselect_b32 s12, 0x1b0000, s12
	s_add_u32 s2, s24, s12
	s_addc_u32 s3, s25, 0
	v_cvt_pk_bf16_f32 v6, v5, v5
	v_lshlrev_b32_e32 v28, 16, v28
	global_store_short v2, v6, s[2:3]
	v_fmac_f32_e32 v28, v52, v5
	v_mov_b32_e32 v5, v28
	s_mov_b32 s12, 0x790000
	s_cmp_eq_u32 s6, 1
	s_cselect_b32 s12, 0x60000, s12
	s_add_u32 s2, s24, s12
	s_addc_u32 s3, s25, 0
	s_lshr_b32 s12, s12, 6
	s_add_u32 s4, s26, s12
	s_addc_u32 s5, s27, 0
	global_load_ushort v25, v2, s[2:3]
	global_load_dword v49, v3, s[4:5]
	s_waitcnt vmcnt(60)
	s_mov_b32 s12, 0x650000
	s_cmp_eq_u32 s6, 1
	s_cselect_b32 s12, 0x1a0000, s12
	s_add_u32 s2, s24, s12
	s_addc_u32 s3, s25, 0
	v_cvt_pk_bf16_f32 v6, v5, v5
	v_lshlrev_b32_e32 v29, 16, v29
	global_store_short v2, v6, s[2:3]
	v_fmac_f32_e32 v29, v53, v5
	v_mov_b32_e32 v5, v29
	s_mov_b32 s12, 0x7a0000
	s_cmp_eq_u32 s6, 1
	s_cselect_b32 s12, 0x50000, s12
	s_add_u32 s2, s24, s12
	s_addc_u32 s3, s25, 0
	s_lshr_b32 s12, s12, 6
	s_add_u32 s4, s26, s12
	s_addc_u32 s5, s27, 0
	global_load_ushort v26, v2, s[2:3]
	global_load_dword v50, v3, s[4:5]
	s_waitcnt vmcnt(60)
	s_mov_b32 s12, 0x660000
	s_cmp_eq_u32 s6, 1
	s_cselect_b32 s12, 0x190000, s12
	s_add_u32 s2, s24, s12
	s_addc_u32 s3, s25, 0
	v_cvt_pk_bf16_f32 v6, v5, v5
	v_lshlrev_b32_e32 v30, 16, v30
	global_store_short v2, v6, s[2:3]
	v_fmac_f32_e32 v30, v54, v5
	v_mov_b32_e32 v5, v30
	s_mov_b32 s12, 0x7b0000
	s_cmp_eq_u32 s6, 1
	s_cselect_b32 s12, 0x40000, s12
	s_add_u32 s2, s24, s12
	s_addc_u32 s3, s25, 0
	s_lshr_b32 s12, s12, 6
	s_add_u32 s4, s26, s12
	s_addc_u32 s5, s27, 0
	global_load_ushort v27, v2, s[2:3]
	global_load_dword v51, v3, s[4:5]
	s_waitcnt vmcnt(60)
	s_mov_b32 s12, 0x670000
	s_cmp_eq_u32 s6, 1
	s_cselect_b32 s12, 0x180000, s12
	s_add_u32 s2, s24, s12
	s_addc_u32 s3, s25, 0
	v_cvt_pk_bf16_f32 v6, v5, v5
	v_lshlrev_b32_e32 v31, 16, v31
	global_store_short v2, v6, s[2:3]
	v_fmac_f32_e32 v31, v55, v5
	v_mov_b32_e32 v5, v31
	s_mov_b32 s12, 0x7c0000
	s_cmp_eq_u32 s6, 1
	s_cselect_b32 s12, 0x30000, s12
	s_add_u32 s2, s24, s12
	s_addc_u32 s3, s25, 0
	s_lshr_b32 s12, s12, 6
	s_add_u32 s4, s26, s12
	s_addc_u32 s5, s27, 0
	global_load_ushort v28, v2, s[2:3]
	global_load_dword v52, v3, s[4:5]
	s_waitcnt vmcnt(60)
	s_mov_b32 s12, 0x680000
	s_cmp_eq_u32 s6, 1
	s_cselect_b32 s12, 0x170000, s12
	s_add_u32 s2, s24, s12
	s_addc_u32 s3, s25, 0
	v_cvt_pk_bf16_f32 v6, v5, v5
	v_lshlrev_b32_e32 v32, 16, v32
	global_store_short v2, v6, s[2:3]
	v_fmac_f32_e32 v32, v56, v5
	v_mov_b32_e32 v5, v32
	s_mov_b32 s12, 0x7d0000
	s_cmp_eq_u32 s6, 1
	s_cselect_b32 s12, 0x20000, s12
	s_add_u32 s2, s24, s12
	s_addc_u32 s3, s25, 0
	s_lshr_b32 s12, s12, 6
	s_add_u32 s4, s26, s12
	s_addc_u32 s5, s27, 0
	global_load_ushort v29, v2, s[2:3]
	global_load_dword v53, v3, s[4:5]
	s_waitcnt vmcnt(60)
	s_mov_b32 s12, 0x690000
	s_cmp_eq_u32 s6, 1
	s_cselect_b32 s12, 0x160000, s12
	s_add_u32 s2, s24, s12
	s_addc_u32 s3, s25, 0
	v_cvt_pk_bf16_f32 v6, v5, v5
	v_lshlrev_b32_e32 v33, 16, v33
	global_store_short v2, v6, s[2:3]
	v_fmac_f32_e32 v33, v57, v5
	v_mov_b32_e32 v5, v33
	s_mov_b32 s12, 0x7e0000
	s_cmp_eq_u32 s6, 1
	s_cselect_b32 s12, 0x10000, s12
	s_add_u32 s2, s24, s12
	s_addc_u32 s3, s25, 0
	s_lshr_b32 s12, s12, 6
	s_add_u32 s4, s26, s12
	s_addc_u32 s5, s27, 0
	global_load_ushort v30, v2, s[2:3]
	global_load_dword v54, v3, s[4:5]
	s_waitcnt vmcnt(60)
; DI int otid() { int t = threadIdx.x; asm volatile("" : "+v"(t)); return t; }
; DI float bf2f(bf16 v) { return __uint_as_float(((unsigned)v) << 16); }
; DI bf16 f2bf(float f) { unsigned u = __float_as_uint(f); u += 0x7fffu + ((u >> 16) & 1u); return (bf16)(u >> 16); }
;   DI bf16* G() const { return (bf16*)(p.ws + WS_G); }
;   DI float* DEC() const { return (float*)(p.ws + WS_DEC); }
; DI void gla_g2(const Ctx& c) {
;   const int gt = blockIdx.x * NT + otid(), gs = gridDim.x * NT;
;   for (int i = gt; i < 16 * 8192; i += gs) {
;     const int e = i & 8191, kk = e & 63, q = i >> 13, h = q & 3, bd = q >> 2, dir = bd & 1;
;     float st = 0.f;
;     for (int c0 = 0; c0 < 132; c0 += 12) {
;       float dsv[12], dec[12]; bf16* pd[12];
; #pragma unroll
;       for (int j = 0; j < 12; ++j) {
;         const int ci = c0 + j;
;         const int cm = dir ? (131 - ci) : (ci < 4 ? 128 + ci : ci - 4);
;         const size_t sidx = (size_t)(bd * 132 + cm) * 4 + h;
;         pd[j] = c.G() + sidx * 8192 + e;
;         dsv[j] = bf2f(*pd[j]); dec[j] = c.DEC()[sidx * 64 + kk];
;       }
; #pragma unroll
;       for (int j = 0; j < 12; ++j) { *pd[j] = f2bf(st); st = dec[j] * st + dsv[j]; }
;     }
;   }
; }
	s_mov_b32 s12, 0x6a0000
	s_cmp_eq_u32 s6, 1
	s_cselect_b32 s12, 0x150000, s12
	s_add_u32 s2, s24, s12
	s_addc_u32 s3, s25, 0
	v_cvt_pk_bf16_f32 v6, v5, v5
	v_lshlrev_b32_e32 v34, 16, v34
	global_store_short v2, v6, s[2:3]
	v_fmac_f32_e32 v34, v58, v5
	v_mov_b32_e32 v5, v34
	s_mov_b32 s12, 0x7f0000
	s_cmp_eq_u32 s6, 1
	s_cselect_b32 s12, 0x0, s12
	s_add_u32 s2, s24, s12
	s_addc_u32 s3, s25, 0
	s_lshr_b32 s12, s12, 6
	s_add_u32 s4, s26, s12
	s_addc_u32 s5, s27, 0
	global_load_ushort v31, v2, s[2:3]
	global_load_dword v55, v3, s[4:5]
	s_waitcnt vmcnt(60)
	s_mov_b32 s12, 0x6b0000
	s_cmp_eq_u32 s6, 1
	s_cselect_b32 s12, 0x140000, s12
	s_add_u32 s2, s24, s12
	s_addc_u32 s3, s25, 0
	v_cvt_pk_bf16_f32 v6, v5, v5
	v_lshlrev_b32_e32 v35, 16, v35
	global_store_short v2, v6, s[2:3]
	v_fmac_f32_e32 v35, v59, v5
	v_mov_b32_e32 v5, v35
	s_waitcnt vmcnt(58)
	s_mov_b32 s12, 0x6c0000
	s_cmp_eq_u32 s6, 1
	s_cselect_b32 s12, 0x130000, s12
	s_add_u32 s2, s24, s12
	s_addc_u32 s3, s25, 0
	v_cvt_pk_bf16_f32 v6, v5, v5
	v_lshlrev_b32_e32 v36, 16, v36
	global_store_short v2, v6, s[2:3]
	v_fmac_f32_e32 v36, v60, v5
	v_mov_b32_e32 v5, v36
	s_waitcnt vmcnt(56)
	s_mov_b32 s12, 0x6d0000
	s_cmp_eq_u32 s6, 1
	s_cselect_b32 s12, 0x120000, s12
	s_add_u32 s2, s24, s12
	s_addc_u32 s3, s25, 0
	v_cvt_pk_bf16_f32 v6, v5, v5
	v_lshlrev_b32_e32 v37, 16, v37
	global_store_short v2, v6, s[2:3]
	v_fmac_f32_e32 v37, v61, v5
	v_mov_b32_e32 v5, v37
	s_waitcnt vmcnt(54)
	s_mov_b32 s12, 0x6e0000
	s_cmp_eq_u32 s6, 1
	s_cselect_b32 s12, 0x110000, s12
	s_add_u32 s2, s24, s12
	s_addc_u32 s3, s25, 0
	v_cvt_pk_bf16_f32 v6, v5, v5
	v_lshlrev_b32_e32 v38, 16, v38
	global_store_short v2, v6, s[2:3]
	v_fmac_f32_e32 v38, v62, v5
	v_mov_b32_e32 v5, v38
	s_waitcnt vmcnt(52)
	s_mov_b32 s12, 0x6f0000
	s_cmp_eq_u32 s6, 1
	s_cselect_b32 s12, 0x100000, s12
	s_add_u32 s2, s24, s12
	s_addc_u32 s3, s25, 0
	v_cvt_pk_bf16_f32 v6, v5, v5
	v_lshlrev_b32_e32 v39, 16, v39
	global_store_short v2, v6, s[2:3]
	v_fmac_f32_e32 v39, v63, v5
	v_mov_b32_e32 v5, v39
	s_waitcnt vmcnt(50)
	s_mov_b32 s12, 0x700000
	s_cmp_eq_u32 s6, 1
	s_cselect_b32 s12, 0xf0000, s12
	s_add_u32 s2, s24, s12
	s_addc_u32 s3, s25, 0
	v_cvt_pk_bf16_f32 v6, v5, v5
	v_lshlrev_b32_e32 v40, 16, v40
	global_store_short v2, v6, s[2:3]
	v_fmac_f32_e32 v40, v64, v5
	v_mov_b32_e32 v5, v40
	s_waitcnt vmcnt(48)
	s_mov_b32 s12, 0x710000
	s_cmp_eq_u32 s6, 1
	s_cselect_b32 s12, 0xe0000, s12
	s_add_u32 s2, s24, s12
	s_addc_u32 s3, s25, 0
	v_cvt_pk_bf16_f32 v6, v5, v5
	v_lshlrev_b32_e32 v41, 16, v41
	global_store_short v2, v6, s[2:3]
	v_fmac_f32_e32 v41, v65, v5
	v_mov_b32_e32 v5, v41
	s_waitcnt vmcnt(46)
	s_mov_b32 s12, 0x720000
	s_cmp_eq_u32 s6, 1
	s_cselect_b32 s12, 0xd0000, s12
	s_add_u32 s2, s24, s12
	s_addc_u32 s3, s25, 0
	v_cvt_pk_bf16_f32 v6, v5, v5
	v_lshlrev_b32_e32 v42, 16, v42
	global_store_short v2, v6, s[2:3]
	v_fmac_f32_e32 v42, v66, v5
	v_mov_b32_e32 v5, v42
	s_waitcnt vmcnt(44)
	s_mov_b32 s12, 0x730000
	s_cmp_eq_u32 s6, 1
	s_cselect_b32 s12, 0xc0000, s12
	s_add_u32 s2, s24, s12
	s_addc_u32 s3, s25, 0
	v_cvt_pk_bf16_f32 v6, v5, v5
	v_lshlrev_b32_e32 v43, 16, v43
	global_store_short v2, v6, s[2:3]
	v_fmac_f32_e32 v43, v67, v5
	v_mov_b32_e32 v5, v43
	s_waitcnt vmcnt(42)
	s_mov_b32 s12, 0x740000
	s_cmp_eq_u32 s6, 1
	s_cselect_b32 s12, 0xb0000, s12
	s_add_u32 s2, s24, s12
	s_addc_u32 s3, s25, 0
	v_cvt_pk_bf16_f32 v6, v5, v5
	v_lshlrev_b32_e32 v20, 16, v20
	global_store_short v2, v6, s[2:3]
	v_fmac_f32_e32 v20, v44, v5
	v_mov_b32_e32 v5, v20
	s_waitcnt vmcnt(40)
	s_mov_b32 s12, 0x750000
	s_cmp_eq_u32 s6, 1
	s_cselect_b32 s12, 0xa0000, s12
	s_add_u32 s2, s24, s12
	s_addc_u32 s3, s25, 0
	v_cvt_pk_bf16_f32 v6, v5, v5
	v_lshlrev_b32_e32 v21, 16, v21
	global_store_short v2, v6, s[2:3]
	v_fmac_f32_e32 v21, v45, v5
	v_mov_b32_e32 v5, v21
	s_waitcnt vmcnt(38)
	s_mov_b32 s12, 0x760000
	s_cmp_eq_u32 s6, 1
	s_cselect_b32 s12, 0x90000, s12
	s_add_u32 s2, s24, s12
	s_addc_u32 s3, s25, 0
	v_cvt_pk_bf16_f32 v6, v5, v5
	v_lshlrev_b32_e32 v22, 16, v22
	global_store_short v2, v6, s[2:3]
	v_fmac_f32_e32 v22, v46, v5
	v_mov_b32_e32 v5, v22
	s_waitcnt vmcnt(36)
	s_mov_b32 s12, 0x770000
	s_cmp_eq_u32 s6, 1
	s_cselect_b32 s12, 0x80000, s12
	s_add_u32 s2, s24, s12
	s_addc_u32 s3, s25, 0
	v_cvt_pk_bf16_f32 v6, v5, v5
	v_lshlrev_b32_e32 v23, 16, v23
	global_store_short v2, v6, s[2:3]
	v_fmac_f32_e32 v23, v47, v5
	v_mov_b32_e32 v5, v23
	s_waitcnt vmcnt(34)
	s_mov_b32 s12, 0x780000
	s_cmp_eq_u32 s6, 1
	s_cselect_b32 s12, 0x70000, s12
	s_add_u32 s2, s24, s12
	s_addc_u32 s3, s25, 0
	v_cvt_pk_bf16_f32 v6, v5, v5
	v_lshlrev_b32_e32 v24, 16, v24
	global_store_short v2, v6, s[2:3]
	v_fmac_f32_e32 v24, v48, v5
	v_mov_b32_e32 v5, v24
	s_waitcnt vmcnt(32)
	s_mov_b32 s12, 0x790000
	s_cmp_eq_u32 s6, 1
	s_cselect_b32 s12, 0x60000, s12
	s_add_u32 s2, s24, s12
	s_addc_u32 s3, s25, 0
	v_cvt_pk_bf16_f32 v6, v5, v5
	v_lshlrev_b32_e32 v25, 16, v25
	global_store_short v2, v6, s[2:3]
	v_fmac_f32_e32 v25, v49, v5
	v_mov_b32_e32 v5, v25
	s_waitcnt vmcnt(30)
	s_mov_b32 s12, 0x7a0000
	s_cmp_eq_u32 s6, 1
	s_cselect_b32 s12, 0x50000, s12
	s_add_u32 s2, s24, s12
	s_addc_u32 s3, s25, 0
	v_cvt_pk_bf16_f32 v6, v5, v5
	v_lshlrev_b32_e32 v26, 16, v26
	global_store_short v2, v6, s[2:3]
	v_fmac_f32_e32 v26, v50, v5
	v_mov_b32_e32 v5, v26
	s_waitcnt vmcnt(28)
	s_mov_b32 s12, 0x7b0000
	s_cmp_eq_u32 s6, 1
	s_cselect_b32 s12, 0x40000, s12
	s_add_u32 s2, s24, s12
	s_addc_u32 s3, s25, 0
	v_cvt_pk_bf16_f32 v6, v5, v5
	v_lshlrev_b32_e32 v27, 16, v27
	global_store_short v2, v6, s[2:3]
	v_fmac_f32_e32 v27, v51, v5
	v_mov_b32_e32 v5, v27
	s_waitcnt vmcnt(26)
	s_mov_b32 s12, 0x7c0000
	s_cmp_eq_u32 s6, 1
	s_cselect_b32 s12, 0x30000, s12
	s_add_u32 s2, s24, s12
	s_addc_u32 s3, s25, 0
	v_cvt_pk_bf16_f32 v6, v5, v5
	v_lshlrev_b32_e32 v28, 16, v28
	global_store_short v2, v6, s[2:3]
	v_fmac_f32_e32 v28, v52, v5
	v_mov_b32_e32 v5, v28
	s_waitcnt vmcnt(24)
	s_mov_b32 s12, 0x7d0000
	s_cmp_eq_u32 s6, 1
	s_cselect_b32 s12, 0x20000, s12
	s_add_u32 s2, s24, s12
	s_addc_u32 s3, s25, 0
	v_cvt_pk_bf16_f32 v6, v5, v5
	v_lshlrev_b32_e32 v29, 16, v29
	global_store_short v2, v6, s[2:3]
	v_fmac_f32_e32 v29, v53, v5
	v_mov_b32_e32 v5, v29
	s_waitcnt vmcnt(22)
	s_mov_b32 s12, 0x7e0000
	s_cmp_eq_u32 s6, 1
	s_cselect_b32 s12, 0x10000, s12
	s_add_u32 s2, s24, s12
	s_addc_u32 s3, s25, 0
	v_cvt_pk_bf16_f32 v6, v5, v5
	v_lshlrev_b32_e32 v30, 16, v30
	global_store_short v2, v6, s[2:3]
	v_fmac_f32_e32 v30, v54, v5
	v_mov_b32_e32 v5, v30
	s_waitcnt vmcnt(20)
	s_mov_b32 s12, 0x7f0000
	s_cmp_eq_u32 s6, 1
	s_cselect_b32 s12, 0x0, s12
	s_add_u32 s2, s24, s12
	s_addc_u32 s3, s25, 0
	v_cvt_pk_bf16_f32 v6, v5, v5
	v_lshlrev_b32_e32 v31, 16, v31
	global_store_short v2, v6, s[2:3]
	v_fmac_f32_e32 v31, v55, v5
	v_mov_b32_e32 v5, v31
	s_waitcnt vmcnt(0)
	s_branch .LBB0_799
